# gla_gate_rows rewritten by hand: 9 rows per wave, loads 2 rows ahead, DPP head reductions
# speedup vs baseline: 1.0117x; 1.0117x over previous
.LBB0_416:
	s_cmp_lt_i32 s24, 5
	s_cselect_b64 s[4:5], -1, 0
	s_cmp_gt_i32 s25, 4
	s_cselect_b64 s[6:7], -1, 0
	s_and_b64 s[4:5], s[4:5], s[6:7]
	s_andn2_b64 vcc, exec, s[4:5]
	v_lshrrev_b32_e32 v146, 6, v129
	s_cbranch_vccnz .LBB0_478
	s_mov_b64 exec, -1
	s_load_dword s3, s[0:1], 0x148
	s_add_u32 s8, s0, 0x148
	s_addc_u32 s9, s1, 0
	s_load_dwordx2 s[18:19], s[0:1], 0x70
	v_and_b32_e32 v1, 63, v129
	v_readfirstlane_b32 s4, v146
	v_lshlrev_b32_e32 v0, 4, v1
	v_lshlrev_b32_e32 v1, 3, v1
	v_mov_b32_e32 v2, 0x3b800000
	v_mov_b32_e32 v3, 0x358637bd
	s_lshl_b32 s5, s2, 3
	s_add_u32 s4, s4, s5
	s_waitcnt lgkmcnt(0)
	global_load_dwordx4 v[4:7], v0, s[18:19] offset:0
	global_load_dwordx4 v[8:11], v0, s[18:19] offset:1024
	global_load_dwordx4 v[12:15], v0, s[18:19] offset:2048
	global_load_dwordx4 v[16:19], v0, s[18:19] offset:3072
	s_lshl_b32 s16, s4, 11
	s_lshr_b32 s17, s4, 21
	s_add_u32 s6, s44, s16
	s_addc_u32 s7, s45, s17
	s_mov_b64 s[14:15], s[6:7]
	s_mul_i32 s16, s4, 0x1a00
	s_mul_hi_u32 s17, s4, 0x1a00
	s_add_u32 s12, s46, s16
	s_addc_u32 s13, s47, s17
	s_add_u32 s12, s12, 0x1000
	s_addc_u32 s13, s13, 0
	s_cmpk_lt_u32 s4, 0x200
	s_cselect_b32 s22, 1, 0
	global_load_dwordx2 v[20:21], v1, s[6:7] offset:0
	global_load_dwordx2 v[22:23], v1, s[6:7] offset:512
	global_load_dwordx2 v[24:25], v1, s[6:7] offset:1024
	global_load_dwordx2 v[26:27], v1, s[6:7] offset:1536
	global_load_dwordx2 v[28:29], v1, s[12:13] offset:0
	global_load_dwordx2 v[30:31], v1, s[12:13] offset:512
	global_load_dwordx2 v[32:33], v1, s[12:13] offset:1024
	global_load_dwordx2 v[34:35], v1, s[12:13] offset:1536
	s_add_u32 s6, s6, 0x400000
	s_addc_u32 s7, s7, 0
	s_add_u32 s12, s12, 0xd00000
	s_addc_u32 s13, s13, 0
	global_load_dwordx2 v[36:37], v1, s[6:7] offset:0
	global_load_dwordx2 v[38:39], v1, s[6:7] offset:512
	global_load_dwordx2 v[40:41], v1, s[6:7] offset:1024
	global_load_dwordx2 v[42:43], v1, s[6:7] offset:1536
	global_load_dwordx2 v[44:45], v1, s[12:13] offset:0
	global_load_dwordx2 v[46:47], v1, s[12:13] offset:512
	global_load_dwordx2 v[48:49], v1, s[12:13] offset:1024
	global_load_dwordx2 v[50:51], v1, s[12:13] offset:1536
	s_add_u32 s6, s6, 0x400000
	s_addc_u32 s7, s7, 0
	s_add_u32 s12, s12, 0xd00000
	s_addc_u32 s13, s13, 0
	global_load_dwordx2 v[52:53], v1, s[6:7] offset:0
	global_load_dwordx2 v[54:55], v1, s[6:7] offset:512
	global_load_dwordx2 v[56:57], v1, s[6:7] offset:1024
	global_load_dwordx2 v[58:59], v1, s[6:7] offset:1536
	global_load_dwordx2 v[60:61], v1, s[12:13] offset:0
	global_load_dwordx2 v[62:63], v1, s[12:13] offset:512
	global_load_dwordx2 v[64:65], v1, s[12:13] offset:1024
	global_load_dwordx2 v[66:67], v1, s[12:13] offset:1536
	s_add_u32 s6, s6, 0x400000
	s_addc_u32 s7, s7, 0
	s_add_u32 s12, s12, 0xd00000
	s_addc_u32 s13, s13, 0
	s_waitcnt vmcnt(16)
	v_lshlrev_b32_e32 v68, 16, v20
	v_and_b32_e32 v69, 0xffff0000, v20
	v_lshlrev_b32_e32 v70, 16, v21
	v_and_b32_e32 v71, 0xffff0000, v21
	v_lshlrev_b32_e32 v72, 16, v22
	v_and_b32_e32 v73, 0xffff0000, v22
	v_lshlrev_b32_e32 v74, 16, v23
	v_and_b32_e32 v75, 0xffff0000, v23
	v_lshlrev_b32_e32 v76, 16, v24
	v_and_b32_e32 v77, 0xffff0000, v24
	v_lshlrev_b32_e32 v78, 16, v25
	v_and_b32_e32 v79, 0xffff0000, v25
	v_lshlrev_b32_e32 v80, 16, v26
	v_and_b32_e32 v81, 0xffff0000, v26
	v_lshlrev_b32_e32 v82, 16, v27
	v_and_b32_e32 v83, 0xffff0000, v27
	v_mul_f32_e32 v84, v68, v68
	v_mul_f32_e32 v85, v72, v72
	v_mul_f32_e32 v86, v76, v76
	v_mul_f32_e32 v87, v80, v80
	v_fmac_f32_e32 v84, v69, v69
	v_fmac_f32_e32 v85, v73, v73
	v_fmac_f32_e32 v86, v77, v77
	v_fmac_f32_e32 v87, v81, v81
	v_fmac_f32_e32 v84, v70, v70
	v_fmac_f32_e32 v85, v74, v74
	v_fmac_f32_e32 v86, v78, v78
	v_fmac_f32_e32 v87, v82, v82
	v_fmac_f32_e32 v84, v71, v71
	v_fmac_f32_e32 v85, v75, v75
	v_fmac_f32_e32 v86, v79, v79
	v_fmac_f32_e32 v87, v83, v83
	v_add_f32_dpp v84, v84, v84 quad_perm:[1,0,3,2] row_mask:0xf bank_mask:0xf
	v_add_f32_dpp v85, v85, v85 quad_perm:[1,0,3,2] row_mask:0xf bank_mask:0xf
	v_add_f32_dpp v86, v86, v86 quad_perm:[1,0,3,2] row_mask:0xf bank_mask:0xf
	v_add_f32_dpp v87, v87, v87 quad_perm:[1,0,3,2] row_mask:0xf bank_mask:0xf
	v_add_f32_dpp v84, v84, v84 quad_perm:[2,3,0,1] row_mask:0xf bank_mask:0xf
	v_add_f32_dpp v85, v85, v85 quad_perm:[2,3,0,1] row_mask:0xf bank_mask:0xf
	v_add_f32_dpp v86, v86, v86 quad_perm:[2,3,0,1] row_mask:0xf bank_mask:0xf
	v_add_f32_dpp v87, v87, v87 quad_perm:[2,3,0,1] row_mask:0xf bank_mask:0xf
	v_add_f32_dpp v84, v84, v84 row_half_mirror row_mask:0xf bank_mask:0xf
	v_add_f32_dpp v85, v85, v85 row_half_mirror row_mask:0xf bank_mask:0xf
	v_add_f32_dpp v86, v86, v86 row_half_mirror row_mask:0xf bank_mask:0xf
	v_add_f32_dpp v87, v87, v87 row_half_mirror row_mask:0xf bank_mask:0xf
	v_add_f32_dpp v84, v84, v84 row_mirror row_mask:0xf bank_mask:0xf
	v_add_f32_dpp v85, v85, v85 row_mirror row_mask:0xf bank_mask:0xf
	v_add_f32_dpp v86, v86, v86 row_mirror row_mask:0xf bank_mask:0xf
	v_add_f32_dpp v87, v87, v87 row_mirror row_mask:0xf bank_mask:0xf
	v_add_f32_dpp v84, v84, v84 row_bcast:15 row_mask:0xa bank_mask:0xf
	v_add_f32_dpp v85, v85, v85 row_bcast:15 row_mask:0xa bank_mask:0xf
	v_add_f32_dpp v86, v86, v86 row_bcast:15 row_mask:0xa bank_mask:0xf
	v_add_f32_dpp v87, v87, v87 row_bcast:15 row_mask:0xa bank_mask:0xf
	v_add_f32_dpp v84, v84, v84 row_bcast:31 row_mask:0xc bank_mask:0xf
	v_add_f32_dpp v85, v85, v85 row_bcast:31 row_mask:0xc bank_mask:0xf
	v_add_f32_dpp v86, v86, v86 row_bcast:31 row_mask:0xc bank_mask:0xf
	v_add_f32_dpp v87, v87, v87 row_bcast:31 row_mask:0xc bank_mask:0xf
	s_nop 0
	v_readlane_b32 s28, v84, 63
	v_readlane_b32 s29, v85, 63
	v_readlane_b32 s30, v86, 63
	v_readlane_b32 s31, v87, 63
	s_nop 1
	v_fma_f32 v88, s28, v2, v3
	v_fma_f32 v89, s29, v2, v3
	v_fma_f32 v90, s30, v2, v3
	v_fma_f32 v91, s31, v2, v3
	v_rsq_f32_e32 v88, v88
	v_rsq_f32_e32 v89, v89
	v_rsq_f32_e32 v90, v90
	v_rsq_f32_e32 v91, v91
	s_nop 0
	v_lshlrev_b32_e32 v100, 16, v28
	v_mul_f32_e32 v101, 0xbfb8aa3b, v100
	v_exp_f32_e32 v101, v101
	v_mul_f32_e32 v68, v68, v88
	v_add_f32_e32 v101, 1.0, v101
	v_mul_f32_e32 v68, v68, v4
	v_and_b32_e32 v108, 0xffff0000, v28
	v_mul_f32_e32 v109, 0xbfb8aa3b, v108
	v_exp_f32_e32 v109, v109
	v_mul_f32_e32 v69, v69, v88
	v_add_f32_e32 v109, 1.0, v109
	v_mul_f32_e32 v69, v69, v5
	v_div_scale_f32 v103, s[16:17], v101, v101, v100
	v_rcp_f32_e32 v104, v103
	s_nop 0
	v_fma_f32 v105, -v103, v104, 1.0
	v_fmac_f32_e32 v104, v105, v104
	v_div_scale_f32 v111, s[16:17], v109, v109, v108
	v_rcp_f32_e32 v112, v111
	s_nop 0
	v_fma_f32 v113, -v111, v112, 1.0
	v_fmac_f32_e32 v112, v113, v112
	v_div_scale_f32 v106, vcc, v100, v101, v100
	v_mul_f32_e32 v102, v106, v104
	v_fma_f32 v105, -v103, v102, v106
	v_fmac_f32_e32 v102, v105, v104
	v_fma_f32 v105, -v103, v102, v106
	v_div_fmas_f32 v102, v105, v104, v102
	v_div_fixup_f32 v102, v102, v101, v100
	v_mul_f32_e32 v68, v68, v102
	v_div_scale_f32 v114, vcc, v108, v109, v108
	v_mul_f32_e32 v110, v114, v112
	v_fma_f32 v113, -v111, v110, v114
	v_fmac_f32_e32 v110, v113, v112
	v_fma_f32 v113, -v111, v110, v114
	v_div_fmas_f32 v110, v113, v112, v110
	v_div_fixup_f32 v110, v110, v109, v108
	v_mul_f32_e32 v69, v69, v110
	v_lshlrev_b32_e32 v100, 16, v29
	v_mul_f32_e32 v101, 0xbfb8aa3b, v100
	v_exp_f32_e32 v101, v101
	v_mul_f32_e32 v70, v70, v88
	v_add_f32_e32 v101, 1.0, v101
	v_mul_f32_e32 v70, v70, v6
	v_and_b32_e32 v108, 0xffff0000, v29
	v_mul_f32_e32 v109, 0xbfb8aa3b, v108
	v_exp_f32_e32 v109, v109
	v_mul_f32_e32 v71, v71, v88
	v_add_f32_e32 v109, 1.0, v109
	v_mul_f32_e32 v71, v71, v7
	v_div_scale_f32 v103, s[16:17], v101, v101, v100
	v_rcp_f32_e32 v104, v103
	s_nop 0
	v_fma_f32 v105, -v103, v104, 1.0
	v_fmac_f32_e32 v104, v105, v104
	v_div_scale_f32 v111, s[16:17], v109, v109, v108
	v_rcp_f32_e32 v112, v111
	s_nop 0
	v_fma_f32 v113, -v111, v112, 1.0
	v_fmac_f32_e32 v112, v113, v112
	v_div_scale_f32 v106, vcc, v100, v101, v100
	v_mul_f32_e32 v102, v106, v104
	v_fma_f32 v105, -v103, v102, v106
	v_fmac_f32_e32 v102, v105, v104
	v_fma_f32 v105, -v103, v102, v106
	v_div_fmas_f32 v102, v105, v104, v102
	v_div_fixup_f32 v102, v102, v101, v100
	v_mul_f32_e32 v70, v70, v102
	v_div_scale_f32 v114, vcc, v108, v109, v108
	v_mul_f32_e32 v110, v114, v112
	v_fma_f32 v113, -v111, v110, v114
	v_fmac_f32_e32 v110, v113, v112
	v_fma_f32 v113, -v111, v110, v114
	v_div_fmas_f32 v110, v113, v112, v110
	v_div_fixup_f32 v110, v110, v109, v108
	v_mul_f32_e32 v71, v71, v110
	v_cvt_pk_bf16_f32 v92, v68, v69
	v_cvt_pk_bf16_f32 v93, v70, v71
	global_store_dwordx2 v1, v[92:93], s[14:15] offset:0
	v_lshlrev_b32_e32 v100, 16, v30
	v_mul_f32_e32 v101, 0xbfb8aa3b, v100
	v_exp_f32_e32 v101, v101
	v_mul_f32_e32 v72, v72, v89
	v_add_f32_e32 v101, 1.0, v101
	v_mul_f32_e32 v72, v72, v8
	v_and_b32_e32 v108, 0xffff0000, v30
	v_mul_f32_e32 v109, 0xbfb8aa3b, v108
	v_exp_f32_e32 v109, v109
	v_mul_f32_e32 v73, v73, v89
	v_add_f32_e32 v109, 1.0, v109
	v_mul_f32_e32 v73, v73, v9
	v_div_scale_f32 v103, s[16:17], v101, v101, v100
	v_rcp_f32_e32 v104, v103
	s_nop 0
	v_fma_f32 v105, -v103, v104, 1.0
	v_fmac_f32_e32 v104, v105, v104
	v_div_scale_f32 v111, s[16:17], v109, v109, v108
	v_rcp_f32_e32 v112, v111
	s_nop 0
	v_fma_f32 v113, -v111, v112, 1.0
	v_fmac_f32_e32 v112, v113, v112
	v_div_scale_f32 v106, vcc, v100, v101, v100
	v_mul_f32_e32 v102, v106, v104
	v_fma_f32 v105, -v103, v102, v106
	v_fmac_f32_e32 v102, v105, v104
	v_fma_f32 v105, -v103, v102, v106
	v_div_fmas_f32 v102, v105, v104, v102
	v_div_fixup_f32 v102, v102, v101, v100
	v_mul_f32_e32 v72, v72, v102
	v_div_scale_f32 v114, vcc, v108, v109, v108
	v_mul_f32_e32 v110, v114, v112
	v_fma_f32 v113, -v111, v110, v114
	v_fmac_f32_e32 v110, v113, v112
	v_fma_f32 v113, -v111, v110, v114
	v_div_fmas_f32 v110, v113, v112, v110
	v_div_fixup_f32 v110, v110, v109, v108
	v_mul_f32_e32 v73, v73, v110
	v_lshlrev_b32_e32 v100, 16, v31
	v_mul_f32_e32 v101, 0xbfb8aa3b, v100
	v_exp_f32_e32 v101, v101
	v_mul_f32_e32 v74, v74, v89
	v_add_f32_e32 v101, 1.0, v101
	v_mul_f32_e32 v74, v74, v10
	v_and_b32_e32 v108, 0xffff0000, v31
	v_mul_f32_e32 v109, 0xbfb8aa3b, v108
	v_exp_f32_e32 v109, v109
	v_mul_f32_e32 v75, v75, v89
	v_add_f32_e32 v109, 1.0, v109
	v_mul_f32_e32 v75, v75, v11
	v_div_scale_f32 v103, s[16:17], v101, v101, v100
	v_rcp_f32_e32 v104, v103
	s_nop 0
	v_fma_f32 v105, -v103, v104, 1.0
	v_fmac_f32_e32 v104, v105, v104
	v_div_scale_f32 v111, s[16:17], v109, v109, v108
	v_rcp_f32_e32 v112, v111
	s_nop 0
	v_fma_f32 v113, -v111, v112, 1.0
	v_fmac_f32_e32 v112, v113, v112
	v_div_scale_f32 v106, vcc, v100, v101, v100
	v_mul_f32_e32 v102, v106, v104
	v_fma_f32 v105, -v103, v102, v106
	v_fmac_f32_e32 v102, v105, v104
	v_fma_f32 v105, -v103, v102, v106
	v_div_fmas_f32 v102, v105, v104, v102
	v_div_fixup_f32 v102, v102, v101, v100
	v_mul_f32_e32 v74, v74, v102
	v_div_scale_f32 v114, vcc, v108, v109, v108
	v_mul_f32_e32 v110, v114, v112
	v_fma_f32 v113, -v111, v110, v114
	v_fmac_f32_e32 v110, v113, v112
	v_fma_f32 v113, -v111, v110, v114
	v_div_fmas_f32 v110, v113, v112, v110
	v_div_fixup_f32 v110, v110, v109, v108
	v_mul_f32_e32 v75, v75, v110
	v_cvt_pk_bf16_f32 v94, v72, v73
	v_cvt_pk_bf16_f32 v95, v74, v75
	global_store_dwordx2 v1, v[94:95], s[14:15] offset:512
	v_lshlrev_b32_e32 v100, 16, v32
	v_mul_f32_e32 v101, 0xbfb8aa3b, v100
	v_exp_f32_e32 v101, v101
	v_mul_f32_e32 v76, v76, v90
	v_add_f32_e32 v101, 1.0, v101
	v_mul_f32_e32 v76, v76, v12
	v_and_b32_e32 v108, 0xffff0000, v32
	v_mul_f32_e32 v109, 0xbfb8aa3b, v108
	v_exp_f32_e32 v109, v109
	v_mul_f32_e32 v77, v77, v90
	v_add_f32_e32 v109, 1.0, v109
	v_mul_f32_e32 v77, v77, v13
	v_div_scale_f32 v103, s[16:17], v101, v101, v100
	v_rcp_f32_e32 v104, v103
	s_nop 0
	v_fma_f32 v105, -v103, v104, 1.0
	v_fmac_f32_e32 v104, v105, v104
	v_div_scale_f32 v111, s[16:17], v109, v109, v108
	v_rcp_f32_e32 v112, v111
	s_nop 0
	v_fma_f32 v113, -v111, v112, 1.0
	v_fmac_f32_e32 v112, v113, v112
	v_div_scale_f32 v106, vcc, v100, v101, v100
	v_mul_f32_e32 v102, v106, v104
	v_fma_f32 v105, -v103, v102, v106
	v_fmac_f32_e32 v102, v105, v104
	v_fma_f32 v105, -v103, v102, v106
	v_div_fmas_f32 v102, v105, v104, v102
	v_div_fixup_f32 v102, v102, v101, v100
	v_mul_f32_e32 v76, v76, v102
	v_div_scale_f32 v114, vcc, v108, v109, v108
	v_mul_f32_e32 v110, v114, v112
	v_fma_f32 v113, -v111, v110, v114
	v_fmac_f32_e32 v110, v113, v112
	v_fma_f32 v113, -v111, v110, v114
	v_div_fmas_f32 v110, v113, v112, v110
	v_div_fixup_f32 v110, v110, v109, v108
	v_mul_f32_e32 v77, v77, v110
	v_lshlrev_b32_e32 v100, 16, v33
	v_mul_f32_e32 v101, 0xbfb8aa3b, v100
	v_exp_f32_e32 v101, v101
	v_mul_f32_e32 v78, v78, v90
	v_add_f32_e32 v101, 1.0, v101
	v_mul_f32_e32 v78, v78, v14
	v_and_b32_e32 v108, 0xffff0000, v33
	v_mul_f32_e32 v109, 0xbfb8aa3b, v108
	v_exp_f32_e32 v109, v109
	v_mul_f32_e32 v79, v79, v90
	v_add_f32_e32 v109, 1.0, v109
	v_mul_f32_e32 v79, v79, v15
	v_div_scale_f32 v103, s[16:17], v101, v101, v100
	v_rcp_f32_e32 v104, v103
	s_nop 0
	v_fma_f32 v105, -v103, v104, 1.0
	v_fmac_f32_e32 v104, v105, v104
	v_div_scale_f32 v111, s[16:17], v109, v109, v108
	v_rcp_f32_e32 v112, v111
	s_nop 0
	v_fma_f32 v113, -v111, v112, 1.0
	v_fmac_f32_e32 v112, v113, v112
	v_div_scale_f32 v106, vcc, v100, v101, v100
	v_mul_f32_e32 v102, v106, v104
	v_fma_f32 v105, -v103, v102, v106
	v_fmac_f32_e32 v102, v105, v104
	v_fma_f32 v105, -v103, v102, v106
	v_div_fmas_f32 v102, v105, v104, v102
	v_div_fixup_f32 v102, v102, v101, v100
	v_mul_f32_e32 v78, v78, v102
	v_div_scale_f32 v114, vcc, v108, v109, v108
	v_mul_f32_e32 v110, v114, v112
	v_fma_f32 v113, -v111, v110, v114
	v_fmac_f32_e32 v110, v113, v112
	v_fma_f32 v113, -v111, v110, v114
	v_div_fmas_f32 v110, v113, v112, v110
	v_div_fixup_f32 v110, v110, v109, v108
	v_mul_f32_e32 v79, v79, v110
	v_cvt_pk_bf16_f32 v96, v76, v77
	v_cvt_pk_bf16_f32 v97, v78, v79
	global_store_dwordx2 v1, v[96:97], s[14:15] offset:1024
	v_lshlrev_b32_e32 v100, 16, v34
	v_mul_f32_e32 v101, 0xbfb8aa3b, v100
	v_exp_f32_e32 v101, v101
	v_mul_f32_e32 v80, v80, v91
	v_add_f32_e32 v101, 1.0, v101
	v_mul_f32_e32 v80, v80, v16
	v_and_b32_e32 v108, 0xffff0000, v34
	v_mul_f32_e32 v109, 0xbfb8aa3b, v108
	v_exp_f32_e32 v109, v109
	v_mul_f32_e32 v81, v81, v91
	v_add_f32_e32 v109, 1.0, v109
	v_mul_f32_e32 v81, v81, v17
	v_div_scale_f32 v103, s[16:17], v101, v101, v100
	v_rcp_f32_e32 v104, v103
	s_nop 0
	v_fma_f32 v105, -v103, v104, 1.0
	v_fmac_f32_e32 v104, v105, v104
	v_div_scale_f32 v111, s[16:17], v109, v109, v108
	v_rcp_f32_e32 v112, v111
	s_nop 0
	v_fma_f32 v113, -v111, v112, 1.0
	v_fmac_f32_e32 v112, v113, v112
	v_div_scale_f32 v106, vcc, v100, v101, v100
	v_mul_f32_e32 v102, v106, v104
	v_fma_f32 v105, -v103, v102, v106
	v_fmac_f32_e32 v102, v105, v104
	v_fma_f32 v105, -v103, v102, v106
	v_div_fmas_f32 v102, v105, v104, v102
	v_div_fixup_f32 v102, v102, v101, v100
	v_mul_f32_e32 v80, v80, v102
	v_div_scale_f32 v114, vcc, v108, v109, v108
	v_mul_f32_e32 v110, v114, v112
	v_fma_f32 v113, -v111, v110, v114
	v_fmac_f32_e32 v110, v113, v112
	v_fma_f32 v113, -v111, v110, v114
	v_div_fmas_f32 v110, v113, v112, v110
	v_div_fixup_f32 v110, v110, v109, v108
	v_mul_f32_e32 v81, v81, v110
	v_lshlrev_b32_e32 v100, 16, v35
	v_mul_f32_e32 v101, 0xbfb8aa3b, v100
	v_exp_f32_e32 v101, v101
	v_mul_f32_e32 v82, v82, v91
	v_add_f32_e32 v101, 1.0, v101
	v_mul_f32_e32 v82, v82, v18
	v_and_b32_e32 v108, 0xffff0000, v35
	v_mul_f32_e32 v109, 0xbfb8aa3b, v108
	v_exp_f32_e32 v109, v109
	v_mul_f32_e32 v83, v83, v91
	v_add_f32_e32 v109, 1.0, v109
	v_mul_f32_e32 v83, v83, v19
	v_div_scale_f32 v103, s[16:17], v101, v101, v100
	v_rcp_f32_e32 v104, v103
	s_nop 0
	v_fma_f32 v105, -v103, v104, 1.0
	v_fmac_f32_e32 v104, v105, v104
	v_div_scale_f32 v111, s[16:17], v109, v109, v108
	v_rcp_f32_e32 v112, v111
	s_nop 0
	v_fma_f32 v113, -v111, v112, 1.0
	v_fmac_f32_e32 v112, v113, v112
	v_div_scale_f32 v106, vcc, v100, v101, v100
	v_mul_f32_e32 v102, v106, v104
	v_fma_f32 v105, -v103, v102, v106
	v_fmac_f32_e32 v102, v105, v104
	v_fma_f32 v105, -v103, v102, v106
	v_div_fmas_f32 v102, v105, v104, v102
	v_div_fixup_f32 v102, v102, v101, v100
	v_mul_f32_e32 v82, v82, v102
	v_div_scale_f32 v114, vcc, v108, v109, v108
	v_mul_f32_e32 v110, v114, v112
	v_fma_f32 v113, -v111, v110, v114
	v_fmac_f32_e32 v110, v113, v112
	v_fma_f32 v113, -v111, v110, v114
	v_div_fmas_f32 v110, v113, v112, v110
	v_div_fixup_f32 v110, v110, v109, v108
	v_mul_f32_e32 v83, v83, v110
	v_cvt_pk_bf16_f32 v98, v80, v81
	v_cvt_pk_bf16_f32 v99, v82, v83
	global_store_dwordx2 v1, v[98:99], s[14:15] offset:1536
	s_add_u32 s14, s14, 0x400000
	s_addc_u32 s15, s15, 0
	global_load_dwordx2 v[20:21], v1, s[6:7] offset:0
	global_load_dwordx2 v[22:23], v1, s[6:7] offset:512
	global_load_dwordx2 v[24:25], v1, s[6:7] offset:1024
	global_load_dwordx2 v[26:27], v1, s[6:7] offset:1536
	global_load_dwordx2 v[28:29], v1, s[12:13] offset:0
	global_load_dwordx2 v[30:31], v1, s[12:13] offset:512
	global_load_dwordx2 v[32:33], v1, s[12:13] offset:1024
	global_load_dwordx2 v[34:35], v1, s[12:13] offset:1536
	s_add_u32 s6, s6, 0x400000
	s_addc_u32 s7, s7, 0
	s_add_u32 s12, s12, 0xd00000
	s_addc_u32 s13, s13, 0
	s_waitcnt vmcnt(20)
	v_lshlrev_b32_e32 v68, 16, v36
	v_and_b32_e32 v69, 0xffff0000, v36
	v_lshlrev_b32_e32 v70, 16, v37
	v_and_b32_e32 v71, 0xffff0000, v37
	v_lshlrev_b32_e32 v72, 16, v38
	v_and_b32_e32 v73, 0xffff0000, v38
	v_lshlrev_b32_e32 v74, 16, v39
	v_and_b32_e32 v75, 0xffff0000, v39
	v_lshlrev_b32_e32 v76, 16, v40
	v_and_b32_e32 v77, 0xffff0000, v40
	v_lshlrev_b32_e32 v78, 16, v41
	v_and_b32_e32 v79, 0xffff0000, v41
	v_lshlrev_b32_e32 v80, 16, v42
	v_and_b32_e32 v81, 0xffff0000, v42
	v_lshlrev_b32_e32 v82, 16, v43
	v_and_b32_e32 v83, 0xffff0000, v43
	v_mul_f32_e32 v84, v68, v68
	v_mul_f32_e32 v85, v72, v72
	v_mul_f32_e32 v86, v76, v76
	v_mul_f32_e32 v87, v80, v80
	v_fmac_f32_e32 v84, v69, v69
	v_fmac_f32_e32 v85, v73, v73
	v_fmac_f32_e32 v86, v77, v77
	v_fmac_f32_e32 v87, v81, v81
	v_fmac_f32_e32 v84, v70, v70
	v_fmac_f32_e32 v85, v74, v74
	v_fmac_f32_e32 v86, v78, v78
	v_fmac_f32_e32 v87, v82, v82
	v_fmac_f32_e32 v84, v71, v71
	v_fmac_f32_e32 v85, v75, v75
	v_fmac_f32_e32 v86, v79, v79
	v_fmac_f32_e32 v87, v83, v83
	v_add_f32_dpp v84, v84, v84 quad_perm:[1,0,3,2] row_mask:0xf bank_mask:0xf
	v_add_f32_dpp v85, v85, v85 quad_perm:[1,0,3,2] row_mask:0xf bank_mask:0xf
	v_add_f32_dpp v86, v86, v86 quad_perm:[1,0,3,2] row_mask:0xf bank_mask:0xf
	v_add_f32_dpp v87, v87, v87 quad_perm:[1,0,3,2] row_mask:0xf bank_mask:0xf
	v_add_f32_dpp v84, v84, v84 quad_perm:[2,3,0,1] row_mask:0xf bank_mask:0xf
	v_add_f32_dpp v85, v85, v85 quad_perm:[2,3,0,1] row_mask:0xf bank_mask:0xf
	v_add_f32_dpp v86, v86, v86 quad_perm:[2,3,0,1] row_mask:0xf bank_mask:0xf
	v_add_f32_dpp v87, v87, v87 quad_perm:[2,3,0,1] row_mask:0xf bank_mask:0xf
	v_add_f32_dpp v84, v84, v84 row_half_mirror row_mask:0xf bank_mask:0xf
	v_add_f32_dpp v85, v85, v85 row_half_mirror row_mask:0xf bank_mask:0xf
	v_add_f32_dpp v86, v86, v86 row_half_mirror row_mask:0xf bank_mask:0xf
	v_add_f32_dpp v87, v87, v87 row_half_mirror row_mask:0xf bank_mask:0xf
	v_add_f32_dpp v84, v84, v84 row_mirror row_mask:0xf bank_mask:0xf
	v_add_f32_dpp v85, v85, v85 row_mirror row_mask:0xf bank_mask:0xf
	v_add_f32_dpp v86, v86, v86 row_mirror row_mask:0xf bank_mask:0xf
	v_add_f32_dpp v87, v87, v87 row_mirror row_mask:0xf bank_mask:0xf
	v_add_f32_dpp v84, v84, v84 row_bcast:15 row_mask:0xa bank_mask:0xf
	v_add_f32_dpp v85, v85, v85 row_bcast:15 row_mask:0xa bank_mask:0xf
	v_add_f32_dpp v86, v86, v86 row_bcast:15 row_mask:0xa bank_mask:0xf
	v_add_f32_dpp v87, v87, v87 row_bcast:15 row_mask:0xa bank_mask:0xf
	v_add_f32_dpp v84, v84, v84 row_bcast:31 row_mask:0xc bank_mask:0xf
	v_add_f32_dpp v85, v85, v85 row_bcast:31 row_mask:0xc bank_mask:0xf
	v_add_f32_dpp v86, v86, v86 row_bcast:31 row_mask:0xc bank_mask:0xf
	v_add_f32_dpp v87, v87, v87 row_bcast:31 row_mask:0xc bank_mask:0xf
	s_nop 0
	v_readlane_b32 s28, v84, 63
	v_readlane_b32 s29, v85, 63
	v_readlane_b32 s30, v86, 63
	v_readlane_b32 s31, v87, 63
	s_nop 1
	v_fma_f32 v88, s28, v2, v3
	v_fma_f32 v89, s29, v2, v3
	v_fma_f32 v90, s30, v2, v3
	v_fma_f32 v91, s31, v2, v3
	v_rsq_f32_e32 v88, v88
	v_rsq_f32_e32 v89, v89
	v_rsq_f32_e32 v90, v90
	v_rsq_f32_e32 v91, v91
	s_nop 0
	v_lshlrev_b32_e32 v100, 16, v44
	v_mul_f32_e32 v101, 0xbfb8aa3b, v100
	v_exp_f32_e32 v101, v101
	v_mul_f32_e32 v68, v68, v88
	v_add_f32_e32 v101, 1.0, v101
	v_mul_f32_e32 v68, v68, v4
	v_and_b32_e32 v108, 0xffff0000, v44
	v_mul_f32_e32 v109, 0xbfb8aa3b, v108
	v_exp_f32_e32 v109, v109
	v_mul_f32_e32 v69, v69, v88
	v_add_f32_e32 v109, 1.0, v109
	v_mul_f32_e32 v69, v69, v5
	v_div_scale_f32 v103, s[16:17], v101, v101, v100
	v_rcp_f32_e32 v104, v103
	s_nop 0
	v_fma_f32 v105, -v103, v104, 1.0
	v_fmac_f32_e32 v104, v105, v104
	v_div_scale_f32 v111, s[16:17], v109, v109, v108
	v_rcp_f32_e32 v112, v111
	s_nop 0
	v_fma_f32 v113, -v111, v112, 1.0
	v_fmac_f32_e32 v112, v113, v112
	v_div_scale_f32 v106, vcc, v100, v101, v100
	v_mul_f32_e32 v102, v106, v104
	v_fma_f32 v105, -v103, v102, v106
	v_fmac_f32_e32 v102, v105, v104
	v_fma_f32 v105, -v103, v102, v106
	v_div_fmas_f32 v102, v105, v104, v102
	v_div_fixup_f32 v102, v102, v101, v100
	v_mul_f32_e32 v68, v68, v102
	v_div_scale_f32 v114, vcc, v108, v109, v108
	v_mul_f32_e32 v110, v114, v112
	v_fma_f32 v113, -v111, v110, v114
	v_fmac_f32_e32 v110, v113, v112
	v_fma_f32 v113, -v111, v110, v114
	v_div_fmas_f32 v110, v113, v112, v110
	v_div_fixup_f32 v110, v110, v109, v108
	v_mul_f32_e32 v69, v69, v110
	v_lshlrev_b32_e32 v100, 16, v45
	v_mul_f32_e32 v101, 0xbfb8aa3b, v100
	v_exp_f32_e32 v101, v101
	v_mul_f32_e32 v70, v70, v88
	v_add_f32_e32 v101, 1.0, v101
	v_mul_f32_e32 v70, v70, v6
	v_and_b32_e32 v108, 0xffff0000, v45
	v_mul_f32_e32 v109, 0xbfb8aa3b, v108
	v_exp_f32_e32 v109, v109
	v_mul_f32_e32 v71, v71, v88
	v_add_f32_e32 v109, 1.0, v109
	v_mul_f32_e32 v71, v71, v7
	v_div_scale_f32 v103, s[16:17], v101, v101, v100
	v_rcp_f32_e32 v104, v103
	s_nop 0
	v_fma_f32 v105, -v103, v104, 1.0
	v_fmac_f32_e32 v104, v105, v104
	v_div_scale_f32 v111, s[16:17], v109, v109, v108
	v_rcp_f32_e32 v112, v111
	s_nop 0
	v_fma_f32 v113, -v111, v112, 1.0
	v_fmac_f32_e32 v112, v113, v112
	v_div_scale_f32 v106, vcc, v100, v101, v100
	v_mul_f32_e32 v102, v106, v104
	v_fma_f32 v105, -v103, v102, v106
	v_fmac_f32_e32 v102, v105, v104
	v_fma_f32 v105, -v103, v102, v106
	v_div_fmas_f32 v102, v105, v104, v102
	v_div_fixup_f32 v102, v102, v101, v100
	v_mul_f32_e32 v70, v70, v102
	v_div_scale_f32 v114, vcc, v108, v109, v108
	v_mul_f32_e32 v110, v114, v112
	v_fma_f32 v113, -v111, v110, v114
	v_fmac_f32_e32 v110, v113, v112
	v_fma_f32 v113, -v111, v110, v114
	v_div_fmas_f32 v110, v113, v112, v110
	v_div_fixup_f32 v110, v110, v109, v108
	v_mul_f32_e32 v71, v71, v110
	v_cvt_pk_bf16_f32 v92, v68, v69
	v_cvt_pk_bf16_f32 v93, v70, v71
	global_store_dwordx2 v1, v[92:93], s[14:15] offset:0
	v_lshlrev_b32_e32 v100, 16, v46
	v_mul_f32_e32 v101, 0xbfb8aa3b, v100
	v_exp_f32_e32 v101, v101
	v_mul_f32_e32 v72, v72, v89
	v_add_f32_e32 v101, 1.0, v101
	v_mul_f32_e32 v72, v72, v8
	v_and_b32_e32 v108, 0xffff0000, v46
	v_mul_f32_e32 v109, 0xbfb8aa3b, v108
	v_exp_f32_e32 v109, v109
	v_mul_f32_e32 v73, v73, v89
	v_add_f32_e32 v109, 1.0, v109
	v_mul_f32_e32 v73, v73, v9
	v_div_scale_f32 v103, s[16:17], v101, v101, v100
	v_rcp_f32_e32 v104, v103
	s_nop 0
	v_fma_f32 v105, -v103, v104, 1.0
	v_fmac_f32_e32 v104, v105, v104
	v_div_scale_f32 v111, s[16:17], v109, v109, v108
	v_rcp_f32_e32 v112, v111
	s_nop 0
	v_fma_f32 v113, -v111, v112, 1.0
	v_fmac_f32_e32 v112, v113, v112
	v_div_scale_f32 v106, vcc, v100, v101, v100
	v_mul_f32_e32 v102, v106, v104
	v_fma_f32 v105, -v103, v102, v106
	v_fmac_f32_e32 v102, v105, v104
	v_fma_f32 v105, -v103, v102, v106
	v_div_fmas_f32 v102, v105, v104, v102
	v_div_fixup_f32 v102, v102, v101, v100
	v_mul_f32_e32 v72, v72, v102
	v_div_scale_f32 v114, vcc, v108, v109, v108
	v_mul_f32_e32 v110, v114, v112
	v_fma_f32 v113, -v111, v110, v114
	v_fmac_f32_e32 v110, v113, v112
	v_fma_f32 v113, -v111, v110, v114
	v_div_fmas_f32 v110, v113, v112, v110
	v_div_fixup_f32 v110, v110, v109, v108
	v_mul_f32_e32 v73, v73, v110
	v_lshlrev_b32_e32 v100, 16, v47
	v_mul_f32_e32 v101, 0xbfb8aa3b, v100
	v_exp_f32_e32 v101, v101
	v_mul_f32_e32 v74, v74, v89
	v_add_f32_e32 v101, 1.0, v101
	v_mul_f32_e32 v74, v74, v10
	v_and_b32_e32 v108, 0xffff0000, v47
	v_mul_f32_e32 v109, 0xbfb8aa3b, v108
	v_exp_f32_e32 v109, v109
	v_mul_f32_e32 v75, v75, v89
	v_add_f32_e32 v109, 1.0, v109
	v_mul_f32_e32 v75, v75, v11
	v_div_scale_f32 v103, s[16:17], v101, v101, v100
	v_rcp_f32_e32 v104, v103
	s_nop 0
	v_fma_f32 v105, -v103, v104, 1.0
	v_fmac_f32_e32 v104, v105, v104
	v_div_scale_f32 v111, s[16:17], v109, v109, v108
	v_rcp_f32_e32 v112, v111
	s_nop 0
	v_fma_f32 v113, -v111, v112, 1.0
	v_fmac_f32_e32 v112, v113, v112
	v_div_scale_f32 v106, vcc, v100, v101, v100
	v_mul_f32_e32 v102, v106, v104
	v_fma_f32 v105, -v103, v102, v106
	v_fmac_f32_e32 v102, v105, v104
	v_fma_f32 v105, -v103, v102, v106
	v_div_fmas_f32 v102, v105, v104, v102
	v_div_fixup_f32 v102, v102, v101, v100
	v_mul_f32_e32 v74, v74, v102
	v_div_scale_f32 v114, vcc, v108, v109, v108
	v_mul_f32_e32 v110, v114, v112
	v_fma_f32 v113, -v111, v110, v114
	v_fmac_f32_e32 v110, v113, v112
	v_fma_f32 v113, -v111, v110, v114
	v_div_fmas_f32 v110, v113, v112, v110
	v_div_fixup_f32 v110, v110, v109, v108
	v_mul_f32_e32 v75, v75, v110
	v_cvt_pk_bf16_f32 v94, v72, v73
	v_cvt_pk_bf16_f32 v95, v74, v75
	global_store_dwordx2 v1, v[94:95], s[14:15] offset:512
	v_lshlrev_b32_e32 v100, 16, v48
	v_mul_f32_e32 v101, 0xbfb8aa3b, v100
	v_exp_f32_e32 v101, v101
	v_mul_f32_e32 v76, v76, v90
	v_add_f32_e32 v101, 1.0, v101
	v_mul_f32_e32 v76, v76, v12
	v_and_b32_e32 v108, 0xffff0000, v48
	v_mul_f32_e32 v109, 0xbfb8aa3b, v108
	v_exp_f32_e32 v109, v109
	v_mul_f32_e32 v77, v77, v90
	v_add_f32_e32 v109, 1.0, v109
	v_mul_f32_e32 v77, v77, v13
	v_div_scale_f32 v103, s[16:17], v101, v101, v100
	v_rcp_f32_e32 v104, v103
	s_nop 0
	v_fma_f32 v105, -v103, v104, 1.0
	v_fmac_f32_e32 v104, v105, v104
	v_div_scale_f32 v111, s[16:17], v109, v109, v108
	v_rcp_f32_e32 v112, v111
	s_nop 0
	v_fma_f32 v113, -v111, v112, 1.0
	v_fmac_f32_e32 v112, v113, v112
	v_div_scale_f32 v106, vcc, v100, v101, v100
	v_mul_f32_e32 v102, v106, v104
	v_fma_f32 v105, -v103, v102, v106
	v_fmac_f32_e32 v102, v105, v104
	v_fma_f32 v105, -v103, v102, v106
	v_div_fmas_f32 v102, v105, v104, v102
	v_div_fixup_f32 v102, v102, v101, v100
	v_mul_f32_e32 v76, v76, v102
	v_div_scale_f32 v114, vcc, v108, v109, v108
	v_mul_f32_e32 v110, v114, v112
	v_fma_f32 v113, -v111, v110, v114
	v_fmac_f32_e32 v110, v113, v112
	v_fma_f32 v113, -v111, v110, v114
	v_div_fmas_f32 v110, v113, v112, v110
	v_div_fixup_f32 v110, v110, v109, v108
	v_mul_f32_e32 v77, v77, v110
	v_lshlrev_b32_e32 v100, 16, v49
	v_mul_f32_e32 v101, 0xbfb8aa3b, v100
	v_exp_f32_e32 v101, v101
	v_mul_f32_e32 v78, v78, v90
	v_add_f32_e32 v101, 1.0, v101
	v_mul_f32_e32 v78, v78, v14
	v_and_b32_e32 v108, 0xffff0000, v49
	v_mul_f32_e32 v109, 0xbfb8aa3b, v108
	v_exp_f32_e32 v109, v109
	v_mul_f32_e32 v79, v79, v90
	v_add_f32_e32 v109, 1.0, v109
	v_mul_f32_e32 v79, v79, v15
	v_div_scale_f32 v103, s[16:17], v101, v101, v100
	v_rcp_f32_e32 v104, v103
	s_nop 0
	v_fma_f32 v105, -v103, v104, 1.0
	v_fmac_f32_e32 v104, v105, v104
	v_div_scale_f32 v111, s[16:17], v109, v109, v108
	v_rcp_f32_e32 v112, v111
	s_nop 0
	v_fma_f32 v113, -v111, v112, 1.0
	v_fmac_f32_e32 v112, v113, v112
	v_div_scale_f32 v106, vcc, v100, v101, v100
	v_mul_f32_e32 v102, v106, v104
	v_fma_f32 v105, -v103, v102, v106
	v_fmac_f32_e32 v102, v105, v104
	v_fma_f32 v105, -v103, v102, v106
	v_div_fmas_f32 v102, v105, v104, v102
	v_div_fixup_f32 v102, v102, v101, v100
	v_mul_f32_e32 v78, v78, v102
	v_div_scale_f32 v114, vcc, v108, v109, v108
	v_mul_f32_e32 v110, v114, v112
	v_fma_f32 v113, -v111, v110, v114
	v_fmac_f32_e32 v110, v113, v112
	v_fma_f32 v113, -v111, v110, v114
	v_div_fmas_f32 v110, v113, v112, v110
	v_div_fixup_f32 v110, v110, v109, v108
	v_mul_f32_e32 v79, v79, v110
	v_cvt_pk_bf16_f32 v96, v76, v77
	v_cvt_pk_bf16_f32 v97, v78, v79
	global_store_dwordx2 v1, v[96:97], s[14:15] offset:1024
	v_lshlrev_b32_e32 v100, 16, v50
	v_mul_f32_e32 v101, 0xbfb8aa3b, v100
	v_exp_f32_e32 v101, v101
	v_mul_f32_e32 v80, v80, v91
	v_add_f32_e32 v101, 1.0, v101
	v_mul_f32_e32 v80, v80, v16
	v_and_b32_e32 v108, 0xffff0000, v50
	v_mul_f32_e32 v109, 0xbfb8aa3b, v108
	v_exp_f32_e32 v109, v109
	v_mul_f32_e32 v81, v81, v91
	v_add_f32_e32 v109, 1.0, v109
	v_mul_f32_e32 v81, v81, v17
	v_div_scale_f32 v103, s[16:17], v101, v101, v100
	v_rcp_f32_e32 v104, v103
	s_nop 0
	v_fma_f32 v105, -v103, v104, 1.0
	v_fmac_f32_e32 v104, v105, v104
	v_div_scale_f32 v111, s[16:17], v109, v109, v108
	v_rcp_f32_e32 v112, v111
	s_nop 0
	v_fma_f32 v113, -v111, v112, 1.0
	v_fmac_f32_e32 v112, v113, v112
	v_div_scale_f32 v106, vcc, v100, v101, v100
	v_mul_f32_e32 v102, v106, v104
	v_fma_f32 v105, -v103, v102, v106
	v_fmac_f32_e32 v102, v105, v104
	v_fma_f32 v105, -v103, v102, v106
	v_div_fmas_f32 v102, v105, v104, v102
	v_div_fixup_f32 v102, v102, v101, v100
	v_mul_f32_e32 v80, v80, v102
	v_div_scale_f32 v114, vcc, v108, v109, v108
	v_mul_f32_e32 v110, v114, v112
	v_fma_f32 v113, -v111, v110, v114
	v_fmac_f32_e32 v110, v113, v112
	v_fma_f32 v113, -v111, v110, v114
	v_div_fmas_f32 v110, v113, v112, v110
	v_div_fixup_f32 v110, v110, v109, v108
	v_mul_f32_e32 v81, v81, v110
	v_lshlrev_b32_e32 v100, 16, v51
	v_mul_f32_e32 v101, 0xbfb8aa3b, v100
	v_exp_f32_e32 v101, v101
	v_mul_f32_e32 v82, v82, v91
	v_add_f32_e32 v101, 1.0, v101
	v_mul_f32_e32 v82, v82, v18
	v_and_b32_e32 v108, 0xffff0000, v51
	v_mul_f32_e32 v109, 0xbfb8aa3b, v108
	v_exp_f32_e32 v109, v109
	v_mul_f32_e32 v83, v83, v91
	v_add_f32_e32 v109, 1.0, v109
	v_mul_f32_e32 v83, v83, v19
	v_div_scale_f32 v103, s[16:17], v101, v101, v100
	v_rcp_f32_e32 v104, v103
	s_nop 0
	v_fma_f32 v105, -v103, v104, 1.0
	v_fmac_f32_e32 v104, v105, v104
	v_div_scale_f32 v111, s[16:17], v109, v109, v108
	v_rcp_f32_e32 v112, v111
	s_nop 0
	v_fma_f32 v113, -v111, v112, 1.0
	v_fmac_f32_e32 v112, v113, v112
	v_div_scale_f32 v106, vcc, v100, v101, v100
	v_mul_f32_e32 v102, v106, v104
	v_fma_f32 v105, -v103, v102, v106
	v_fmac_f32_e32 v102, v105, v104
	v_fma_f32 v105, -v103, v102, v106
	v_div_fmas_f32 v102, v105, v104, v102
	v_div_fixup_f32 v102, v102, v101, v100
	v_mul_f32_e32 v82, v82, v102
	v_div_scale_f32 v114, vcc, v108, v109, v108
	v_mul_f32_e32 v110, v114, v112
	v_fma_f32 v113, -v111, v110, v114
	v_fmac_f32_e32 v110, v113, v112
	v_fma_f32 v113, -v111, v110, v114
	v_div_fmas_f32 v110, v113, v112, v110
	v_div_fixup_f32 v110, v110, v109, v108
	v_mul_f32_e32 v83, v83, v110
	v_cvt_pk_bf16_f32 v98, v80, v81
	v_cvt_pk_bf16_f32 v99, v82, v83
	global_store_dwordx2 v1, v[98:99], s[14:15] offset:1536
	s_add_u32 s14, s14, 0x400000
	s_addc_u32 s15, s15, 0
	global_load_dwordx2 v[36:37], v1, s[6:7] offset:0
	global_load_dwordx2 v[38:39], v1, s[6:7] offset:512
	global_load_dwordx2 v[40:41], v1, s[6:7] offset:1024
	global_load_dwordx2 v[42:43], v1, s[6:7] offset:1536
	global_load_dwordx2 v[44:45], v1, s[12:13] offset:0
	global_load_dwordx2 v[46:47], v1, s[12:13] offset:512
	global_load_dwordx2 v[48:49], v1, s[12:13] offset:1024
	global_load_dwordx2 v[50:51], v1, s[12:13] offset:1536
	s_add_u32 s6, s6, 0x400000
	s_addc_u32 s7, s7, 0
	s_add_u32 s12, s12, 0xd00000
	s_addc_u32 s13, s13, 0
	s_waitcnt vmcnt(24)
	v_lshlrev_b32_e32 v68, 16, v52
	v_and_b32_e32 v69, 0xffff0000, v52
	v_lshlrev_b32_e32 v70, 16, v53
	v_and_b32_e32 v71, 0xffff0000, v53
	v_lshlrev_b32_e32 v72, 16, v54
	v_and_b32_e32 v73, 0xffff0000, v54
	v_lshlrev_b32_e32 v74, 16, v55
	v_and_b32_e32 v75, 0xffff0000, v55
	v_lshlrev_b32_e32 v76, 16, v56
	v_and_b32_e32 v77, 0xffff0000, v56
	v_lshlrev_b32_e32 v78, 16, v57
	v_and_b32_e32 v79, 0xffff0000, v57
	v_lshlrev_b32_e32 v80, 16, v58
	v_and_b32_e32 v81, 0xffff0000, v58
	v_lshlrev_b32_e32 v82, 16, v59
	v_and_b32_e32 v83, 0xffff0000, v59
	v_mul_f32_e32 v84, v68, v68
	v_mul_f32_e32 v85, v72, v72
	v_mul_f32_e32 v86, v76, v76
	v_mul_f32_e32 v87, v80, v80
	v_fmac_f32_e32 v84, v69, v69
	v_fmac_f32_e32 v85, v73, v73
	v_fmac_f32_e32 v86, v77, v77
	v_fmac_f32_e32 v87, v81, v81
	v_fmac_f32_e32 v84, v70, v70
	v_fmac_f32_e32 v85, v74, v74
	v_fmac_f32_e32 v86, v78, v78
	v_fmac_f32_e32 v87, v82, v82
	v_fmac_f32_e32 v84, v71, v71
	v_fmac_f32_e32 v85, v75, v75
	v_fmac_f32_e32 v86, v79, v79
	v_fmac_f32_e32 v87, v83, v83
	v_add_f32_dpp v84, v84, v84 quad_perm:[1,0,3,2] row_mask:0xf bank_mask:0xf
	v_add_f32_dpp v85, v85, v85 quad_perm:[1,0,3,2] row_mask:0xf bank_mask:0xf
	v_add_f32_dpp v86, v86, v86 quad_perm:[1,0,3,2] row_mask:0xf bank_mask:0xf
	v_add_f32_dpp v87, v87, v87 quad_perm:[1,0,3,2] row_mask:0xf bank_mask:0xf
	v_add_f32_dpp v84, v84, v84 quad_perm:[2,3,0,1] row_mask:0xf bank_mask:0xf
	v_add_f32_dpp v85, v85, v85 quad_perm:[2,3,0,1] row_mask:0xf bank_mask:0xf
	v_add_f32_dpp v86, v86, v86 quad_perm:[2,3,0,1] row_mask:0xf bank_mask:0xf
	v_add_f32_dpp v87, v87, v87 quad_perm:[2,3,0,1] row_mask:0xf bank_mask:0xf
	v_add_f32_dpp v84, v84, v84 row_half_mirror row_mask:0xf bank_mask:0xf
	v_add_f32_dpp v85, v85, v85 row_half_mirror row_mask:0xf bank_mask:0xf
	v_add_f32_dpp v86, v86, v86 row_half_mirror row_mask:0xf bank_mask:0xf
	v_add_f32_dpp v87, v87, v87 row_half_mirror row_mask:0xf bank_mask:0xf
	v_add_f32_dpp v84, v84, v84 row_mirror row_mask:0xf bank_mask:0xf
	v_add_f32_dpp v85, v85, v85 row_mirror row_mask:0xf bank_mask:0xf
	v_add_f32_dpp v86, v86, v86 row_mirror row_mask:0xf bank_mask:0xf
	v_add_f32_dpp v87, v87, v87 row_mirror row_mask:0xf bank_mask:0xf
	v_add_f32_dpp v84, v84, v84 row_bcast:15 row_mask:0xa bank_mask:0xf
	v_add_f32_dpp v85, v85, v85 row_bcast:15 row_mask:0xa bank_mask:0xf
	v_add_f32_dpp v86, v86, v86 row_bcast:15 row_mask:0xa bank_mask:0xf
	v_add_f32_dpp v87, v87, v87 row_bcast:15 row_mask:0xa bank_mask:0xf
	v_add_f32_dpp v84, v84, v84 row_bcast:31 row_mask:0xc bank_mask:0xf
	v_add_f32_dpp v85, v85, v85 row_bcast:31 row_mask:0xc bank_mask:0xf
	v_add_f32_dpp v86, v86, v86 row_bcast:31 row_mask:0xc bank_mask:0xf
	v_add_f32_dpp v87, v87, v87 row_bcast:31 row_mask:0xc bank_mask:0xf
	s_nop 0
	v_readlane_b32 s28, v84, 63
	v_readlane_b32 s29, v85, 63
	v_readlane_b32 s30, v86, 63
	v_readlane_b32 s31, v87, 63
	s_nop 1
	v_fma_f32 v88, s28, v2, v3
	v_fma_f32 v89, s29, v2, v3
	v_fma_f32 v90, s30, v2, v3
	v_fma_f32 v91, s31, v2, v3
	v_rsq_f32_e32 v88, v88
	v_rsq_f32_e32 v89, v89
	v_rsq_f32_e32 v90, v90
	v_rsq_f32_e32 v91, v91
	s_nop 0
	v_lshlrev_b32_e32 v100, 16, v60
	v_mul_f32_e32 v101, 0xbfb8aa3b, v100
	v_exp_f32_e32 v101, v101
	v_mul_f32_e32 v68, v68, v88
	v_add_f32_e32 v101, 1.0, v101
	v_mul_f32_e32 v68, v68, v4
	v_and_b32_e32 v108, 0xffff0000, v60
	v_mul_f32_e32 v109, 0xbfb8aa3b, v108
	v_exp_f32_e32 v109, v109
	v_mul_f32_e32 v69, v69, v88
	v_add_f32_e32 v109, 1.0, v109
	v_mul_f32_e32 v69, v69, v5
	v_div_scale_f32 v103, s[16:17], v101, v101, v100
	v_rcp_f32_e32 v104, v103
	s_nop 0
	v_fma_f32 v105, -v103, v104, 1.0
	v_fmac_f32_e32 v104, v105, v104
	v_div_scale_f32 v111, s[16:17], v109, v109, v108
	v_rcp_f32_e32 v112, v111
	s_nop 0
	v_fma_f32 v113, -v111, v112, 1.0
	v_fmac_f32_e32 v112, v113, v112
	v_div_scale_f32 v106, vcc, v100, v101, v100
	v_mul_f32_e32 v102, v106, v104
	v_fma_f32 v105, -v103, v102, v106
	v_fmac_f32_e32 v102, v105, v104
	v_fma_f32 v105, -v103, v102, v106
	v_div_fmas_f32 v102, v105, v104, v102
	v_div_fixup_f32 v102, v102, v101, v100
	v_mul_f32_e32 v68, v68, v102
	v_div_scale_f32 v114, vcc, v108, v109, v108
	v_mul_f32_e32 v110, v114, v112
	v_fma_f32 v113, -v111, v110, v114
	v_fmac_f32_e32 v110, v113, v112
	v_fma_f32 v113, -v111, v110, v114
	v_div_fmas_f32 v110, v113, v112, v110
	v_div_fixup_f32 v110, v110, v109, v108
	v_mul_f32_e32 v69, v69, v110
	v_lshlrev_b32_e32 v100, 16, v61
	v_mul_f32_e32 v101, 0xbfb8aa3b, v100
	v_exp_f32_e32 v101, v101
	v_mul_f32_e32 v70, v70, v88
	v_add_f32_e32 v101, 1.0, v101
	v_mul_f32_e32 v70, v70, v6
	v_and_b32_e32 v108, 0xffff0000, v61
	v_mul_f32_e32 v109, 0xbfb8aa3b, v108
	v_exp_f32_e32 v109, v109
	v_mul_f32_e32 v71, v71, v88
	v_add_f32_e32 v109, 1.0, v109
	v_mul_f32_e32 v71, v71, v7
	v_div_scale_f32 v103, s[16:17], v101, v101, v100
	v_rcp_f32_e32 v104, v103
	s_nop 0
	v_fma_f32 v105, -v103, v104, 1.0
	v_fmac_f32_e32 v104, v105, v104
	v_div_scale_f32 v111, s[16:17], v109, v109, v108
	v_rcp_f32_e32 v112, v111
	s_nop 0
	v_fma_f32 v113, -v111, v112, 1.0
	v_fmac_f32_e32 v112, v113, v112
	v_div_scale_f32 v106, vcc, v100, v101, v100
	v_mul_f32_e32 v102, v106, v104
	v_fma_f32 v105, -v103, v102, v106
	v_fmac_f32_e32 v102, v105, v104
	v_fma_f32 v105, -v103, v102, v106
	v_div_fmas_f32 v102, v105, v104, v102
	v_div_fixup_f32 v102, v102, v101, v100
	v_mul_f32_e32 v70, v70, v102
	v_div_scale_f32 v114, vcc, v108, v109, v108
	v_mul_f32_e32 v110, v114, v112
	v_fma_f32 v113, -v111, v110, v114
	v_fmac_f32_e32 v110, v113, v112
	v_fma_f32 v113, -v111, v110, v114
	v_div_fmas_f32 v110, v113, v112, v110
	v_div_fixup_f32 v110, v110, v109, v108
	v_mul_f32_e32 v71, v71, v110
	v_cvt_pk_bf16_f32 v92, v68, v69
	v_cvt_pk_bf16_f32 v93, v70, v71
	global_store_dwordx2 v1, v[92:93], s[14:15] offset:0
	v_lshlrev_b32_e32 v100, 16, v62
	v_mul_f32_e32 v101, 0xbfb8aa3b, v100
	v_exp_f32_e32 v101, v101
	v_mul_f32_e32 v72, v72, v89
	v_add_f32_e32 v101, 1.0, v101
	v_mul_f32_e32 v72, v72, v8
	v_and_b32_e32 v108, 0xffff0000, v62
	v_mul_f32_e32 v109, 0xbfb8aa3b, v108
	v_exp_f32_e32 v109, v109
	v_mul_f32_e32 v73, v73, v89
	v_add_f32_e32 v109, 1.0, v109
	v_mul_f32_e32 v73, v73, v9
	v_div_scale_f32 v103, s[16:17], v101, v101, v100
	v_rcp_f32_e32 v104, v103
	s_nop 0
	v_fma_f32 v105, -v103, v104, 1.0
	v_fmac_f32_e32 v104, v105, v104
	v_div_scale_f32 v111, s[16:17], v109, v109, v108
	v_rcp_f32_e32 v112, v111
	s_nop 0
	v_fma_f32 v113, -v111, v112, 1.0
	v_fmac_f32_e32 v112, v113, v112
	v_div_scale_f32 v106, vcc, v100, v101, v100
	v_mul_f32_e32 v102, v106, v104
	v_fma_f32 v105, -v103, v102, v106
	v_fmac_f32_e32 v102, v105, v104
	v_fma_f32 v105, -v103, v102, v106
	v_div_fmas_f32 v102, v105, v104, v102
	v_div_fixup_f32 v102, v102, v101, v100
	v_mul_f32_e32 v72, v72, v102
	v_div_scale_f32 v114, vcc, v108, v109, v108
	v_mul_f32_e32 v110, v114, v112
	v_fma_f32 v113, -v111, v110, v114
	v_fmac_f32_e32 v110, v113, v112
	v_fma_f32 v113, -v111, v110, v114
	v_div_fmas_f32 v110, v113, v112, v110
	v_div_fixup_f32 v110, v110, v109, v108
	v_mul_f32_e32 v73, v73, v110
	v_lshlrev_b32_e32 v100, 16, v63
	v_mul_f32_e32 v101, 0xbfb8aa3b, v100
	v_exp_f32_e32 v101, v101
	v_mul_f32_e32 v74, v74, v89
	v_add_f32_e32 v101, 1.0, v101
	v_mul_f32_e32 v74, v74, v10
	v_and_b32_e32 v108, 0xffff0000, v63
	v_mul_f32_e32 v109, 0xbfb8aa3b, v108
	v_exp_f32_e32 v109, v109
	v_mul_f32_e32 v75, v75, v89
	v_add_f32_e32 v109, 1.0, v109
	v_mul_f32_e32 v75, v75, v11
	v_div_scale_f32 v103, s[16:17], v101, v101, v100
	v_rcp_f32_e32 v104, v103
	s_nop 0
	v_fma_f32 v105, -v103, v104, 1.0
	v_fmac_f32_e32 v104, v105, v104
	v_div_scale_f32 v111, s[16:17], v109, v109, v108
	v_rcp_f32_e32 v112, v111
	s_nop 0
	v_fma_f32 v113, -v111, v112, 1.0
	v_fmac_f32_e32 v112, v113, v112
	v_div_scale_f32 v106, vcc, v100, v101, v100
	v_mul_f32_e32 v102, v106, v104
	v_fma_f32 v105, -v103, v102, v106
	v_fmac_f32_e32 v102, v105, v104
	v_fma_f32 v105, -v103, v102, v106
	v_div_fmas_f32 v102, v105, v104, v102
	v_div_fixup_f32 v102, v102, v101, v100
	v_mul_f32_e32 v74, v74, v102
	v_div_scale_f32 v114, vcc, v108, v109, v108
	v_mul_f32_e32 v110, v114, v112
	v_fma_f32 v113, -v111, v110, v114
	v_fmac_f32_e32 v110, v113, v112
	v_fma_f32 v113, -v111, v110, v114
	v_div_fmas_f32 v110, v113, v112, v110
	v_div_fixup_f32 v110, v110, v109, v108
	v_mul_f32_e32 v75, v75, v110
	v_cvt_pk_bf16_f32 v94, v72, v73
	v_cvt_pk_bf16_f32 v95, v74, v75
	global_store_dwordx2 v1, v[94:95], s[14:15] offset:512
	v_lshlrev_b32_e32 v100, 16, v64
	v_mul_f32_e32 v101, 0xbfb8aa3b, v100
	v_exp_f32_e32 v101, v101
	v_mul_f32_e32 v76, v76, v90
	v_add_f32_e32 v101, 1.0, v101
	v_mul_f32_e32 v76, v76, v12
	v_and_b32_e32 v108, 0xffff0000, v64
	v_mul_f32_e32 v109, 0xbfb8aa3b, v108
	v_exp_f32_e32 v109, v109
	v_mul_f32_e32 v77, v77, v90
	v_add_f32_e32 v109, 1.0, v109
	v_mul_f32_e32 v77, v77, v13
	v_div_scale_f32 v103, s[16:17], v101, v101, v100
	v_rcp_f32_e32 v104, v103
	s_nop 0
	v_fma_f32 v105, -v103, v104, 1.0
	v_fmac_f32_e32 v104, v105, v104
	v_div_scale_f32 v111, s[16:17], v109, v109, v108
	v_rcp_f32_e32 v112, v111
	s_nop 0
	v_fma_f32 v113, -v111, v112, 1.0
	v_fmac_f32_e32 v112, v113, v112
	v_div_scale_f32 v106, vcc, v100, v101, v100
	v_mul_f32_e32 v102, v106, v104
	v_fma_f32 v105, -v103, v102, v106
	v_fmac_f32_e32 v102, v105, v104
	v_fma_f32 v105, -v103, v102, v106
	v_div_fmas_f32 v102, v105, v104, v102
	v_div_fixup_f32 v102, v102, v101, v100
	v_mul_f32_e32 v76, v76, v102
	v_div_scale_f32 v114, vcc, v108, v109, v108
	v_mul_f32_e32 v110, v114, v112
	v_fma_f32 v113, -v111, v110, v114
	v_fmac_f32_e32 v110, v113, v112
	v_fma_f32 v113, -v111, v110, v114
	v_div_fmas_f32 v110, v113, v112, v110
	v_div_fixup_f32 v110, v110, v109, v108
	v_mul_f32_e32 v77, v77, v110
	v_lshlrev_b32_e32 v100, 16, v65
	v_mul_f32_e32 v101, 0xbfb8aa3b, v100
	v_exp_f32_e32 v101, v101
	v_mul_f32_e32 v78, v78, v90
	v_add_f32_e32 v101, 1.0, v101
	v_mul_f32_e32 v78, v78, v14
	v_and_b32_e32 v108, 0xffff0000, v65
	v_mul_f32_e32 v109, 0xbfb8aa3b, v108
	v_exp_f32_e32 v109, v109
	v_mul_f32_e32 v79, v79, v90
	v_add_f32_e32 v109, 1.0, v109
	v_mul_f32_e32 v79, v79, v15
	v_div_scale_f32 v103, s[16:17], v101, v101, v100
	v_rcp_f32_e32 v104, v103
	s_nop 0
	v_fma_f32 v105, -v103, v104, 1.0
	v_fmac_f32_e32 v104, v105, v104
	v_div_scale_f32 v111, s[16:17], v109, v109, v108
	v_rcp_f32_e32 v112, v111
	s_nop 0
	v_fma_f32 v113, -v111, v112, 1.0
	v_fmac_f32_e32 v112, v113, v112
	v_div_scale_f32 v106, vcc, v100, v101, v100
	v_mul_f32_e32 v102, v106, v104
	v_fma_f32 v105, -v103, v102, v106
	v_fmac_f32_e32 v102, v105, v104
	v_fma_f32 v105, -v103, v102, v106
	v_div_fmas_f32 v102, v105, v104, v102
	v_div_fixup_f32 v102, v102, v101, v100
	v_mul_f32_e32 v78, v78, v102
	v_div_scale_f32 v114, vcc, v108, v109, v108
	v_mul_f32_e32 v110, v114, v112
	v_fma_f32 v113, -v111, v110, v114
	v_fmac_f32_e32 v110, v113, v112
	v_fma_f32 v113, -v111, v110, v114
	v_div_fmas_f32 v110, v113, v112, v110
	v_div_fixup_f32 v110, v110, v109, v108
	v_mul_f32_e32 v79, v79, v110
	v_cvt_pk_bf16_f32 v96, v76, v77
	v_cvt_pk_bf16_f32 v97, v78, v79
	global_store_dwordx2 v1, v[96:97], s[14:15] offset:1024
	v_lshlrev_b32_e32 v100, 16, v66
	v_mul_f32_e32 v101, 0xbfb8aa3b, v100
	v_exp_f32_e32 v101, v101
	v_mul_f32_e32 v80, v80, v91
	v_add_f32_e32 v101, 1.0, v101
	v_mul_f32_e32 v80, v80, v16
	v_and_b32_e32 v108, 0xffff0000, v66
	v_mul_f32_e32 v109, 0xbfb8aa3b, v108
	v_exp_f32_e32 v109, v109
	v_mul_f32_e32 v81, v81, v91
	v_add_f32_e32 v109, 1.0, v109
	v_mul_f32_e32 v81, v81, v17
	v_div_scale_f32 v103, s[16:17], v101, v101, v100
	v_rcp_f32_e32 v104, v103
	s_nop 0
	v_fma_f32 v105, -v103, v104, 1.0
	v_fmac_f32_e32 v104, v105, v104
	v_div_scale_f32 v111, s[16:17], v109, v109, v108
	v_rcp_f32_e32 v112, v111
	s_nop 0
	v_fma_f32 v113, -v111, v112, 1.0
	v_fmac_f32_e32 v112, v113, v112
	v_div_scale_f32 v106, vcc, v100, v101, v100
	v_mul_f32_e32 v102, v106, v104
	v_fma_f32 v105, -v103, v102, v106
	v_fmac_f32_e32 v102, v105, v104
	v_fma_f32 v105, -v103, v102, v106
	v_div_fmas_f32 v102, v105, v104, v102
	v_div_fixup_f32 v102, v102, v101, v100
	v_mul_f32_e32 v80, v80, v102
	v_div_scale_f32 v114, vcc, v108, v109, v108
	v_mul_f32_e32 v110, v114, v112
	v_fma_f32 v113, -v111, v110, v114
	v_fmac_f32_e32 v110, v113, v112
	v_fma_f32 v113, -v111, v110, v114
	v_div_fmas_f32 v110, v113, v112, v110
	v_div_fixup_f32 v110, v110, v109, v108
	v_mul_f32_e32 v81, v81, v110
	v_lshlrev_b32_e32 v100, 16, v67
	v_mul_f32_e32 v101, 0xbfb8aa3b, v100
	v_exp_f32_e32 v101, v101
	v_mul_f32_e32 v82, v82, v91
	v_add_f32_e32 v101, 1.0, v101
	v_mul_f32_e32 v82, v82, v18
	v_and_b32_e32 v108, 0xffff0000, v67
	v_mul_f32_e32 v109, 0xbfb8aa3b, v108
	v_exp_f32_e32 v109, v109
	v_mul_f32_e32 v83, v83, v91
	v_add_f32_e32 v109, 1.0, v109
	v_mul_f32_e32 v83, v83, v19
	v_div_scale_f32 v103, s[16:17], v101, v101, v100
	v_rcp_f32_e32 v104, v103
	s_nop 0
	v_fma_f32 v105, -v103, v104, 1.0
	v_fmac_f32_e32 v104, v105, v104
	v_div_scale_f32 v111, s[16:17], v109, v109, v108
	v_rcp_f32_e32 v112, v111
	s_nop 0
	v_fma_f32 v113, -v111, v112, 1.0
	v_fmac_f32_e32 v112, v113, v112
	v_div_scale_f32 v106, vcc, v100, v101, v100
	v_mul_f32_e32 v102, v106, v104
	v_fma_f32 v105, -v103, v102, v106
	v_fmac_f32_e32 v102, v105, v104
	v_fma_f32 v105, -v103, v102, v106
	v_div_fmas_f32 v102, v105, v104, v102
	v_div_fixup_f32 v102, v102, v101, v100
	v_mul_f32_e32 v82, v82, v102
	v_div_scale_f32 v114, vcc, v108, v109, v108
	v_mul_f32_e32 v110, v114, v112
	v_fma_f32 v113, -v111, v110, v114
	v_fmac_f32_e32 v110, v113, v112
	v_fma_f32 v113, -v111, v110, v114
	v_div_fmas_f32 v110, v113, v112, v110
	v_div_fixup_f32 v110, v110, v109, v108
	v_mul_f32_e32 v83, v83, v110
	v_cvt_pk_bf16_f32 v98, v80, v81
	v_cvt_pk_bf16_f32 v99, v82, v83
	global_store_dwordx2 v1, v[98:99], s[14:15] offset:1536
	s_add_u32 s14, s14, 0x400000
	s_addc_u32 s15, s15, 0
	global_load_dwordx2 v[52:53], v1, s[6:7] offset:0
	global_load_dwordx2 v[54:55], v1, s[6:7] offset:512
	global_load_dwordx2 v[56:57], v1, s[6:7] offset:1024
	global_load_dwordx2 v[58:59], v1, s[6:7] offset:1536
	global_load_dwordx2 v[60:61], v1, s[12:13] offset:0
	global_load_dwordx2 v[62:63], v1, s[12:13] offset:512
	global_load_dwordx2 v[64:65], v1, s[12:13] offset:1024
	global_load_dwordx2 v[66:67], v1, s[12:13] offset:1536
	s_add_u32 s6, s6, 0x400000
	s_addc_u32 s7, s7, 0
	s_add_u32 s12, s12, 0xd00000
	s_addc_u32 s13, s13, 0
	s_waitcnt vmcnt(24)
	v_lshlrev_b32_e32 v68, 16, v20
	v_and_b32_e32 v69, 0xffff0000, v20
	v_lshlrev_b32_e32 v70, 16, v21
	v_and_b32_e32 v71, 0xffff0000, v21
	v_lshlrev_b32_e32 v72, 16, v22
	v_and_b32_e32 v73, 0xffff0000, v22
	v_lshlrev_b32_e32 v74, 16, v23
	v_and_b32_e32 v75, 0xffff0000, v23
	v_lshlrev_b32_e32 v76, 16, v24
	v_and_b32_e32 v77, 0xffff0000, v24
	v_lshlrev_b32_e32 v78, 16, v25
	v_and_b32_e32 v79, 0xffff0000, v25
	v_lshlrev_b32_e32 v80, 16, v26
	v_and_b32_e32 v81, 0xffff0000, v26
	v_lshlrev_b32_e32 v82, 16, v27
	v_and_b32_e32 v83, 0xffff0000, v27
	v_mul_f32_e32 v84, v68, v68
	v_mul_f32_e32 v85, v72, v72
	v_mul_f32_e32 v86, v76, v76
	v_mul_f32_e32 v87, v80, v80
	v_fmac_f32_e32 v84, v69, v69
	v_fmac_f32_e32 v85, v73, v73
	v_fmac_f32_e32 v86, v77, v77
	v_fmac_f32_e32 v87, v81, v81
	v_fmac_f32_e32 v84, v70, v70
	v_fmac_f32_e32 v85, v74, v74
	v_fmac_f32_e32 v86, v78, v78
	v_fmac_f32_e32 v87, v82, v82
	v_fmac_f32_e32 v84, v71, v71
	v_fmac_f32_e32 v85, v75, v75
	v_fmac_f32_e32 v86, v79, v79
	v_fmac_f32_e32 v87, v83, v83
	v_add_f32_dpp v84, v84, v84 quad_perm:[1,0,3,2] row_mask:0xf bank_mask:0xf
	v_add_f32_dpp v85, v85, v85 quad_perm:[1,0,3,2] row_mask:0xf bank_mask:0xf
	v_add_f32_dpp v86, v86, v86 quad_perm:[1,0,3,2] row_mask:0xf bank_mask:0xf
	v_add_f32_dpp v87, v87, v87 quad_perm:[1,0,3,2] row_mask:0xf bank_mask:0xf
	v_add_f32_dpp v84, v84, v84 quad_perm:[2,3,0,1] row_mask:0xf bank_mask:0xf
	v_add_f32_dpp v85, v85, v85 quad_perm:[2,3,0,1] row_mask:0xf bank_mask:0xf
	v_add_f32_dpp v86, v86, v86 quad_perm:[2,3,0,1] row_mask:0xf bank_mask:0xf
	v_add_f32_dpp v87, v87, v87 quad_perm:[2,3,0,1] row_mask:0xf bank_mask:0xf
	v_add_f32_dpp v84, v84, v84 row_half_mirror row_mask:0xf bank_mask:0xf
	v_add_f32_dpp v85, v85, v85 row_half_mirror row_mask:0xf bank_mask:0xf
	v_add_f32_dpp v86, v86, v86 row_half_mirror row_mask:0xf bank_mask:0xf
	v_add_f32_dpp v87, v87, v87 row_half_mirror row_mask:0xf bank_mask:0xf
	v_add_f32_dpp v84, v84, v84 row_mirror row_mask:0xf bank_mask:0xf
	v_add_f32_dpp v85, v85, v85 row_mirror row_mask:0xf bank_mask:0xf
	v_add_f32_dpp v86, v86, v86 row_mirror row_mask:0xf bank_mask:0xf
	v_add_f32_dpp v87, v87, v87 row_mirror row_mask:0xf bank_mask:0xf
	v_add_f32_dpp v84, v84, v84 row_bcast:15 row_mask:0xa bank_mask:0xf
	v_add_f32_dpp v85, v85, v85 row_bcast:15 row_mask:0xa bank_mask:0xf
	v_add_f32_dpp v86, v86, v86 row_bcast:15 row_mask:0xa bank_mask:0xf
	v_add_f32_dpp v87, v87, v87 row_bcast:15 row_mask:0xa bank_mask:0xf
	v_add_f32_dpp v84, v84, v84 row_bcast:31 row_mask:0xc bank_mask:0xf
	v_add_f32_dpp v85, v85, v85 row_bcast:31 row_mask:0xc bank_mask:0xf
	v_add_f32_dpp v86, v86, v86 row_bcast:31 row_mask:0xc bank_mask:0xf
	v_add_f32_dpp v87, v87, v87 row_bcast:31 row_mask:0xc bank_mask:0xf
	s_nop 0
	v_readlane_b32 s28, v84, 63
	v_readlane_b32 s29, v85, 63
	v_readlane_b32 s30, v86, 63
	v_readlane_b32 s31, v87, 63
	s_nop 1
	v_fma_f32 v88, s28, v2, v3
	v_fma_f32 v89, s29, v2, v3
	v_fma_f32 v90, s30, v2, v3
	v_fma_f32 v91, s31, v2, v3
	v_rsq_f32_e32 v88, v88
	v_rsq_f32_e32 v89, v89
	v_rsq_f32_e32 v90, v90
	v_rsq_f32_e32 v91, v91
	s_nop 0
	v_lshlrev_b32_e32 v100, 16, v28
	v_mul_f32_e32 v101, 0xbfb8aa3b, v100
	v_exp_f32_e32 v101, v101
	v_mul_f32_e32 v68, v68, v88
	v_add_f32_e32 v101, 1.0, v101
	v_mul_f32_e32 v68, v68, v4
	v_and_b32_e32 v108, 0xffff0000, v28
	v_mul_f32_e32 v109, 0xbfb8aa3b, v108
	v_exp_f32_e32 v109, v109
	v_mul_f32_e32 v69, v69, v88
	v_add_f32_e32 v109, 1.0, v109
	v_mul_f32_e32 v69, v69, v5
	v_div_scale_f32 v103, s[16:17], v101, v101, v100
	v_rcp_f32_e32 v104, v103
	s_nop 0
	v_fma_f32 v105, -v103, v104, 1.0
	v_fmac_f32_e32 v104, v105, v104
	v_div_scale_f32 v111, s[16:17], v109, v109, v108
	v_rcp_f32_e32 v112, v111
	s_nop 0
	v_fma_f32 v113, -v111, v112, 1.0
	v_fmac_f32_e32 v112, v113, v112
	v_div_scale_f32 v106, vcc, v100, v101, v100
	v_mul_f32_e32 v102, v106, v104
	v_fma_f32 v105, -v103, v102, v106
	v_fmac_f32_e32 v102, v105, v104
	v_fma_f32 v105, -v103, v102, v106
	v_div_fmas_f32 v102, v105, v104, v102
	v_div_fixup_f32 v102, v102, v101, v100
	v_mul_f32_e32 v68, v68, v102
	v_div_scale_f32 v114, vcc, v108, v109, v108
	v_mul_f32_e32 v110, v114, v112
	v_fma_f32 v113, -v111, v110, v114
	v_fmac_f32_e32 v110, v113, v112
	v_fma_f32 v113, -v111, v110, v114
	v_div_fmas_f32 v110, v113, v112, v110
	v_div_fixup_f32 v110, v110, v109, v108
	v_mul_f32_e32 v69, v69, v110
	v_lshlrev_b32_e32 v100, 16, v29
	v_mul_f32_e32 v101, 0xbfb8aa3b, v100
	v_exp_f32_e32 v101, v101
	v_mul_f32_e32 v70, v70, v88
	v_add_f32_e32 v101, 1.0, v101
	v_mul_f32_e32 v70, v70, v6
	v_and_b32_e32 v108, 0xffff0000, v29
	v_mul_f32_e32 v109, 0xbfb8aa3b, v108
	v_exp_f32_e32 v109, v109
	v_mul_f32_e32 v71, v71, v88
	v_add_f32_e32 v109, 1.0, v109
	v_mul_f32_e32 v71, v71, v7
	v_div_scale_f32 v103, s[16:17], v101, v101, v100
	v_rcp_f32_e32 v104, v103
	s_nop 0
	v_fma_f32 v105, -v103, v104, 1.0
	v_fmac_f32_e32 v104, v105, v104
	v_div_scale_f32 v111, s[16:17], v109, v109, v108
	v_rcp_f32_e32 v112, v111
	s_nop 0
	v_fma_f32 v113, -v111, v112, 1.0
	v_fmac_f32_e32 v112, v113, v112
	v_div_scale_f32 v106, vcc, v100, v101, v100
	v_mul_f32_e32 v102, v106, v104
	v_fma_f32 v105, -v103, v102, v106
	v_fmac_f32_e32 v102, v105, v104
	v_fma_f32 v105, -v103, v102, v106
	v_div_fmas_f32 v102, v105, v104, v102
	v_div_fixup_f32 v102, v102, v101, v100
	v_mul_f32_e32 v70, v70, v102
	v_div_scale_f32 v114, vcc, v108, v109, v108
	v_mul_f32_e32 v110, v114, v112
	v_fma_f32 v113, -v111, v110, v114
	v_fmac_f32_e32 v110, v113, v112
	v_fma_f32 v113, -v111, v110, v114
	v_div_fmas_f32 v110, v113, v112, v110
	v_div_fixup_f32 v110, v110, v109, v108
	v_mul_f32_e32 v71, v71, v110
	v_cvt_pk_bf16_f32 v92, v68, v69
	v_cvt_pk_bf16_f32 v93, v70, v71
	global_store_dwordx2 v1, v[92:93], s[14:15] offset:0
	v_lshlrev_b32_e32 v100, 16, v30
	v_mul_f32_e32 v101, 0xbfb8aa3b, v100
	v_exp_f32_e32 v101, v101
	v_mul_f32_e32 v72, v72, v89
	v_add_f32_e32 v101, 1.0, v101
	v_mul_f32_e32 v72, v72, v8
	v_and_b32_e32 v108, 0xffff0000, v30
	v_mul_f32_e32 v109, 0xbfb8aa3b, v108
	v_exp_f32_e32 v109, v109
	v_mul_f32_e32 v73, v73, v89
	v_add_f32_e32 v109, 1.0, v109
	v_mul_f32_e32 v73, v73, v9
	v_div_scale_f32 v103, s[16:17], v101, v101, v100
	v_rcp_f32_e32 v104, v103
	s_nop 0
	v_fma_f32 v105, -v103, v104, 1.0
	v_fmac_f32_e32 v104, v105, v104
	v_div_scale_f32 v111, s[16:17], v109, v109, v108
	v_rcp_f32_e32 v112, v111
	s_nop 0
	v_fma_f32 v113, -v111, v112, 1.0
	v_fmac_f32_e32 v112, v113, v112
	v_div_scale_f32 v106, vcc, v100, v101, v100
	v_mul_f32_e32 v102, v106, v104
	v_fma_f32 v105, -v103, v102, v106
	v_fmac_f32_e32 v102, v105, v104
	v_fma_f32 v105, -v103, v102, v106
	v_div_fmas_f32 v102, v105, v104, v102
	v_div_fixup_f32 v102, v102, v101, v100
	v_mul_f32_e32 v72, v72, v102
	v_div_scale_f32 v114, vcc, v108, v109, v108
	v_mul_f32_e32 v110, v114, v112
	v_fma_f32 v113, -v111, v110, v114
	v_fmac_f32_e32 v110, v113, v112
	v_fma_f32 v113, -v111, v110, v114
	v_div_fmas_f32 v110, v113, v112, v110
	v_div_fixup_f32 v110, v110, v109, v108
	v_mul_f32_e32 v73, v73, v110
	v_lshlrev_b32_e32 v100, 16, v31
	v_mul_f32_e32 v101, 0xbfb8aa3b, v100
	v_exp_f32_e32 v101, v101
	v_mul_f32_e32 v74, v74, v89
	v_add_f32_e32 v101, 1.0, v101
	v_mul_f32_e32 v74, v74, v10
	v_and_b32_e32 v108, 0xffff0000, v31
	v_mul_f32_e32 v109, 0xbfb8aa3b, v108
	v_exp_f32_e32 v109, v109
	v_mul_f32_e32 v75, v75, v89
	v_add_f32_e32 v109, 1.0, v109
	v_mul_f32_e32 v75, v75, v11
	v_div_scale_f32 v103, s[16:17], v101, v101, v100
	v_rcp_f32_e32 v104, v103
	s_nop 0
	v_fma_f32 v105, -v103, v104, 1.0
	v_fmac_f32_e32 v104, v105, v104
	v_div_scale_f32 v111, s[16:17], v109, v109, v108
	v_rcp_f32_e32 v112, v111
	s_nop 0
	v_fma_f32 v113, -v111, v112, 1.0
	v_fmac_f32_e32 v112, v113, v112
	v_div_scale_f32 v106, vcc, v100, v101, v100
	v_mul_f32_e32 v102, v106, v104
	v_fma_f32 v105, -v103, v102, v106
	v_fmac_f32_e32 v102, v105, v104
	v_fma_f32 v105, -v103, v102, v106
	v_div_fmas_f32 v102, v105, v104, v102
	v_div_fixup_f32 v102, v102, v101, v100
	v_mul_f32_e32 v74, v74, v102
	v_div_scale_f32 v114, vcc, v108, v109, v108
	v_mul_f32_e32 v110, v114, v112
	v_fma_f32 v113, -v111, v110, v114
	v_fmac_f32_e32 v110, v113, v112
	v_fma_f32 v113, -v111, v110, v114
	v_div_fmas_f32 v110, v113, v112, v110
	v_div_fixup_f32 v110, v110, v109, v108
	v_mul_f32_e32 v75, v75, v110
	v_cvt_pk_bf16_f32 v94, v72, v73
	v_cvt_pk_bf16_f32 v95, v74, v75
	global_store_dwordx2 v1, v[94:95], s[14:15] offset:512
	v_lshlrev_b32_e32 v100, 16, v32
	v_mul_f32_e32 v101, 0xbfb8aa3b, v100
	v_exp_f32_e32 v101, v101
	v_mul_f32_e32 v76, v76, v90
	v_add_f32_e32 v101, 1.0, v101
	v_mul_f32_e32 v76, v76, v12
	v_and_b32_e32 v108, 0xffff0000, v32
	v_mul_f32_e32 v109, 0xbfb8aa3b, v108
	v_exp_f32_e32 v109, v109
	v_mul_f32_e32 v77, v77, v90
	v_add_f32_e32 v109, 1.0, v109
	v_mul_f32_e32 v77, v77, v13
	v_div_scale_f32 v103, s[16:17], v101, v101, v100
	v_rcp_f32_e32 v104, v103
	s_nop 0
	v_fma_f32 v105, -v103, v104, 1.0
	v_fmac_f32_e32 v104, v105, v104
	v_div_scale_f32 v111, s[16:17], v109, v109, v108
	v_rcp_f32_e32 v112, v111
	s_nop 0
	v_fma_f32 v113, -v111, v112, 1.0
	v_fmac_f32_e32 v112, v113, v112
	v_div_scale_f32 v106, vcc, v100, v101, v100
	v_mul_f32_e32 v102, v106, v104
	v_fma_f32 v105, -v103, v102, v106
	v_fmac_f32_e32 v102, v105, v104
	v_fma_f32 v105, -v103, v102, v106
	v_div_fmas_f32 v102, v105, v104, v102
	v_div_fixup_f32 v102, v102, v101, v100
	v_mul_f32_e32 v76, v76, v102
	v_div_scale_f32 v114, vcc, v108, v109, v108
	v_mul_f32_e32 v110, v114, v112
	v_fma_f32 v113, -v111, v110, v114
	v_fmac_f32_e32 v110, v113, v112
	v_fma_f32 v113, -v111, v110, v114
	v_div_fmas_f32 v110, v113, v112, v110
	v_div_fixup_f32 v110, v110, v109, v108
	v_mul_f32_e32 v77, v77, v110
	v_lshlrev_b32_e32 v100, 16, v33
	v_mul_f32_e32 v101, 0xbfb8aa3b, v100
	v_exp_f32_e32 v101, v101
	v_mul_f32_e32 v78, v78, v90
	v_add_f32_e32 v101, 1.0, v101
	v_mul_f32_e32 v78, v78, v14
	v_and_b32_e32 v108, 0xffff0000, v33
	v_mul_f32_e32 v109, 0xbfb8aa3b, v108
	v_exp_f32_e32 v109, v109
	v_mul_f32_e32 v79, v79, v90
	v_add_f32_e32 v109, 1.0, v109
	v_mul_f32_e32 v79, v79, v15
	v_div_scale_f32 v103, s[16:17], v101, v101, v100
	v_rcp_f32_e32 v104, v103
	s_nop 0
	v_fma_f32 v105, -v103, v104, 1.0
	v_fmac_f32_e32 v104, v105, v104
	v_div_scale_f32 v111, s[16:17], v109, v109, v108
	v_rcp_f32_e32 v112, v111
	s_nop 0
	v_fma_f32 v113, -v111, v112, 1.0
	v_fmac_f32_e32 v112, v113, v112
	v_div_scale_f32 v106, vcc, v100, v101, v100
	v_mul_f32_e32 v102, v106, v104
	v_fma_f32 v105, -v103, v102, v106
	v_fmac_f32_e32 v102, v105, v104
	v_fma_f32 v105, -v103, v102, v106
	v_div_fmas_f32 v102, v105, v104, v102
	v_div_fixup_f32 v102, v102, v101, v100
	v_mul_f32_e32 v78, v78, v102
	v_div_scale_f32 v114, vcc, v108, v109, v108
	v_mul_f32_e32 v110, v114, v112
	v_fma_f32 v113, -v111, v110, v114
	v_fmac_f32_e32 v110, v113, v112
	v_fma_f32 v113, -v111, v110, v114
	v_div_fmas_f32 v110, v113, v112, v110
	v_div_fixup_f32 v110, v110, v109, v108
	v_mul_f32_e32 v79, v79, v110
	v_cvt_pk_bf16_f32 v96, v76, v77
	v_cvt_pk_bf16_f32 v97, v78, v79
	global_store_dwordx2 v1, v[96:97], s[14:15] offset:1024
	v_lshlrev_b32_e32 v100, 16, v34
	v_mul_f32_e32 v101, 0xbfb8aa3b, v100
	v_exp_f32_e32 v101, v101
	v_mul_f32_e32 v80, v80, v91
	v_add_f32_e32 v101, 1.0, v101
	v_mul_f32_e32 v80, v80, v16
	v_and_b32_e32 v108, 0xffff0000, v34
	v_mul_f32_e32 v109, 0xbfb8aa3b, v108
	v_exp_f32_e32 v109, v109
	v_mul_f32_e32 v81, v81, v91
	v_add_f32_e32 v109, 1.0, v109
	v_mul_f32_e32 v81, v81, v17
	v_div_scale_f32 v103, s[16:17], v101, v101, v100
	v_rcp_f32_e32 v104, v103
	s_nop 0
	v_fma_f32 v105, -v103, v104, 1.0
	v_fmac_f32_e32 v104, v105, v104
	v_div_scale_f32 v111, s[16:17], v109, v109, v108
	v_rcp_f32_e32 v112, v111
	s_nop 0
	v_fma_f32 v113, -v111, v112, 1.0
	v_fmac_f32_e32 v112, v113, v112
	v_div_scale_f32 v106, vcc, v100, v101, v100
	v_mul_f32_e32 v102, v106, v104
	v_fma_f32 v105, -v103, v102, v106
	v_fmac_f32_e32 v102, v105, v104
	v_fma_f32 v105, -v103, v102, v106
	v_div_fmas_f32 v102, v105, v104, v102
	v_div_fixup_f32 v102, v102, v101, v100
	v_mul_f32_e32 v80, v80, v102
	v_div_scale_f32 v114, vcc, v108, v109, v108
	v_mul_f32_e32 v110, v114, v112
	v_fma_f32 v113, -v111, v110, v114
	v_fmac_f32_e32 v110, v113, v112
	v_fma_f32 v113, -v111, v110, v114
	v_div_fmas_f32 v110, v113, v112, v110
	v_div_fixup_f32 v110, v110, v109, v108
	v_mul_f32_e32 v81, v81, v110
	v_lshlrev_b32_e32 v100, 16, v35
	v_mul_f32_e32 v101, 0xbfb8aa3b, v100
	v_exp_f32_e32 v101, v101
	v_mul_f32_e32 v82, v82, v91
	v_add_f32_e32 v101, 1.0, v101
	v_mul_f32_e32 v82, v82, v18
	v_and_b32_e32 v108, 0xffff0000, v35
	v_mul_f32_e32 v109, 0xbfb8aa3b, v108
	v_exp_f32_e32 v109, v109
	v_mul_f32_e32 v83, v83, v91
	v_add_f32_e32 v109, 1.0, v109
	v_mul_f32_e32 v83, v83, v19
	v_div_scale_f32 v103, s[16:17], v101, v101, v100
	v_rcp_f32_e32 v104, v103
	s_nop 0
	v_fma_f32 v105, -v103, v104, 1.0
	v_fmac_f32_e32 v104, v105, v104
	v_div_scale_f32 v111, s[16:17], v109, v109, v108
	v_rcp_f32_e32 v112, v111
	s_nop 0
	v_fma_f32 v113, -v111, v112, 1.0
	v_fmac_f32_e32 v112, v113, v112
	v_div_scale_f32 v106, vcc, v100, v101, v100
	v_mul_f32_e32 v102, v106, v104
	v_fma_f32 v105, -v103, v102, v106
	v_fmac_f32_e32 v102, v105, v104
	v_fma_f32 v105, -v103, v102, v106
	v_div_fmas_f32 v102, v105, v104, v102
	v_div_fixup_f32 v102, v102, v101, v100
	v_mul_f32_e32 v82, v82, v102
	v_div_scale_f32 v114, vcc, v108, v109, v108
	v_mul_f32_e32 v110, v114, v112
	v_fma_f32 v113, -v111, v110, v114
	v_fmac_f32_e32 v110, v113, v112
	v_fma_f32 v113, -v111, v110, v114
	v_div_fmas_f32 v110, v113, v112, v110
	v_div_fixup_f32 v110, v110, v109, v108
	v_mul_f32_e32 v83, v83, v110
	v_cvt_pk_bf16_f32 v98, v80, v81
	v_cvt_pk_bf16_f32 v99, v82, v83
	global_store_dwordx2 v1, v[98:99], s[14:15] offset:1536
	s_add_u32 s14, s14, 0x400000
	s_addc_u32 s15, s15, 0
	global_load_dwordx2 v[20:21], v1, s[6:7] offset:0
	global_load_dwordx2 v[22:23], v1, s[6:7] offset:512
	global_load_dwordx2 v[24:25], v1, s[6:7] offset:1024
	global_load_dwordx2 v[26:27], v1, s[6:7] offset:1536
	global_load_dwordx2 v[28:29], v1, s[12:13] offset:0
	global_load_dwordx2 v[30:31], v1, s[12:13] offset:512
	global_load_dwordx2 v[32:33], v1, s[12:13] offset:1024
	global_load_dwordx2 v[34:35], v1, s[12:13] offset:1536
	s_add_u32 s6, s6, 0x400000
	s_addc_u32 s7, s7, 0
	s_add_u32 s12, s12, 0xd00000
	s_addc_u32 s13, s13, 0
	s_waitcnt vmcnt(24)
	v_lshlrev_b32_e32 v68, 16, v36
	v_and_b32_e32 v69, 0xffff0000, v36
	v_lshlrev_b32_e32 v70, 16, v37
	v_and_b32_e32 v71, 0xffff0000, v37
	v_lshlrev_b32_e32 v72, 16, v38
	v_and_b32_e32 v73, 0xffff0000, v38
	v_lshlrev_b32_e32 v74, 16, v39
	v_and_b32_e32 v75, 0xffff0000, v39
	v_lshlrev_b32_e32 v76, 16, v40
	v_and_b32_e32 v77, 0xffff0000, v40
	v_lshlrev_b32_e32 v78, 16, v41
	v_and_b32_e32 v79, 0xffff0000, v41
	v_lshlrev_b32_e32 v80, 16, v42
	v_and_b32_e32 v81, 0xffff0000, v42
	v_lshlrev_b32_e32 v82, 16, v43
	v_and_b32_e32 v83, 0xffff0000, v43
	v_mul_f32_e32 v84, v68, v68
	v_mul_f32_e32 v85, v72, v72
	v_mul_f32_e32 v86, v76, v76
	v_mul_f32_e32 v87, v80, v80
	v_fmac_f32_e32 v84, v69, v69
	v_fmac_f32_e32 v85, v73, v73
	v_fmac_f32_e32 v86, v77, v77
	v_fmac_f32_e32 v87, v81, v81
	v_fmac_f32_e32 v84, v70, v70
	v_fmac_f32_e32 v85, v74, v74
	v_fmac_f32_e32 v86, v78, v78
	v_fmac_f32_e32 v87, v82, v82
	v_fmac_f32_e32 v84, v71, v71
	v_fmac_f32_e32 v85, v75, v75
	v_fmac_f32_e32 v86, v79, v79
	v_fmac_f32_e32 v87, v83, v83
	v_add_f32_dpp v84, v84, v84 quad_perm:[1,0,3,2] row_mask:0xf bank_mask:0xf
	v_add_f32_dpp v85, v85, v85 quad_perm:[1,0,3,2] row_mask:0xf bank_mask:0xf
	v_add_f32_dpp v86, v86, v86 quad_perm:[1,0,3,2] row_mask:0xf bank_mask:0xf
	v_add_f32_dpp v87, v87, v87 quad_perm:[1,0,3,2] row_mask:0xf bank_mask:0xf
	v_add_f32_dpp v84, v84, v84 quad_perm:[2,3,0,1] row_mask:0xf bank_mask:0xf
	v_add_f32_dpp v85, v85, v85 quad_perm:[2,3,0,1] row_mask:0xf bank_mask:0xf
	v_add_f32_dpp v86, v86, v86 quad_perm:[2,3,0,1] row_mask:0xf bank_mask:0xf
	v_add_f32_dpp v87, v87, v87 quad_perm:[2,3,0,1] row_mask:0xf bank_mask:0xf
	v_add_f32_dpp v84, v84, v84 row_half_mirror row_mask:0xf bank_mask:0xf
	v_add_f32_dpp v85, v85, v85 row_half_mirror row_mask:0xf bank_mask:0xf
	v_add_f32_dpp v86, v86, v86 row_half_mirror row_mask:0xf bank_mask:0xf
	v_add_f32_dpp v87, v87, v87 row_half_mirror row_mask:0xf bank_mask:0xf
	v_add_f32_dpp v84, v84, v84 row_mirror row_mask:0xf bank_mask:0xf
	v_add_f32_dpp v85, v85, v85 row_mirror row_mask:0xf bank_mask:0xf
	v_add_f32_dpp v86, v86, v86 row_mirror row_mask:0xf bank_mask:0xf
	v_add_f32_dpp v87, v87, v87 row_mirror row_mask:0xf bank_mask:0xf
	v_add_f32_dpp v84, v84, v84 row_bcast:15 row_mask:0xa bank_mask:0xf
	v_add_f32_dpp v85, v85, v85 row_bcast:15 row_mask:0xa bank_mask:0xf
	v_add_f32_dpp v86, v86, v86 row_bcast:15 row_mask:0xa bank_mask:0xf
	v_add_f32_dpp v87, v87, v87 row_bcast:15 row_mask:0xa bank_mask:0xf
	v_add_f32_dpp v84, v84, v84 row_bcast:31 row_mask:0xc bank_mask:0xf
	v_add_f32_dpp v85, v85, v85 row_bcast:31 row_mask:0xc bank_mask:0xf
	v_add_f32_dpp v86, v86, v86 row_bcast:31 row_mask:0xc bank_mask:0xf
	v_add_f32_dpp v87, v87, v87 row_bcast:31 row_mask:0xc bank_mask:0xf
	s_nop 0
	v_readlane_b32 s28, v84, 63
	v_readlane_b32 s29, v85, 63
	v_readlane_b32 s30, v86, 63
	v_readlane_b32 s31, v87, 63
	s_nop 1
	v_fma_f32 v88, s28, v2, v3
	v_fma_f32 v89, s29, v2, v3
	v_fma_f32 v90, s30, v2, v3
	v_fma_f32 v91, s31, v2, v3
	v_rsq_f32_e32 v88, v88
	v_rsq_f32_e32 v89, v89
	v_rsq_f32_e32 v90, v90
	v_rsq_f32_e32 v91, v91
	s_nop 0
	v_lshlrev_b32_e32 v100, 16, v44
	v_mul_f32_e32 v101, 0xbfb8aa3b, v100
	v_exp_f32_e32 v101, v101
	v_mul_f32_e32 v68, v68, v88
	v_add_f32_e32 v101, 1.0, v101
	v_mul_f32_e32 v68, v68, v4
	v_and_b32_e32 v108, 0xffff0000, v44
	v_mul_f32_e32 v109, 0xbfb8aa3b, v108
	v_exp_f32_e32 v109, v109
	v_mul_f32_e32 v69, v69, v88
	v_add_f32_e32 v109, 1.0, v109
	v_mul_f32_e32 v69, v69, v5
	v_div_scale_f32 v103, s[16:17], v101, v101, v100
	v_rcp_f32_e32 v104, v103
	s_nop 0
	v_fma_f32 v105, -v103, v104, 1.0
	v_fmac_f32_e32 v104, v105, v104
	v_div_scale_f32 v111, s[16:17], v109, v109, v108
	v_rcp_f32_e32 v112, v111
	s_nop 0
	v_fma_f32 v113, -v111, v112, 1.0
	v_fmac_f32_e32 v112, v113, v112
	v_div_scale_f32 v106, vcc, v100, v101, v100
	v_mul_f32_e32 v102, v106, v104
	v_fma_f32 v105, -v103, v102, v106
	v_fmac_f32_e32 v102, v105, v104
	v_fma_f32 v105, -v103, v102, v106
	v_div_fmas_f32 v102, v105, v104, v102
	v_div_fixup_f32 v102, v102, v101, v100
	v_mul_f32_e32 v68, v68, v102
	v_div_scale_f32 v114, vcc, v108, v109, v108
	v_mul_f32_e32 v110, v114, v112
	v_fma_f32 v113, -v111, v110, v114
	v_fmac_f32_e32 v110, v113, v112
	v_fma_f32 v113, -v111, v110, v114
	v_div_fmas_f32 v110, v113, v112, v110
	v_div_fixup_f32 v110, v110, v109, v108
	v_mul_f32_e32 v69, v69, v110
	v_lshlrev_b32_e32 v100, 16, v45
	v_mul_f32_e32 v101, 0xbfb8aa3b, v100
	v_exp_f32_e32 v101, v101
	v_mul_f32_e32 v70, v70, v88
	v_add_f32_e32 v101, 1.0, v101
	v_mul_f32_e32 v70, v70, v6
	v_and_b32_e32 v108, 0xffff0000, v45
	v_mul_f32_e32 v109, 0xbfb8aa3b, v108
	v_exp_f32_e32 v109, v109
	v_mul_f32_e32 v71, v71, v88
	v_add_f32_e32 v109, 1.0, v109
	v_mul_f32_e32 v71, v71, v7
	v_div_scale_f32 v103, s[16:17], v101, v101, v100
	v_rcp_f32_e32 v104, v103
	s_nop 0
	v_fma_f32 v105, -v103, v104, 1.0
	v_fmac_f32_e32 v104, v105, v104
	v_div_scale_f32 v111, s[16:17], v109, v109, v108
	v_rcp_f32_e32 v112, v111
	s_nop 0
	v_fma_f32 v113, -v111, v112, 1.0
	v_fmac_f32_e32 v112, v113, v112
	v_div_scale_f32 v106, vcc, v100, v101, v100
	v_mul_f32_e32 v102, v106, v104
	v_fma_f32 v105, -v103, v102, v106
	v_fmac_f32_e32 v102, v105, v104
	v_fma_f32 v105, -v103, v102, v106
	v_div_fmas_f32 v102, v105, v104, v102
	v_div_fixup_f32 v102, v102, v101, v100
	v_mul_f32_e32 v70, v70, v102
	v_div_scale_f32 v114, vcc, v108, v109, v108
	v_mul_f32_e32 v110, v114, v112
	v_fma_f32 v113, -v111, v110, v114
	v_fmac_f32_e32 v110, v113, v112
	v_fma_f32 v113, -v111, v110, v114
	v_div_fmas_f32 v110, v113, v112, v110
	v_div_fixup_f32 v110, v110, v109, v108
	v_mul_f32_e32 v71, v71, v110
	v_cvt_pk_bf16_f32 v92, v68, v69
	v_cvt_pk_bf16_f32 v93, v70, v71
	global_store_dwordx2 v1, v[92:93], s[14:15] offset:0
	v_lshlrev_b32_e32 v100, 16, v46
	v_mul_f32_e32 v101, 0xbfb8aa3b, v100
	v_exp_f32_e32 v101, v101
	v_mul_f32_e32 v72, v72, v89
	v_add_f32_e32 v101, 1.0, v101
	v_mul_f32_e32 v72, v72, v8
	v_and_b32_e32 v108, 0xffff0000, v46
	v_mul_f32_e32 v109, 0xbfb8aa3b, v108
	v_exp_f32_e32 v109, v109
	v_mul_f32_e32 v73, v73, v89
	v_add_f32_e32 v109, 1.0, v109
	v_mul_f32_e32 v73, v73, v9
	v_div_scale_f32 v103, s[16:17], v101, v101, v100
	v_rcp_f32_e32 v104, v103
	s_nop 0
	v_fma_f32 v105, -v103, v104, 1.0
	v_fmac_f32_e32 v104, v105, v104
	v_div_scale_f32 v111, s[16:17], v109, v109, v108
	v_rcp_f32_e32 v112, v111
	s_nop 0
	v_fma_f32 v113, -v111, v112, 1.0
	v_fmac_f32_e32 v112, v113, v112
	v_div_scale_f32 v106, vcc, v100, v101, v100
	v_mul_f32_e32 v102, v106, v104
	v_fma_f32 v105, -v103, v102, v106
	v_fmac_f32_e32 v102, v105, v104
	v_fma_f32 v105, -v103, v102, v106
	v_div_fmas_f32 v102, v105, v104, v102
	v_div_fixup_f32 v102, v102, v101, v100
	v_mul_f32_e32 v72, v72, v102
	v_div_scale_f32 v114, vcc, v108, v109, v108
	v_mul_f32_e32 v110, v114, v112
	v_fma_f32 v113, -v111, v110, v114
	v_fmac_f32_e32 v110, v113, v112
	v_fma_f32 v113, -v111, v110, v114
	v_div_fmas_f32 v110, v113, v112, v110
	v_div_fixup_f32 v110, v110, v109, v108
	v_mul_f32_e32 v73, v73, v110
	v_lshlrev_b32_e32 v100, 16, v47
	v_mul_f32_e32 v101, 0xbfb8aa3b, v100
	v_exp_f32_e32 v101, v101
	v_mul_f32_e32 v74, v74, v89
	v_add_f32_e32 v101, 1.0, v101
	v_mul_f32_e32 v74, v74, v10
	v_and_b32_e32 v108, 0xffff0000, v47
	v_mul_f32_e32 v109, 0xbfb8aa3b, v108
	v_exp_f32_e32 v109, v109
	v_mul_f32_e32 v75, v75, v89
	v_add_f32_e32 v109, 1.0, v109
	v_mul_f32_e32 v75, v75, v11
	v_div_scale_f32 v103, s[16:17], v101, v101, v100
	v_rcp_f32_e32 v104, v103
	s_nop 0
	v_fma_f32 v105, -v103, v104, 1.0
	v_fmac_f32_e32 v104, v105, v104
	v_div_scale_f32 v111, s[16:17], v109, v109, v108
	v_rcp_f32_e32 v112, v111
	s_nop 0
	v_fma_f32 v113, -v111, v112, 1.0
	v_fmac_f32_e32 v112, v113, v112
	v_div_scale_f32 v106, vcc, v100, v101, v100
	v_mul_f32_e32 v102, v106, v104
	v_fma_f32 v105, -v103, v102, v106
	v_fmac_f32_e32 v102, v105, v104
	v_fma_f32 v105, -v103, v102, v106
	v_div_fmas_f32 v102, v105, v104, v102
	v_div_fixup_f32 v102, v102, v101, v100
	v_mul_f32_e32 v74, v74, v102
	v_div_scale_f32 v114, vcc, v108, v109, v108
	v_mul_f32_e32 v110, v114, v112
	v_fma_f32 v113, -v111, v110, v114
	v_fmac_f32_e32 v110, v113, v112
	v_fma_f32 v113, -v111, v110, v114
	v_div_fmas_f32 v110, v113, v112, v110
	v_div_fixup_f32 v110, v110, v109, v108
	v_mul_f32_e32 v75, v75, v110
	v_cvt_pk_bf16_f32 v94, v72, v73
	v_cvt_pk_bf16_f32 v95, v74, v75
	global_store_dwordx2 v1, v[94:95], s[14:15] offset:512
	v_lshlrev_b32_e32 v100, 16, v48
	v_mul_f32_e32 v101, 0xbfb8aa3b, v100
	v_exp_f32_e32 v101, v101
	v_mul_f32_e32 v76, v76, v90
	v_add_f32_e32 v101, 1.0, v101
	v_mul_f32_e32 v76, v76, v12
	v_and_b32_e32 v108, 0xffff0000, v48
	v_mul_f32_e32 v109, 0xbfb8aa3b, v108
	v_exp_f32_e32 v109, v109
	v_mul_f32_e32 v77, v77, v90
	v_add_f32_e32 v109, 1.0, v109
	v_mul_f32_e32 v77, v77, v13
	v_div_scale_f32 v103, s[16:17], v101, v101, v100
	v_rcp_f32_e32 v104, v103
	s_nop 0
	v_fma_f32 v105, -v103, v104, 1.0
	v_fmac_f32_e32 v104, v105, v104
	v_div_scale_f32 v111, s[16:17], v109, v109, v108
	v_rcp_f32_e32 v112, v111
	s_nop 0
	v_fma_f32 v113, -v111, v112, 1.0
	v_fmac_f32_e32 v112, v113, v112
	v_div_scale_f32 v106, vcc, v100, v101, v100
	v_mul_f32_e32 v102, v106, v104
	v_fma_f32 v105, -v103, v102, v106
	v_fmac_f32_e32 v102, v105, v104
	v_fma_f32 v105, -v103, v102, v106
	v_div_fmas_f32 v102, v105, v104, v102
	v_div_fixup_f32 v102, v102, v101, v100
	v_mul_f32_e32 v76, v76, v102
	v_div_scale_f32 v114, vcc, v108, v109, v108
	v_mul_f32_e32 v110, v114, v112
	v_fma_f32 v113, -v111, v110, v114
	v_fmac_f32_e32 v110, v113, v112
	v_fma_f32 v113, -v111, v110, v114
	v_div_fmas_f32 v110, v113, v112, v110
	v_div_fixup_f32 v110, v110, v109, v108
	v_mul_f32_e32 v77, v77, v110
	v_lshlrev_b32_e32 v100, 16, v49
	v_mul_f32_e32 v101, 0xbfb8aa3b, v100
	v_exp_f32_e32 v101, v101
	v_mul_f32_e32 v78, v78, v90
	v_add_f32_e32 v101, 1.0, v101
	v_mul_f32_e32 v78, v78, v14
	v_and_b32_e32 v108, 0xffff0000, v49
	v_mul_f32_e32 v109, 0xbfb8aa3b, v108
	v_exp_f32_e32 v109, v109
	v_mul_f32_e32 v79, v79, v90
	v_add_f32_e32 v109, 1.0, v109
	v_mul_f32_e32 v79, v79, v15
	v_div_scale_f32 v103, s[16:17], v101, v101, v100
	v_rcp_f32_e32 v104, v103
	s_nop 0
	v_fma_f32 v105, -v103, v104, 1.0
	v_fmac_f32_e32 v104, v105, v104
	v_div_scale_f32 v111, s[16:17], v109, v109, v108
	v_rcp_f32_e32 v112, v111
	s_nop 0
	v_fma_f32 v113, -v111, v112, 1.0
	v_fmac_f32_e32 v112, v113, v112
	v_div_scale_f32 v106, vcc, v100, v101, v100
	v_mul_f32_e32 v102, v106, v104
	v_fma_f32 v105, -v103, v102, v106
	v_fmac_f32_e32 v102, v105, v104
	v_fma_f32 v105, -v103, v102, v106
	v_div_fmas_f32 v102, v105, v104, v102
	v_div_fixup_f32 v102, v102, v101, v100
	v_mul_f32_e32 v78, v78, v102
	v_div_scale_f32 v114, vcc, v108, v109, v108
	v_mul_f32_e32 v110, v114, v112
	v_fma_f32 v113, -v111, v110, v114
	v_fmac_f32_e32 v110, v113, v112
	v_fma_f32 v113, -v111, v110, v114
	v_div_fmas_f32 v110, v113, v112, v110
	v_div_fixup_f32 v110, v110, v109, v108
	v_mul_f32_e32 v79, v79, v110
	v_cvt_pk_bf16_f32 v96, v76, v77
	v_cvt_pk_bf16_f32 v97, v78, v79
	global_store_dwordx2 v1, v[96:97], s[14:15] offset:1024
	v_lshlrev_b32_e32 v100, 16, v50
	v_mul_f32_e32 v101, 0xbfb8aa3b, v100
	v_exp_f32_e32 v101, v101
	v_mul_f32_e32 v80, v80, v91
	v_add_f32_e32 v101, 1.0, v101
	v_mul_f32_e32 v80, v80, v16
	v_and_b32_e32 v108, 0xffff0000, v50
	v_mul_f32_e32 v109, 0xbfb8aa3b, v108
	v_exp_f32_e32 v109, v109
	v_mul_f32_e32 v81, v81, v91
	v_add_f32_e32 v109, 1.0, v109
	v_mul_f32_e32 v81, v81, v17
	v_div_scale_f32 v103, s[16:17], v101, v101, v100
	v_rcp_f32_e32 v104, v103
	s_nop 0
	v_fma_f32 v105, -v103, v104, 1.0
	v_fmac_f32_e32 v104, v105, v104
	v_div_scale_f32 v111, s[16:17], v109, v109, v108
	v_rcp_f32_e32 v112, v111
	s_nop 0
	v_fma_f32 v113, -v111, v112, 1.0
	v_fmac_f32_e32 v112, v113, v112
	v_div_scale_f32 v106, vcc, v100, v101, v100
	v_mul_f32_e32 v102, v106, v104
	v_fma_f32 v105, -v103, v102, v106
	v_fmac_f32_e32 v102, v105, v104
	v_fma_f32 v105, -v103, v102, v106
	v_div_fmas_f32 v102, v105, v104, v102
	v_div_fixup_f32 v102, v102, v101, v100
	v_mul_f32_e32 v80, v80, v102
	v_div_scale_f32 v114, vcc, v108, v109, v108
	v_mul_f32_e32 v110, v114, v112
	v_fma_f32 v113, -v111, v110, v114
	v_fmac_f32_e32 v110, v113, v112
	v_fma_f32 v113, -v111, v110, v114
	v_div_fmas_f32 v110, v113, v112, v110
	v_div_fixup_f32 v110, v110, v109, v108
	v_mul_f32_e32 v81, v81, v110
	v_lshlrev_b32_e32 v100, 16, v51
	v_mul_f32_e32 v101, 0xbfb8aa3b, v100
	v_exp_f32_e32 v101, v101
	v_mul_f32_e32 v82, v82, v91
	v_add_f32_e32 v101, 1.0, v101
	v_mul_f32_e32 v82, v82, v18
	v_and_b32_e32 v108, 0xffff0000, v51
	v_mul_f32_e32 v109, 0xbfb8aa3b, v108
	v_exp_f32_e32 v109, v109
	v_mul_f32_e32 v83, v83, v91
	v_add_f32_e32 v109, 1.0, v109
	v_mul_f32_e32 v83, v83, v19
	v_div_scale_f32 v103, s[16:17], v101, v101, v100
	v_rcp_f32_e32 v104, v103
	s_nop 0
	v_fma_f32 v105, -v103, v104, 1.0
	v_fmac_f32_e32 v104, v105, v104
	v_div_scale_f32 v111, s[16:17], v109, v109, v108
	v_rcp_f32_e32 v112, v111
	s_nop 0
	v_fma_f32 v113, -v111, v112, 1.0
	v_fmac_f32_e32 v112, v113, v112
	v_div_scale_f32 v106, vcc, v100, v101, v100
	v_mul_f32_e32 v102, v106, v104
	v_fma_f32 v105, -v103, v102, v106
	v_fmac_f32_e32 v102, v105, v104
	v_fma_f32 v105, -v103, v102, v106
	v_div_fmas_f32 v102, v105, v104, v102
	v_div_fixup_f32 v102, v102, v101, v100
	v_mul_f32_e32 v82, v82, v102
	v_div_scale_f32 v114, vcc, v108, v109, v108
	v_mul_f32_e32 v110, v114, v112
	v_fma_f32 v113, -v111, v110, v114
	v_fmac_f32_e32 v110, v113, v112
	v_fma_f32 v113, -v111, v110, v114
	v_div_fmas_f32 v110, v113, v112, v110
	v_div_fixup_f32 v110, v110, v109, v108
	v_mul_f32_e32 v83, v83, v110
	v_cvt_pk_bf16_f32 v98, v80, v81
	v_cvt_pk_bf16_f32 v99, v82, v83
	global_store_dwordx2 v1, v[98:99], s[14:15] offset:1536
	s_add_u32 s14, s14, 0x400000
	s_addc_u32 s15, s15, 0
	global_load_dwordx2 v[36:37], v1, s[6:7] offset:0
	global_load_dwordx2 v[38:39], v1, s[6:7] offset:512
	global_load_dwordx2 v[40:41], v1, s[6:7] offset:1024
	global_load_dwordx2 v[42:43], v1, s[6:7] offset:1536
	global_load_dwordx2 v[44:45], v1, s[12:13] offset:0
	global_load_dwordx2 v[46:47], v1, s[12:13] offset:512
	global_load_dwordx2 v[48:49], v1, s[12:13] offset:1024
	global_load_dwordx2 v[50:51], v1, s[12:13] offset:1536
	s_add_u32 s6, s6, 0x400000
	s_addc_u32 s7, s7, 0
	s_add_u32 s12, s12, 0xd00000
	s_addc_u32 s13, s13, 0
	s_waitcnt vmcnt(24)
	v_lshlrev_b32_e32 v68, 16, v52
	v_and_b32_e32 v69, 0xffff0000, v52
	v_lshlrev_b32_e32 v70, 16, v53
	v_and_b32_e32 v71, 0xffff0000, v53
	v_lshlrev_b32_e32 v72, 16, v54
	v_and_b32_e32 v73, 0xffff0000, v54
	v_lshlrev_b32_e32 v74, 16, v55
	v_and_b32_e32 v75, 0xffff0000, v55
	v_lshlrev_b32_e32 v76, 16, v56
	v_and_b32_e32 v77, 0xffff0000, v56
	v_lshlrev_b32_e32 v78, 16, v57
	v_and_b32_e32 v79, 0xffff0000, v57
	v_lshlrev_b32_e32 v80, 16, v58
	v_and_b32_e32 v81, 0xffff0000, v58
	v_lshlrev_b32_e32 v82, 16, v59
	v_and_b32_e32 v83, 0xffff0000, v59
	v_mul_f32_e32 v84, v68, v68
	v_mul_f32_e32 v85, v72, v72
	v_mul_f32_e32 v86, v76, v76
	v_mul_f32_e32 v87, v80, v80
	v_fmac_f32_e32 v84, v69, v69
	v_fmac_f32_e32 v85, v73, v73
	v_fmac_f32_e32 v86, v77, v77
	v_fmac_f32_e32 v87, v81, v81
	v_fmac_f32_e32 v84, v70, v70
	v_fmac_f32_e32 v85, v74, v74
	v_fmac_f32_e32 v86, v78, v78
	v_fmac_f32_e32 v87, v82, v82
	v_fmac_f32_e32 v84, v71, v71
	v_fmac_f32_e32 v85, v75, v75
	v_fmac_f32_e32 v86, v79, v79
	v_fmac_f32_e32 v87, v83, v83
	v_add_f32_dpp v84, v84, v84 quad_perm:[1,0,3,2] row_mask:0xf bank_mask:0xf
	v_add_f32_dpp v85, v85, v85 quad_perm:[1,0,3,2] row_mask:0xf bank_mask:0xf
	v_add_f32_dpp v86, v86, v86 quad_perm:[1,0,3,2] row_mask:0xf bank_mask:0xf
	v_add_f32_dpp v87, v87, v87 quad_perm:[1,0,3,2] row_mask:0xf bank_mask:0xf
	v_add_f32_dpp v84, v84, v84 quad_perm:[2,3,0,1] row_mask:0xf bank_mask:0xf
	v_add_f32_dpp v85, v85, v85 quad_perm:[2,3,0,1] row_mask:0xf bank_mask:0xf
	v_add_f32_dpp v86, v86, v86 quad_perm:[2,3,0,1] row_mask:0xf bank_mask:0xf
	v_add_f32_dpp v87, v87, v87 quad_perm:[2,3,0,1] row_mask:0xf bank_mask:0xf
	v_add_f32_dpp v84, v84, v84 row_half_mirror row_mask:0xf bank_mask:0xf
	v_add_f32_dpp v85, v85, v85 row_half_mirror row_mask:0xf bank_mask:0xf
	v_add_f32_dpp v86, v86, v86 row_half_mirror row_mask:0xf bank_mask:0xf
	v_add_f32_dpp v87, v87, v87 row_half_mirror row_mask:0xf bank_mask:0xf
	v_add_f32_dpp v84, v84, v84 row_mirror row_mask:0xf bank_mask:0xf
	v_add_f32_dpp v85, v85, v85 row_mirror row_mask:0xf bank_mask:0xf
	v_add_f32_dpp v86, v86, v86 row_mirror row_mask:0xf bank_mask:0xf
	v_add_f32_dpp v87, v87, v87 row_mirror row_mask:0xf bank_mask:0xf
	v_add_f32_dpp v84, v84, v84 row_bcast:15 row_mask:0xa bank_mask:0xf
	v_add_f32_dpp v85, v85, v85 row_bcast:15 row_mask:0xa bank_mask:0xf
	v_add_f32_dpp v86, v86, v86 row_bcast:15 row_mask:0xa bank_mask:0xf
	v_add_f32_dpp v87, v87, v87 row_bcast:15 row_mask:0xa bank_mask:0xf
	v_add_f32_dpp v84, v84, v84 row_bcast:31 row_mask:0xc bank_mask:0xf
	v_add_f32_dpp v85, v85, v85 row_bcast:31 row_mask:0xc bank_mask:0xf
	v_add_f32_dpp v86, v86, v86 row_bcast:31 row_mask:0xc bank_mask:0xf
	v_add_f32_dpp v87, v87, v87 row_bcast:31 row_mask:0xc bank_mask:0xf
	s_nop 0
	v_readlane_b32 s28, v84, 63
	v_readlane_b32 s29, v85, 63
	v_readlane_b32 s30, v86, 63
	v_readlane_b32 s31, v87, 63
	s_nop 1
	v_fma_f32 v88, s28, v2, v3
	v_fma_f32 v89, s29, v2, v3
	v_fma_f32 v90, s30, v2, v3
	v_fma_f32 v91, s31, v2, v3
	v_rsq_f32_e32 v88, v88
	v_rsq_f32_e32 v89, v89
	v_rsq_f32_e32 v90, v90
	v_rsq_f32_e32 v91, v91
	s_nop 0
	v_lshlrev_b32_e32 v100, 16, v60
	v_mul_f32_e32 v101, 0xbfb8aa3b, v100
	v_exp_f32_e32 v101, v101
	v_mul_f32_e32 v68, v68, v88
	v_add_f32_e32 v101, 1.0, v101
	v_mul_f32_e32 v68, v68, v4
	v_and_b32_e32 v108, 0xffff0000, v60
	v_mul_f32_e32 v109, 0xbfb8aa3b, v108
	v_exp_f32_e32 v109, v109
	v_mul_f32_e32 v69, v69, v88
	v_add_f32_e32 v109, 1.0, v109
	v_mul_f32_e32 v69, v69, v5
	v_div_scale_f32 v103, s[16:17], v101, v101, v100
	v_rcp_f32_e32 v104, v103
	s_nop 0
	v_fma_f32 v105, -v103, v104, 1.0
	v_fmac_f32_e32 v104, v105, v104
	v_div_scale_f32 v111, s[16:17], v109, v109, v108
	v_rcp_f32_e32 v112, v111
	s_nop 0
	v_fma_f32 v113, -v111, v112, 1.0
	v_fmac_f32_e32 v112, v113, v112
	v_div_scale_f32 v106, vcc, v100, v101, v100
	v_mul_f32_e32 v102, v106, v104
	v_fma_f32 v105, -v103, v102, v106
	v_fmac_f32_e32 v102, v105, v104
	v_fma_f32 v105, -v103, v102, v106
	v_div_fmas_f32 v102, v105, v104, v102
	v_div_fixup_f32 v102, v102, v101, v100
	v_mul_f32_e32 v68, v68, v102
	v_div_scale_f32 v114, vcc, v108, v109, v108
	v_mul_f32_e32 v110, v114, v112
	v_fma_f32 v113, -v111, v110, v114
	v_fmac_f32_e32 v110, v113, v112
	v_fma_f32 v113, -v111, v110, v114
	v_div_fmas_f32 v110, v113, v112, v110
	v_div_fixup_f32 v110, v110, v109, v108
	v_mul_f32_e32 v69, v69, v110
	v_lshlrev_b32_e32 v100, 16, v61
	v_mul_f32_e32 v101, 0xbfb8aa3b, v100
	v_exp_f32_e32 v101, v101
	v_mul_f32_e32 v70, v70, v88
	v_add_f32_e32 v101, 1.0, v101
	v_mul_f32_e32 v70, v70, v6
	v_and_b32_e32 v108, 0xffff0000, v61
	v_mul_f32_e32 v109, 0xbfb8aa3b, v108
	v_exp_f32_e32 v109, v109
	v_mul_f32_e32 v71, v71, v88
	v_add_f32_e32 v109, 1.0, v109
	v_mul_f32_e32 v71, v71, v7
	v_div_scale_f32 v103, s[16:17], v101, v101, v100
	v_rcp_f32_e32 v104, v103
	s_nop 0
	v_fma_f32 v105, -v103, v104, 1.0
	v_fmac_f32_e32 v104, v105, v104
	v_div_scale_f32 v111, s[16:17], v109, v109, v108
	v_rcp_f32_e32 v112, v111
	s_nop 0
	v_fma_f32 v113, -v111, v112, 1.0
	v_fmac_f32_e32 v112, v113, v112
	v_div_scale_f32 v106, vcc, v100, v101, v100
	v_mul_f32_e32 v102, v106, v104
	v_fma_f32 v105, -v103, v102, v106
	v_fmac_f32_e32 v102, v105, v104
	v_fma_f32 v105, -v103, v102, v106
	v_div_fmas_f32 v102, v105, v104, v102
	v_div_fixup_f32 v102, v102, v101, v100
	v_mul_f32_e32 v70, v70, v102
	v_div_scale_f32 v114, vcc, v108, v109, v108
	v_mul_f32_e32 v110, v114, v112
	v_fma_f32 v113, -v111, v110, v114
	v_fmac_f32_e32 v110, v113, v112
	v_fma_f32 v113, -v111, v110, v114
	v_div_fmas_f32 v110, v113, v112, v110
	v_div_fixup_f32 v110, v110, v109, v108
	v_mul_f32_e32 v71, v71, v110
	v_cvt_pk_bf16_f32 v92, v68, v69
	v_cvt_pk_bf16_f32 v93, v70, v71
	global_store_dwordx2 v1, v[92:93], s[14:15] offset:0
	v_lshlrev_b32_e32 v100, 16, v62
	v_mul_f32_e32 v101, 0xbfb8aa3b, v100
	v_exp_f32_e32 v101, v101
	v_mul_f32_e32 v72, v72, v89
	v_add_f32_e32 v101, 1.0, v101
	v_mul_f32_e32 v72, v72, v8
	v_and_b32_e32 v108, 0xffff0000, v62
	v_mul_f32_e32 v109, 0xbfb8aa3b, v108
	v_exp_f32_e32 v109, v109
	v_mul_f32_e32 v73, v73, v89
	v_add_f32_e32 v109, 1.0, v109
	v_mul_f32_e32 v73, v73, v9
	v_div_scale_f32 v103, s[16:17], v101, v101, v100
	v_rcp_f32_e32 v104, v103
	s_nop 0
	v_fma_f32 v105, -v103, v104, 1.0
	v_fmac_f32_e32 v104, v105, v104
	v_div_scale_f32 v111, s[16:17], v109, v109, v108
	v_rcp_f32_e32 v112, v111
	s_nop 0
	v_fma_f32 v113, -v111, v112, 1.0
	v_fmac_f32_e32 v112, v113, v112
	v_div_scale_f32 v106, vcc, v100, v101, v100
	v_mul_f32_e32 v102, v106, v104
	v_fma_f32 v105, -v103, v102, v106
	v_fmac_f32_e32 v102, v105, v104
	v_fma_f32 v105, -v103, v102, v106
	v_div_fmas_f32 v102, v105, v104, v102
	v_div_fixup_f32 v102, v102, v101, v100
	v_mul_f32_e32 v72, v72, v102
	v_div_scale_f32 v114, vcc, v108, v109, v108
	v_mul_f32_e32 v110, v114, v112
	v_fma_f32 v113, -v111, v110, v114
	v_fmac_f32_e32 v110, v113, v112
	v_fma_f32 v113, -v111, v110, v114
	v_div_fmas_f32 v110, v113, v112, v110
	v_div_fixup_f32 v110, v110, v109, v108
	v_mul_f32_e32 v73, v73, v110
	v_lshlrev_b32_e32 v100, 16, v63
	v_mul_f32_e32 v101, 0xbfb8aa3b, v100
	v_exp_f32_e32 v101, v101
	v_mul_f32_e32 v74, v74, v89
	v_add_f32_e32 v101, 1.0, v101
	v_mul_f32_e32 v74, v74, v10
	v_and_b32_e32 v108, 0xffff0000, v63
	v_mul_f32_e32 v109, 0xbfb8aa3b, v108
	v_exp_f32_e32 v109, v109
	v_mul_f32_e32 v75, v75, v89
	v_add_f32_e32 v109, 1.0, v109
	v_mul_f32_e32 v75, v75, v11
	v_div_scale_f32 v103, s[16:17], v101, v101, v100
	v_rcp_f32_e32 v104, v103
	s_nop 0
	v_fma_f32 v105, -v103, v104, 1.0
	v_fmac_f32_e32 v104, v105, v104
	v_div_scale_f32 v111, s[16:17], v109, v109, v108
	v_rcp_f32_e32 v112, v111
	s_nop 0
	v_fma_f32 v113, -v111, v112, 1.0
	v_fmac_f32_e32 v112, v113, v112
	v_div_scale_f32 v106, vcc, v100, v101, v100
	v_mul_f32_e32 v102, v106, v104
	v_fma_f32 v105, -v103, v102, v106
	v_fmac_f32_e32 v102, v105, v104
	v_fma_f32 v105, -v103, v102, v106
	v_div_fmas_f32 v102, v105, v104, v102
	v_div_fixup_f32 v102, v102, v101, v100
	v_mul_f32_e32 v74, v74, v102
	v_div_scale_f32 v114, vcc, v108, v109, v108
	v_mul_f32_e32 v110, v114, v112
	v_fma_f32 v113, -v111, v110, v114
	v_fmac_f32_e32 v110, v113, v112
	v_fma_f32 v113, -v111, v110, v114
	v_div_fmas_f32 v110, v113, v112, v110
	v_div_fixup_f32 v110, v110, v109, v108
	v_mul_f32_e32 v75, v75, v110
	v_cvt_pk_bf16_f32 v94, v72, v73
	v_cvt_pk_bf16_f32 v95, v74, v75
	global_store_dwordx2 v1, v[94:95], s[14:15] offset:512
	v_lshlrev_b32_e32 v100, 16, v64
	v_mul_f32_e32 v101, 0xbfb8aa3b, v100
	v_exp_f32_e32 v101, v101
	v_mul_f32_e32 v76, v76, v90
	v_add_f32_e32 v101, 1.0, v101
	v_mul_f32_e32 v76, v76, v12
	v_and_b32_e32 v108, 0xffff0000, v64
	v_mul_f32_e32 v109, 0xbfb8aa3b, v108
	v_exp_f32_e32 v109, v109
	v_mul_f32_e32 v77, v77, v90
	v_add_f32_e32 v109, 1.0, v109
	v_mul_f32_e32 v77, v77, v13
	v_div_scale_f32 v103, s[16:17], v101, v101, v100
	v_rcp_f32_e32 v104, v103
	s_nop 0
	v_fma_f32 v105, -v103, v104, 1.0
	v_fmac_f32_e32 v104, v105, v104
	v_div_scale_f32 v111, s[16:17], v109, v109, v108
	v_rcp_f32_e32 v112, v111
	s_nop 0
	v_fma_f32 v113, -v111, v112, 1.0
	v_fmac_f32_e32 v112, v113, v112
	v_div_scale_f32 v106, vcc, v100, v101, v100
	v_mul_f32_e32 v102, v106, v104
	v_fma_f32 v105, -v103, v102, v106
	v_fmac_f32_e32 v102, v105, v104
	v_fma_f32 v105, -v103, v102, v106
	v_div_fmas_f32 v102, v105, v104, v102
	v_div_fixup_f32 v102, v102, v101, v100
	v_mul_f32_e32 v76, v76, v102
	v_div_scale_f32 v114, vcc, v108, v109, v108
	v_mul_f32_e32 v110, v114, v112
	v_fma_f32 v113, -v111, v110, v114
	v_fmac_f32_e32 v110, v113, v112
	v_fma_f32 v113, -v111, v110, v114
	v_div_fmas_f32 v110, v113, v112, v110
	v_div_fixup_f32 v110, v110, v109, v108
	v_mul_f32_e32 v77, v77, v110
	v_lshlrev_b32_e32 v100, 16, v65
	v_mul_f32_e32 v101, 0xbfb8aa3b, v100
	v_exp_f32_e32 v101, v101
	v_mul_f32_e32 v78, v78, v90
	v_add_f32_e32 v101, 1.0, v101
	v_mul_f32_e32 v78, v78, v14
	v_and_b32_e32 v108, 0xffff0000, v65
	v_mul_f32_e32 v109, 0xbfb8aa3b, v108
	v_exp_f32_e32 v109, v109
	v_mul_f32_e32 v79, v79, v90
	v_add_f32_e32 v109, 1.0, v109
	v_mul_f32_e32 v79, v79, v15
	v_div_scale_f32 v103, s[16:17], v101, v101, v100
	v_rcp_f32_e32 v104, v103
	s_nop 0
	v_fma_f32 v105, -v103, v104, 1.0
	v_fmac_f32_e32 v104, v105, v104
	v_div_scale_f32 v111, s[16:17], v109, v109, v108
	v_rcp_f32_e32 v112, v111
	s_nop 0
	v_fma_f32 v113, -v111, v112, 1.0
	v_fmac_f32_e32 v112, v113, v112
	v_div_scale_f32 v106, vcc, v100, v101, v100
	v_mul_f32_e32 v102, v106, v104
	v_fma_f32 v105, -v103, v102, v106
	v_fmac_f32_e32 v102, v105, v104
	v_fma_f32 v105, -v103, v102, v106
	v_div_fmas_f32 v102, v105, v104, v102
	v_div_fixup_f32 v102, v102, v101, v100
	v_mul_f32_e32 v78, v78, v102
	v_div_scale_f32 v114, vcc, v108, v109, v108
	v_mul_f32_e32 v110, v114, v112
	v_fma_f32 v113, -v111, v110, v114
	v_fmac_f32_e32 v110, v113, v112
	v_fma_f32 v113, -v111, v110, v114
	v_div_fmas_f32 v110, v113, v112, v110
	v_div_fixup_f32 v110, v110, v109, v108
	v_mul_f32_e32 v79, v79, v110
	v_cvt_pk_bf16_f32 v96, v76, v77
	v_cvt_pk_bf16_f32 v97, v78, v79
	global_store_dwordx2 v1, v[96:97], s[14:15] offset:1024
	v_lshlrev_b32_e32 v100, 16, v66
	v_mul_f32_e32 v101, 0xbfb8aa3b, v100
	v_exp_f32_e32 v101, v101
	v_mul_f32_e32 v80, v80, v91
	v_add_f32_e32 v101, 1.0, v101
	v_mul_f32_e32 v80, v80, v16
	v_and_b32_e32 v108, 0xffff0000, v66
	v_mul_f32_e32 v109, 0xbfb8aa3b, v108
	v_exp_f32_e32 v109, v109
	v_mul_f32_e32 v81, v81, v91
	v_add_f32_e32 v109, 1.0, v109
	v_mul_f32_e32 v81, v81, v17
	v_div_scale_f32 v103, s[16:17], v101, v101, v100
	v_rcp_f32_e32 v104, v103
	s_nop 0
	v_fma_f32 v105, -v103, v104, 1.0
	v_fmac_f32_e32 v104, v105, v104
	v_div_scale_f32 v111, s[16:17], v109, v109, v108
	v_rcp_f32_e32 v112, v111
	s_nop 0
	v_fma_f32 v113, -v111, v112, 1.0
	v_fmac_f32_e32 v112, v113, v112
	v_div_scale_f32 v106, vcc, v100, v101, v100
	v_mul_f32_e32 v102, v106, v104
	v_fma_f32 v105, -v103, v102, v106
	v_fmac_f32_e32 v102, v105, v104
	v_fma_f32 v105, -v103, v102, v106
	v_div_fmas_f32 v102, v105, v104, v102
	v_div_fixup_f32 v102, v102, v101, v100
	v_mul_f32_e32 v80, v80, v102
	v_div_scale_f32 v114, vcc, v108, v109, v108
	v_mul_f32_e32 v110, v114, v112
	v_fma_f32 v113, -v111, v110, v114
	v_fmac_f32_e32 v110, v113, v112
	v_fma_f32 v113, -v111, v110, v114
	v_div_fmas_f32 v110, v113, v112, v110
	v_div_fixup_f32 v110, v110, v109, v108
	v_mul_f32_e32 v81, v81, v110
	v_lshlrev_b32_e32 v100, 16, v67
	v_mul_f32_e32 v101, 0xbfb8aa3b, v100
	v_exp_f32_e32 v101, v101
	v_mul_f32_e32 v82, v82, v91
	v_add_f32_e32 v101, 1.0, v101
	v_mul_f32_e32 v82, v82, v18
	v_and_b32_e32 v108, 0xffff0000, v67
	v_mul_f32_e32 v109, 0xbfb8aa3b, v108
	v_exp_f32_e32 v109, v109
	v_mul_f32_e32 v83, v83, v91
	v_add_f32_e32 v109, 1.0, v109
	v_mul_f32_e32 v83, v83, v19
	v_div_scale_f32 v103, s[16:17], v101, v101, v100
	v_rcp_f32_e32 v104, v103
	s_nop 0
	v_fma_f32 v105, -v103, v104, 1.0
	v_fmac_f32_e32 v104, v105, v104
	v_div_scale_f32 v111, s[16:17], v109, v109, v108
	v_rcp_f32_e32 v112, v111
	s_nop 0
	v_fma_f32 v113, -v111, v112, 1.0
	v_fmac_f32_e32 v112, v113, v112
	v_div_scale_f32 v106, vcc, v100, v101, v100
	v_mul_f32_e32 v102, v106, v104
	v_fma_f32 v105, -v103, v102, v106
	v_fmac_f32_e32 v102, v105, v104
	v_fma_f32 v105, -v103, v102, v106
	v_div_fmas_f32 v102, v105, v104, v102
	v_div_fixup_f32 v102, v102, v101, v100
	v_mul_f32_e32 v82, v82, v102
	v_div_scale_f32 v114, vcc, v108, v109, v108
	v_mul_f32_e32 v110, v114, v112
	v_fma_f32 v113, -v111, v110, v114
	v_fmac_f32_e32 v110, v113, v112
	v_fma_f32 v113, -v111, v110, v114
	v_div_fmas_f32 v110, v113, v112, v110
	v_div_fixup_f32 v110, v110, v109, v108
	v_mul_f32_e32 v83, v83, v110
	v_cvt_pk_bf16_f32 v98, v80, v81
	v_cvt_pk_bf16_f32 v99, v82, v83
	global_store_dwordx2 v1, v[98:99], s[14:15] offset:1536
	s_add_u32 s14, s14, 0x400000
	s_addc_u32 s15, s15, 0
	s_cmp_eq_u32 s22, 0
	s_cbranch_scc0 .Lgate_r8ok
	s_sub_u32 s6, s6, 0x400000
	s_subb_u32 s7, s7, 0
	s_sub_u32 s12, s12, 0xd00000
	s_subb_u32 s13, s13, 0
.Lgate_r8ok:
	global_load_dwordx2 v[52:53], v1, s[6:7] offset:0
	global_load_dwordx2 v[54:55], v1, s[6:7] offset:512
	global_load_dwordx2 v[56:57], v1, s[6:7] offset:1024
	global_load_dwordx2 v[58:59], v1, s[6:7] offset:1536
	global_load_dwordx2 v[60:61], v1, s[12:13] offset:0
	global_load_dwordx2 v[62:63], v1, s[12:13] offset:512
	global_load_dwordx2 v[64:65], v1, s[12:13] offset:1024
	global_load_dwordx2 v[66:67], v1, s[12:13] offset:1536
	s_add_u32 s6, s6, 0x400000
	s_addc_u32 s7, s7, 0
	s_add_u32 s12, s12, 0xd00000
	s_addc_u32 s13, s13, 0
	s_waitcnt vmcnt(24)
	v_lshlrev_b32_e32 v68, 16, v20
	v_and_b32_e32 v69, 0xffff0000, v20
	v_lshlrev_b32_e32 v70, 16, v21
	v_and_b32_e32 v71, 0xffff0000, v21
	v_lshlrev_b32_e32 v72, 16, v22
	v_and_b32_e32 v73, 0xffff0000, v22
	v_lshlrev_b32_e32 v74, 16, v23
	v_and_b32_e32 v75, 0xffff0000, v23
	v_lshlrev_b32_e32 v76, 16, v24
	v_and_b32_e32 v77, 0xffff0000, v24
	v_lshlrev_b32_e32 v78, 16, v25
	v_and_b32_e32 v79, 0xffff0000, v25
	v_lshlrev_b32_e32 v80, 16, v26
	v_and_b32_e32 v81, 0xffff0000, v26
	v_lshlrev_b32_e32 v82, 16, v27
	v_and_b32_e32 v83, 0xffff0000, v27
	v_mul_f32_e32 v84, v68, v68
	v_mul_f32_e32 v85, v72, v72
	v_mul_f32_e32 v86, v76, v76
	v_mul_f32_e32 v87, v80, v80
	v_fmac_f32_e32 v84, v69, v69
	v_fmac_f32_e32 v85, v73, v73
	v_fmac_f32_e32 v86, v77, v77
	v_fmac_f32_e32 v87, v81, v81
	v_fmac_f32_e32 v84, v70, v70
	v_fmac_f32_e32 v85, v74, v74
	v_fmac_f32_e32 v86, v78, v78
	v_fmac_f32_e32 v87, v82, v82
	v_fmac_f32_e32 v84, v71, v71
	v_fmac_f32_e32 v85, v75, v75
	v_fmac_f32_e32 v86, v79, v79
	v_fmac_f32_e32 v87, v83, v83
	v_add_f32_dpp v84, v84, v84 quad_perm:[1,0,3,2] row_mask:0xf bank_mask:0xf
	v_add_f32_dpp v85, v85, v85 quad_perm:[1,0,3,2] row_mask:0xf bank_mask:0xf
	v_add_f32_dpp v86, v86, v86 quad_perm:[1,0,3,2] row_mask:0xf bank_mask:0xf
	v_add_f32_dpp v87, v87, v87 quad_perm:[1,0,3,2] row_mask:0xf bank_mask:0xf
	v_add_f32_dpp v84, v84, v84 quad_perm:[2,3,0,1] row_mask:0xf bank_mask:0xf
	v_add_f32_dpp v85, v85, v85 quad_perm:[2,3,0,1] row_mask:0xf bank_mask:0xf
	v_add_f32_dpp v86, v86, v86 quad_perm:[2,3,0,1] row_mask:0xf bank_mask:0xf
	v_add_f32_dpp v87, v87, v87 quad_perm:[2,3,0,1] row_mask:0xf bank_mask:0xf
	v_add_f32_dpp v84, v84, v84 row_half_mirror row_mask:0xf bank_mask:0xf
	v_add_f32_dpp v85, v85, v85 row_half_mirror row_mask:0xf bank_mask:0xf
	v_add_f32_dpp v86, v86, v86 row_half_mirror row_mask:0xf bank_mask:0xf
	v_add_f32_dpp v87, v87, v87 row_half_mirror row_mask:0xf bank_mask:0xf
	v_add_f32_dpp v84, v84, v84 row_mirror row_mask:0xf bank_mask:0xf
	v_add_f32_dpp v85, v85, v85 row_mirror row_mask:0xf bank_mask:0xf
	v_add_f32_dpp v86, v86, v86 row_mirror row_mask:0xf bank_mask:0xf
	v_add_f32_dpp v87, v87, v87 row_mirror row_mask:0xf bank_mask:0xf
	v_add_f32_dpp v84, v84, v84 row_bcast:15 row_mask:0xa bank_mask:0xf
	v_add_f32_dpp v85, v85, v85 row_bcast:15 row_mask:0xa bank_mask:0xf
	v_add_f32_dpp v86, v86, v86 row_bcast:15 row_mask:0xa bank_mask:0xf
	v_add_f32_dpp v87, v87, v87 row_bcast:15 row_mask:0xa bank_mask:0xf
	v_add_f32_dpp v84, v84, v84 row_bcast:31 row_mask:0xc bank_mask:0xf
	v_add_f32_dpp v85, v85, v85 row_bcast:31 row_mask:0xc bank_mask:0xf
	v_add_f32_dpp v86, v86, v86 row_bcast:31 row_mask:0xc bank_mask:0xf
	v_add_f32_dpp v87, v87, v87 row_bcast:31 row_mask:0xc bank_mask:0xf
	s_nop 0
	v_readlane_b32 s28, v84, 63
	v_readlane_b32 s29, v85, 63
	v_readlane_b32 s30, v86, 63
	v_readlane_b32 s31, v87, 63
	s_nop 1
	v_fma_f32 v88, s28, v2, v3
	v_fma_f32 v89, s29, v2, v3
	v_fma_f32 v90, s30, v2, v3
	v_fma_f32 v91, s31, v2, v3
	v_rsq_f32_e32 v88, v88
	v_rsq_f32_e32 v89, v89
	v_rsq_f32_e32 v90, v90
	v_rsq_f32_e32 v91, v91
	s_nop 0
	v_lshlrev_b32_e32 v100, 16, v28
	v_mul_f32_e32 v101, 0xbfb8aa3b, v100
	v_exp_f32_e32 v101, v101
	v_mul_f32_e32 v68, v68, v88
	v_add_f32_e32 v101, 1.0, v101
	v_mul_f32_e32 v68, v68, v4
	v_and_b32_e32 v108, 0xffff0000, v28
	v_mul_f32_e32 v109, 0xbfb8aa3b, v108
	v_exp_f32_e32 v109, v109
	v_mul_f32_e32 v69, v69, v88
	v_add_f32_e32 v109, 1.0, v109
	v_mul_f32_e32 v69, v69, v5
	v_div_scale_f32 v103, s[16:17], v101, v101, v100
	v_rcp_f32_e32 v104, v103
	s_nop 0
	v_fma_f32 v105, -v103, v104, 1.0
	v_fmac_f32_e32 v104, v105, v104
	v_div_scale_f32 v111, s[16:17], v109, v109, v108
	v_rcp_f32_e32 v112, v111
	s_nop 0
	v_fma_f32 v113, -v111, v112, 1.0
	v_fmac_f32_e32 v112, v113, v112
	v_div_scale_f32 v106, vcc, v100, v101, v100
	v_mul_f32_e32 v102, v106, v104
	v_fma_f32 v105, -v103, v102, v106
	v_fmac_f32_e32 v102, v105, v104
	v_fma_f32 v105, -v103, v102, v106
	v_div_fmas_f32 v102, v105, v104, v102
	v_div_fixup_f32 v102, v102, v101, v100
	v_mul_f32_e32 v68, v68, v102
	v_div_scale_f32 v114, vcc, v108, v109, v108
	v_mul_f32_e32 v110, v114, v112
	v_fma_f32 v113, -v111, v110, v114
	v_fmac_f32_e32 v110, v113, v112
	v_fma_f32 v113, -v111, v110, v114
	v_div_fmas_f32 v110, v113, v112, v110
	v_div_fixup_f32 v110, v110, v109, v108
	v_mul_f32_e32 v69, v69, v110
	v_lshlrev_b32_e32 v100, 16, v29
	v_mul_f32_e32 v101, 0xbfb8aa3b, v100
	v_exp_f32_e32 v101, v101
	v_mul_f32_e32 v70, v70, v88
	v_add_f32_e32 v101, 1.0, v101
	v_mul_f32_e32 v70, v70, v6
	v_and_b32_e32 v108, 0xffff0000, v29
	v_mul_f32_e32 v109, 0xbfb8aa3b, v108
	v_exp_f32_e32 v109, v109
	v_mul_f32_e32 v71, v71, v88
	v_add_f32_e32 v109, 1.0, v109
	v_mul_f32_e32 v71, v71, v7
	v_div_scale_f32 v103, s[16:17], v101, v101, v100
	v_rcp_f32_e32 v104, v103
	s_nop 0
	v_fma_f32 v105, -v103, v104, 1.0
	v_fmac_f32_e32 v104, v105, v104
	v_div_scale_f32 v111, s[16:17], v109, v109, v108
	v_rcp_f32_e32 v112, v111
	s_nop 0
	v_fma_f32 v113, -v111, v112, 1.0
	v_fmac_f32_e32 v112, v113, v112
	v_div_scale_f32 v106, vcc, v100, v101, v100
	v_mul_f32_e32 v102, v106, v104
	v_fma_f32 v105, -v103, v102, v106
	v_fmac_f32_e32 v102, v105, v104
	v_fma_f32 v105, -v103, v102, v106
	v_div_fmas_f32 v102, v105, v104, v102
	v_div_fixup_f32 v102, v102, v101, v100
	v_mul_f32_e32 v70, v70, v102
	v_div_scale_f32 v114, vcc, v108, v109, v108
	v_mul_f32_e32 v110, v114, v112
	v_fma_f32 v113, -v111, v110, v114
	v_fmac_f32_e32 v110, v113, v112
	v_fma_f32 v113, -v111, v110, v114
	v_div_fmas_f32 v110, v113, v112, v110
	v_div_fixup_f32 v110, v110, v109, v108
	v_mul_f32_e32 v71, v71, v110
	v_cvt_pk_bf16_f32 v92, v68, v69
	v_cvt_pk_bf16_f32 v93, v70, v71
	global_store_dwordx2 v1, v[92:93], s[14:15] offset:0
	v_lshlrev_b32_e32 v100, 16, v30
	v_mul_f32_e32 v101, 0xbfb8aa3b, v100
	v_exp_f32_e32 v101, v101
	v_mul_f32_e32 v72, v72, v89
	v_add_f32_e32 v101, 1.0, v101
	v_mul_f32_e32 v72, v72, v8
	v_and_b32_e32 v108, 0xffff0000, v30
	v_mul_f32_e32 v109, 0xbfb8aa3b, v108
	v_exp_f32_e32 v109, v109
	v_mul_f32_e32 v73, v73, v89
	v_add_f32_e32 v109, 1.0, v109
	v_mul_f32_e32 v73, v73, v9
	v_div_scale_f32 v103, s[16:17], v101, v101, v100
	v_rcp_f32_e32 v104, v103
	s_nop 0
	v_fma_f32 v105, -v103, v104, 1.0
	v_fmac_f32_e32 v104, v105, v104
	v_div_scale_f32 v111, s[16:17], v109, v109, v108
	v_rcp_f32_e32 v112, v111
	s_nop 0
	v_fma_f32 v113, -v111, v112, 1.0
	v_fmac_f32_e32 v112, v113, v112
	v_div_scale_f32 v106, vcc, v100, v101, v100
	v_mul_f32_e32 v102, v106, v104
	v_fma_f32 v105, -v103, v102, v106
	v_fmac_f32_e32 v102, v105, v104
	v_fma_f32 v105, -v103, v102, v106
	v_div_fmas_f32 v102, v105, v104, v102
	v_div_fixup_f32 v102, v102, v101, v100
	v_mul_f32_e32 v72, v72, v102
	v_div_scale_f32 v114, vcc, v108, v109, v108
	v_mul_f32_e32 v110, v114, v112
	v_fma_f32 v113, -v111, v110, v114
	v_fmac_f32_e32 v110, v113, v112
	v_fma_f32 v113, -v111, v110, v114
	v_div_fmas_f32 v110, v113, v112, v110
	v_div_fixup_f32 v110, v110, v109, v108
	v_mul_f32_e32 v73, v73, v110
	v_lshlrev_b32_e32 v100, 16, v31
	v_mul_f32_e32 v101, 0xbfb8aa3b, v100
	v_exp_f32_e32 v101, v101
	v_mul_f32_e32 v74, v74, v89
	v_add_f32_e32 v101, 1.0, v101
	v_mul_f32_e32 v74, v74, v10
	v_and_b32_e32 v108, 0xffff0000, v31
	v_mul_f32_e32 v109, 0xbfb8aa3b, v108
	v_exp_f32_e32 v109, v109
	v_mul_f32_e32 v75, v75, v89
	v_add_f32_e32 v109, 1.0, v109
	v_mul_f32_e32 v75, v75, v11
	v_div_scale_f32 v103, s[16:17], v101, v101, v100
	v_rcp_f32_e32 v104, v103
	s_nop 0
	v_fma_f32 v105, -v103, v104, 1.0
	v_fmac_f32_e32 v104, v105, v104
	v_div_scale_f32 v111, s[16:17], v109, v109, v108
	v_rcp_f32_e32 v112, v111
	s_nop 0
	v_fma_f32 v113, -v111, v112, 1.0
	v_fmac_f32_e32 v112, v113, v112
	v_div_scale_f32 v106, vcc, v100, v101, v100
	v_mul_f32_e32 v102, v106, v104
	v_fma_f32 v105, -v103, v102, v106
	v_fmac_f32_e32 v102, v105, v104
	v_fma_f32 v105, -v103, v102, v106
	v_div_fmas_f32 v102, v105, v104, v102
	v_div_fixup_f32 v102, v102, v101, v100
	v_mul_f32_e32 v74, v74, v102
	v_div_scale_f32 v114, vcc, v108, v109, v108
	v_mul_f32_e32 v110, v114, v112
	v_fma_f32 v113, -v111, v110, v114
	v_fmac_f32_e32 v110, v113, v112
	v_fma_f32 v113, -v111, v110, v114
	v_div_fmas_f32 v110, v113, v112, v110
	v_div_fixup_f32 v110, v110, v109, v108
	v_mul_f32_e32 v75, v75, v110
	v_cvt_pk_bf16_f32 v94, v72, v73
	v_cvt_pk_bf16_f32 v95, v74, v75
	global_store_dwordx2 v1, v[94:95], s[14:15] offset:512
	v_lshlrev_b32_e32 v100, 16, v32
	v_mul_f32_e32 v101, 0xbfb8aa3b, v100
	v_exp_f32_e32 v101, v101
	v_mul_f32_e32 v76, v76, v90
	v_add_f32_e32 v101, 1.0, v101
	v_mul_f32_e32 v76, v76, v12
	v_and_b32_e32 v108, 0xffff0000, v32
	v_mul_f32_e32 v109, 0xbfb8aa3b, v108
	v_exp_f32_e32 v109, v109
	v_mul_f32_e32 v77, v77, v90
	v_add_f32_e32 v109, 1.0, v109
	v_mul_f32_e32 v77, v77, v13
	v_div_scale_f32 v103, s[16:17], v101, v101, v100
	v_rcp_f32_e32 v104, v103
	s_nop 0
	v_fma_f32 v105, -v103, v104, 1.0
	v_fmac_f32_e32 v104, v105, v104
	v_div_scale_f32 v111, s[16:17], v109, v109, v108
	v_rcp_f32_e32 v112, v111
	s_nop 0
	v_fma_f32 v113, -v111, v112, 1.0
	v_fmac_f32_e32 v112, v113, v112
	v_div_scale_f32 v106, vcc, v100, v101, v100
	v_mul_f32_e32 v102, v106, v104
	v_fma_f32 v105, -v103, v102, v106
	v_fmac_f32_e32 v102, v105, v104
	v_fma_f32 v105, -v103, v102, v106
	v_div_fmas_f32 v102, v105, v104, v102
	v_div_fixup_f32 v102, v102, v101, v100
	v_mul_f32_e32 v76, v76, v102
	v_div_scale_f32 v114, vcc, v108, v109, v108
	v_mul_f32_e32 v110, v114, v112
	v_fma_f32 v113, -v111, v110, v114
	v_fmac_f32_e32 v110, v113, v112
	v_fma_f32 v113, -v111, v110, v114
	v_div_fmas_f32 v110, v113, v112, v110
	v_div_fixup_f32 v110, v110, v109, v108
	v_mul_f32_e32 v77, v77, v110
	v_lshlrev_b32_e32 v100, 16, v33
	v_mul_f32_e32 v101, 0xbfb8aa3b, v100
	v_exp_f32_e32 v101, v101
	v_mul_f32_e32 v78, v78, v90
	v_add_f32_e32 v101, 1.0, v101
	v_mul_f32_e32 v78, v78, v14
	v_and_b32_e32 v108, 0xffff0000, v33
	v_mul_f32_e32 v109, 0xbfb8aa3b, v108
	v_exp_f32_e32 v109, v109
	v_mul_f32_e32 v79, v79, v90
	v_add_f32_e32 v109, 1.0, v109
	v_mul_f32_e32 v79, v79, v15
	v_div_scale_f32 v103, s[16:17], v101, v101, v100
	v_rcp_f32_e32 v104, v103
	s_nop 0
	v_fma_f32 v105, -v103, v104, 1.0
	v_fmac_f32_e32 v104, v105, v104
	v_div_scale_f32 v111, s[16:17], v109, v109, v108
	v_rcp_f32_e32 v112, v111
	s_nop 0
	v_fma_f32 v113, -v111, v112, 1.0
	v_fmac_f32_e32 v112, v113, v112
	v_div_scale_f32 v106, vcc, v100, v101, v100
	v_mul_f32_e32 v102, v106, v104
	v_fma_f32 v105, -v103, v102, v106
	v_fmac_f32_e32 v102, v105, v104
	v_fma_f32 v105, -v103, v102, v106
	v_div_fmas_f32 v102, v105, v104, v102
	v_div_fixup_f32 v102, v102, v101, v100
	v_mul_f32_e32 v78, v78, v102
	v_div_scale_f32 v114, vcc, v108, v109, v108
	v_mul_f32_e32 v110, v114, v112
	v_fma_f32 v113, -v111, v110, v114
	v_fmac_f32_e32 v110, v113, v112
	v_fma_f32 v113, -v111, v110, v114
	v_div_fmas_f32 v110, v113, v112, v110
	v_div_fixup_f32 v110, v110, v109, v108
	v_mul_f32_e32 v79, v79, v110
	v_cvt_pk_bf16_f32 v96, v76, v77
	v_cvt_pk_bf16_f32 v97, v78, v79
	global_store_dwordx2 v1, v[96:97], s[14:15] offset:1024
	v_lshlrev_b32_e32 v100, 16, v34
	v_mul_f32_e32 v101, 0xbfb8aa3b, v100
	v_exp_f32_e32 v101, v101
	v_mul_f32_e32 v80, v80, v91
	v_add_f32_e32 v101, 1.0, v101
	v_mul_f32_e32 v80, v80, v16
	v_and_b32_e32 v108, 0xffff0000, v34
	v_mul_f32_e32 v109, 0xbfb8aa3b, v108
	v_exp_f32_e32 v109, v109
	v_mul_f32_e32 v81, v81, v91
	v_add_f32_e32 v109, 1.0, v109
	v_mul_f32_e32 v81, v81, v17
	v_div_scale_f32 v103, s[16:17], v101, v101, v100
	v_rcp_f32_e32 v104, v103
	s_nop 0
	v_fma_f32 v105, -v103, v104, 1.0
	v_fmac_f32_e32 v104, v105, v104
	v_div_scale_f32 v111, s[16:17], v109, v109, v108
	v_rcp_f32_e32 v112, v111
	s_nop 0
	v_fma_f32 v113, -v111, v112, 1.0
	v_fmac_f32_e32 v112, v113, v112
	v_div_scale_f32 v106, vcc, v100, v101, v100
	v_mul_f32_e32 v102, v106, v104
	v_fma_f32 v105, -v103, v102, v106
	v_fmac_f32_e32 v102, v105, v104
	v_fma_f32 v105, -v103, v102, v106
	v_div_fmas_f32 v102, v105, v104, v102
	v_div_fixup_f32 v102, v102, v101, v100
	v_mul_f32_e32 v80, v80, v102
	v_div_scale_f32 v114, vcc, v108, v109, v108
	v_mul_f32_e32 v110, v114, v112
	v_fma_f32 v113, -v111, v110, v114
	v_fmac_f32_e32 v110, v113, v112
	v_fma_f32 v113, -v111, v110, v114
	v_div_fmas_f32 v110, v113, v112, v110
	v_div_fixup_f32 v110, v110, v109, v108
	v_mul_f32_e32 v81, v81, v110
	v_lshlrev_b32_e32 v100, 16, v35
	v_mul_f32_e32 v101, 0xbfb8aa3b, v100
	v_exp_f32_e32 v101, v101
	v_mul_f32_e32 v82, v82, v91
	v_add_f32_e32 v101, 1.0, v101
	v_mul_f32_e32 v82, v82, v18
	v_and_b32_e32 v108, 0xffff0000, v35
	v_mul_f32_e32 v109, 0xbfb8aa3b, v108
	v_exp_f32_e32 v109, v109
	v_mul_f32_e32 v83, v83, v91
	v_add_f32_e32 v109, 1.0, v109
	v_mul_f32_e32 v83, v83, v19
	v_div_scale_f32 v103, s[16:17], v101, v101, v100
	v_rcp_f32_e32 v104, v103
	s_nop 0
	v_fma_f32 v105, -v103, v104, 1.0
	v_fmac_f32_e32 v104, v105, v104
	v_div_scale_f32 v111, s[16:17], v109, v109, v108
	v_rcp_f32_e32 v112, v111
	s_nop 0
	v_fma_f32 v113, -v111, v112, 1.0
	v_fmac_f32_e32 v112, v113, v112
	v_div_scale_f32 v106, vcc, v100, v101, v100
	v_mul_f32_e32 v102, v106, v104
	v_fma_f32 v105, -v103, v102, v106
	v_fmac_f32_e32 v102, v105, v104
	v_fma_f32 v105, -v103, v102, v106
	v_div_fmas_f32 v102, v105, v104, v102
	v_div_fixup_f32 v102, v102, v101, v100
	v_mul_f32_e32 v82, v82, v102
	v_div_scale_f32 v114, vcc, v108, v109, v108
	v_mul_f32_e32 v110, v114, v112
	v_fma_f32 v113, -v111, v110, v114
	v_fmac_f32_e32 v110, v113, v112
	v_fma_f32 v113, -v111, v110, v114
	v_div_fmas_f32 v110, v113, v112, v110
	v_div_fixup_f32 v110, v110, v109, v108
	v_mul_f32_e32 v83, v83, v110
	v_cvt_pk_bf16_f32 v98, v80, v81
	v_cvt_pk_bf16_f32 v99, v82, v83
	global_store_dwordx2 v1, v[98:99], s[14:15] offset:1536
	s_add_u32 s14, s14, 0x400000
	s_addc_u32 s15, s15, 0
	s_waitcnt vmcnt(16)
	v_lshlrev_b32_e32 v68, 16, v36
	v_and_b32_e32 v69, 0xffff0000, v36
	v_lshlrev_b32_e32 v70, 16, v37
	v_and_b32_e32 v71, 0xffff0000, v37
	v_lshlrev_b32_e32 v72, 16, v38
	v_and_b32_e32 v73, 0xffff0000, v38
	v_lshlrev_b32_e32 v74, 16, v39
	v_and_b32_e32 v75, 0xffff0000, v39
	v_lshlrev_b32_e32 v76, 16, v40
	v_and_b32_e32 v77, 0xffff0000, v40
	v_lshlrev_b32_e32 v78, 16, v41
	v_and_b32_e32 v79, 0xffff0000, v41
	v_lshlrev_b32_e32 v80, 16, v42
	v_and_b32_e32 v81, 0xffff0000, v42
	v_lshlrev_b32_e32 v82, 16, v43
	v_and_b32_e32 v83, 0xffff0000, v43
	v_mul_f32_e32 v84, v68, v68
	v_mul_f32_e32 v85, v72, v72
	v_mul_f32_e32 v86, v76, v76
	v_mul_f32_e32 v87, v80, v80
	v_fmac_f32_e32 v84, v69, v69
	v_fmac_f32_e32 v85, v73, v73
	v_fmac_f32_e32 v86, v77, v77
	v_fmac_f32_e32 v87, v81, v81
	v_fmac_f32_e32 v84, v70, v70
	v_fmac_f32_e32 v85, v74, v74
	v_fmac_f32_e32 v86, v78, v78
	v_fmac_f32_e32 v87, v82, v82
	v_fmac_f32_e32 v84, v71, v71
	v_fmac_f32_e32 v85, v75, v75
	v_fmac_f32_e32 v86, v79, v79
	v_fmac_f32_e32 v87, v83, v83
	v_add_f32_dpp v84, v84, v84 quad_perm:[1,0,3,2] row_mask:0xf bank_mask:0xf
	v_add_f32_dpp v85, v85, v85 quad_perm:[1,0,3,2] row_mask:0xf bank_mask:0xf
	v_add_f32_dpp v86, v86, v86 quad_perm:[1,0,3,2] row_mask:0xf bank_mask:0xf
	v_add_f32_dpp v87, v87, v87 quad_perm:[1,0,3,2] row_mask:0xf bank_mask:0xf
	v_add_f32_dpp v84, v84, v84 quad_perm:[2,3,0,1] row_mask:0xf bank_mask:0xf
	v_add_f32_dpp v85, v85, v85 quad_perm:[2,3,0,1] row_mask:0xf bank_mask:0xf
	v_add_f32_dpp v86, v86, v86 quad_perm:[2,3,0,1] row_mask:0xf bank_mask:0xf
	v_add_f32_dpp v87, v87, v87 quad_perm:[2,3,0,1] row_mask:0xf bank_mask:0xf
	v_add_f32_dpp v84, v84, v84 row_half_mirror row_mask:0xf bank_mask:0xf
	v_add_f32_dpp v85, v85, v85 row_half_mirror row_mask:0xf bank_mask:0xf
	v_add_f32_dpp v86, v86, v86 row_half_mirror row_mask:0xf bank_mask:0xf
	v_add_f32_dpp v87, v87, v87 row_half_mirror row_mask:0xf bank_mask:0xf
	v_add_f32_dpp v84, v84, v84 row_mirror row_mask:0xf bank_mask:0xf
	v_add_f32_dpp v85, v85, v85 row_mirror row_mask:0xf bank_mask:0xf
	v_add_f32_dpp v86, v86, v86 row_mirror row_mask:0xf bank_mask:0xf
	v_add_f32_dpp v87, v87, v87 row_mirror row_mask:0xf bank_mask:0xf
	v_add_f32_dpp v84, v84, v84 row_bcast:15 row_mask:0xa bank_mask:0xf
	v_add_f32_dpp v85, v85, v85 row_bcast:15 row_mask:0xa bank_mask:0xf
	v_add_f32_dpp v86, v86, v86 row_bcast:15 row_mask:0xa bank_mask:0xf
	v_add_f32_dpp v87, v87, v87 row_bcast:15 row_mask:0xa bank_mask:0xf
	v_add_f32_dpp v84, v84, v84 row_bcast:31 row_mask:0xc bank_mask:0xf
	v_add_f32_dpp v85, v85, v85 row_bcast:31 row_mask:0xc bank_mask:0xf
	v_add_f32_dpp v86, v86, v86 row_bcast:31 row_mask:0xc bank_mask:0xf
	v_add_f32_dpp v87, v87, v87 row_bcast:31 row_mask:0xc bank_mask:0xf
	s_nop 0
	v_readlane_b32 s28, v84, 63
	v_readlane_b32 s29, v85, 63
	v_readlane_b32 s30, v86, 63
	v_readlane_b32 s31, v87, 63
	s_nop 1
	v_fma_f32 v88, s28, v2, v3
	v_fma_f32 v89, s29, v2, v3
	v_fma_f32 v90, s30, v2, v3
	v_fma_f32 v91, s31, v2, v3
	v_rsq_f32_e32 v88, v88
	v_rsq_f32_e32 v89, v89
	v_rsq_f32_e32 v90, v90
	v_rsq_f32_e32 v91, v91
	s_nop 0
	v_lshlrev_b32_e32 v100, 16, v44
	v_mul_f32_e32 v101, 0xbfb8aa3b, v100
	v_exp_f32_e32 v101, v101
	v_mul_f32_e32 v68, v68, v88
	v_add_f32_e32 v101, 1.0, v101
	v_mul_f32_e32 v68, v68, v4
	v_and_b32_e32 v108, 0xffff0000, v44
	v_mul_f32_e32 v109, 0xbfb8aa3b, v108
	v_exp_f32_e32 v109, v109
	v_mul_f32_e32 v69, v69, v88
	v_add_f32_e32 v109, 1.0, v109
	v_mul_f32_e32 v69, v69, v5
	v_div_scale_f32 v103, s[16:17], v101, v101, v100
	v_rcp_f32_e32 v104, v103
	s_nop 0
	v_fma_f32 v105, -v103, v104, 1.0
	v_fmac_f32_e32 v104, v105, v104
	v_div_scale_f32 v111, s[16:17], v109, v109, v108
	v_rcp_f32_e32 v112, v111
	s_nop 0
	v_fma_f32 v113, -v111, v112, 1.0
	v_fmac_f32_e32 v112, v113, v112
	v_div_scale_f32 v106, vcc, v100, v101, v100
	v_mul_f32_e32 v102, v106, v104
	v_fma_f32 v105, -v103, v102, v106
	v_fmac_f32_e32 v102, v105, v104
	v_fma_f32 v105, -v103, v102, v106
	v_div_fmas_f32 v102, v105, v104, v102
	v_div_fixup_f32 v102, v102, v101, v100
	v_mul_f32_e32 v68, v68, v102
	v_div_scale_f32 v114, vcc, v108, v109, v108
	v_mul_f32_e32 v110, v114, v112
	v_fma_f32 v113, -v111, v110, v114
	v_fmac_f32_e32 v110, v113, v112
	v_fma_f32 v113, -v111, v110, v114
	v_div_fmas_f32 v110, v113, v112, v110
	v_div_fixup_f32 v110, v110, v109, v108
	v_mul_f32_e32 v69, v69, v110
	v_lshlrev_b32_e32 v100, 16, v45
	v_mul_f32_e32 v101, 0xbfb8aa3b, v100
	v_exp_f32_e32 v101, v101
	v_mul_f32_e32 v70, v70, v88
	v_add_f32_e32 v101, 1.0, v101
	v_mul_f32_e32 v70, v70, v6
	v_and_b32_e32 v108, 0xffff0000, v45
	v_mul_f32_e32 v109, 0xbfb8aa3b, v108
	v_exp_f32_e32 v109, v109
	v_mul_f32_e32 v71, v71, v88
	v_add_f32_e32 v109, 1.0, v109
	v_mul_f32_e32 v71, v71, v7
	v_div_scale_f32 v103, s[16:17], v101, v101, v100
	v_rcp_f32_e32 v104, v103
	s_nop 0
	v_fma_f32 v105, -v103, v104, 1.0
	v_fmac_f32_e32 v104, v105, v104
	v_div_scale_f32 v111, s[16:17], v109, v109, v108
	v_rcp_f32_e32 v112, v111
	s_nop 0
	v_fma_f32 v113, -v111, v112, 1.0
	v_fmac_f32_e32 v112, v113, v112
	v_div_scale_f32 v106, vcc, v100, v101, v100
	v_mul_f32_e32 v102, v106, v104
	v_fma_f32 v105, -v103, v102, v106
	v_fmac_f32_e32 v102, v105, v104
	v_fma_f32 v105, -v103, v102, v106
	v_div_fmas_f32 v102, v105, v104, v102
	v_div_fixup_f32 v102, v102, v101, v100
	v_mul_f32_e32 v70, v70, v102
	v_div_scale_f32 v114, vcc, v108, v109, v108
	v_mul_f32_e32 v110, v114, v112
	v_fma_f32 v113, -v111, v110, v114
	v_fmac_f32_e32 v110, v113, v112
	v_fma_f32 v113, -v111, v110, v114
	v_div_fmas_f32 v110, v113, v112, v110
	v_div_fixup_f32 v110, v110, v109, v108
	v_mul_f32_e32 v71, v71, v110
	v_cvt_pk_bf16_f32 v92, v68, v69
	v_cvt_pk_bf16_f32 v93, v70, v71
	global_store_dwordx2 v1, v[92:93], s[14:15] offset:0
	v_lshlrev_b32_e32 v100, 16, v46
	v_mul_f32_e32 v101, 0xbfb8aa3b, v100
	v_exp_f32_e32 v101, v101
	v_mul_f32_e32 v72, v72, v89
	v_add_f32_e32 v101, 1.0, v101
	v_mul_f32_e32 v72, v72, v8
	v_and_b32_e32 v108, 0xffff0000, v46
	v_mul_f32_e32 v109, 0xbfb8aa3b, v108
	v_exp_f32_e32 v109, v109
	v_mul_f32_e32 v73, v73, v89
	v_add_f32_e32 v109, 1.0, v109
	v_mul_f32_e32 v73, v73, v9
	v_div_scale_f32 v103, s[16:17], v101, v101, v100
	v_rcp_f32_e32 v104, v103
	s_nop 0
	v_fma_f32 v105, -v103, v104, 1.0
	v_fmac_f32_e32 v104, v105, v104
	v_div_scale_f32 v111, s[16:17], v109, v109, v108
	v_rcp_f32_e32 v112, v111
	s_nop 0
	v_fma_f32 v113, -v111, v112, 1.0
	v_fmac_f32_e32 v112, v113, v112
	v_div_scale_f32 v106, vcc, v100, v101, v100
	v_mul_f32_e32 v102, v106, v104
	v_fma_f32 v105, -v103, v102, v106
	v_fmac_f32_e32 v102, v105, v104
	v_fma_f32 v105, -v103, v102, v106
	v_div_fmas_f32 v102, v105, v104, v102
	v_div_fixup_f32 v102, v102, v101, v100
	v_mul_f32_e32 v72, v72, v102
	v_div_scale_f32 v114, vcc, v108, v109, v108
	v_mul_f32_e32 v110, v114, v112
	v_fma_f32 v113, -v111, v110, v114
	v_fmac_f32_e32 v110, v113, v112
	v_fma_f32 v113, -v111, v110, v114
	v_div_fmas_f32 v110, v113, v112, v110
	v_div_fixup_f32 v110, v110, v109, v108
	v_mul_f32_e32 v73, v73, v110
	v_lshlrev_b32_e32 v100, 16, v47
	v_mul_f32_e32 v101, 0xbfb8aa3b, v100
	v_exp_f32_e32 v101, v101
	v_mul_f32_e32 v74, v74, v89
	v_add_f32_e32 v101, 1.0, v101
	v_mul_f32_e32 v74, v74, v10
	v_and_b32_e32 v108, 0xffff0000, v47
	v_mul_f32_e32 v109, 0xbfb8aa3b, v108
	v_exp_f32_e32 v109, v109
	v_mul_f32_e32 v75, v75, v89
	v_add_f32_e32 v109, 1.0, v109
	v_mul_f32_e32 v75, v75, v11
	v_div_scale_f32 v103, s[16:17], v101, v101, v100
	v_rcp_f32_e32 v104, v103
	s_nop 0
	v_fma_f32 v105, -v103, v104, 1.0
	v_fmac_f32_e32 v104, v105, v104
	v_div_scale_f32 v111, s[16:17], v109, v109, v108
	v_rcp_f32_e32 v112, v111
	s_nop 0
	v_fma_f32 v113, -v111, v112, 1.0
	v_fmac_f32_e32 v112, v113, v112
	v_div_scale_f32 v106, vcc, v100, v101, v100
	v_mul_f32_e32 v102, v106, v104
	v_fma_f32 v105, -v103, v102, v106
	v_fmac_f32_e32 v102, v105, v104
	v_fma_f32 v105, -v103, v102, v106
	v_div_fmas_f32 v102, v105, v104, v102
	v_div_fixup_f32 v102, v102, v101, v100
	v_mul_f32_e32 v74, v74, v102
	v_div_scale_f32 v114, vcc, v108, v109, v108
	v_mul_f32_e32 v110, v114, v112
	v_fma_f32 v113, -v111, v110, v114
	v_fmac_f32_e32 v110, v113, v112
	v_fma_f32 v113, -v111, v110, v114
	v_div_fmas_f32 v110, v113, v112, v110
	v_div_fixup_f32 v110, v110, v109, v108
	v_mul_f32_e32 v75, v75, v110
	v_cvt_pk_bf16_f32 v94, v72, v73
	v_cvt_pk_bf16_f32 v95, v74, v75
	global_store_dwordx2 v1, v[94:95], s[14:15] offset:512
	v_lshlrev_b32_e32 v100, 16, v48
	v_mul_f32_e32 v101, 0xbfb8aa3b, v100
	v_exp_f32_e32 v101, v101
	v_mul_f32_e32 v76, v76, v90
	v_add_f32_e32 v101, 1.0, v101
	v_mul_f32_e32 v76, v76, v12
	v_and_b32_e32 v108, 0xffff0000, v48
	v_mul_f32_e32 v109, 0xbfb8aa3b, v108
	v_exp_f32_e32 v109, v109
	v_mul_f32_e32 v77, v77, v90
	v_add_f32_e32 v109, 1.0, v109
	v_mul_f32_e32 v77, v77, v13
	v_div_scale_f32 v103, s[16:17], v101, v101, v100
	v_rcp_f32_e32 v104, v103
	s_nop 0
	v_fma_f32 v105, -v103, v104, 1.0
	v_fmac_f32_e32 v104, v105, v104
	v_div_scale_f32 v111, s[16:17], v109, v109, v108
	v_rcp_f32_e32 v112, v111
	s_nop 0
	v_fma_f32 v113, -v111, v112, 1.0
	v_fmac_f32_e32 v112, v113, v112
	v_div_scale_f32 v106, vcc, v100, v101, v100
	v_mul_f32_e32 v102, v106, v104
	v_fma_f32 v105, -v103, v102, v106
	v_fmac_f32_e32 v102, v105, v104
	v_fma_f32 v105, -v103, v102, v106
	v_div_fmas_f32 v102, v105, v104, v102
	v_div_fixup_f32 v102, v102, v101, v100
	v_mul_f32_e32 v76, v76, v102
	v_div_scale_f32 v114, vcc, v108, v109, v108
	v_mul_f32_e32 v110, v114, v112
	v_fma_f32 v113, -v111, v110, v114
	v_fmac_f32_e32 v110, v113, v112
	v_fma_f32 v113, -v111, v110, v114
	v_div_fmas_f32 v110, v113, v112, v110
	v_div_fixup_f32 v110, v110, v109, v108
	v_mul_f32_e32 v77, v77, v110
	v_lshlrev_b32_e32 v100, 16, v49
	v_mul_f32_e32 v101, 0xbfb8aa3b, v100
	v_exp_f32_e32 v101, v101
	v_mul_f32_e32 v78, v78, v90
	v_add_f32_e32 v101, 1.0, v101
	v_mul_f32_e32 v78, v78, v14
	v_and_b32_e32 v108, 0xffff0000, v49
	v_mul_f32_e32 v109, 0xbfb8aa3b, v108
	v_exp_f32_e32 v109, v109
	v_mul_f32_e32 v79, v79, v90
	v_add_f32_e32 v109, 1.0, v109
	v_mul_f32_e32 v79, v79, v15
	v_div_scale_f32 v103, s[16:17], v101, v101, v100
	v_rcp_f32_e32 v104, v103
	s_nop 0
	v_fma_f32 v105, -v103, v104, 1.0
	v_fmac_f32_e32 v104, v105, v104
	v_div_scale_f32 v111, s[16:17], v109, v109, v108
	v_rcp_f32_e32 v112, v111
	s_nop 0
	v_fma_f32 v113, -v111, v112, 1.0
	v_fmac_f32_e32 v112, v113, v112
	v_div_scale_f32 v106, vcc, v100, v101, v100
	v_mul_f32_e32 v102, v106, v104
	v_fma_f32 v105, -v103, v102, v106
	v_fmac_f32_e32 v102, v105, v104
	v_fma_f32 v105, -v103, v102, v106
	v_div_fmas_f32 v102, v105, v104, v102
	v_div_fixup_f32 v102, v102, v101, v100
	v_mul_f32_e32 v78, v78, v102
	v_div_scale_f32 v114, vcc, v108, v109, v108
	v_mul_f32_e32 v110, v114, v112
	v_fma_f32 v113, -v111, v110, v114
	v_fmac_f32_e32 v110, v113, v112
	v_fma_f32 v113, -v111, v110, v114
	v_div_fmas_f32 v110, v113, v112, v110
	v_div_fixup_f32 v110, v110, v109, v108
	v_mul_f32_e32 v79, v79, v110
	v_cvt_pk_bf16_f32 v96, v76, v77
	v_cvt_pk_bf16_f32 v97, v78, v79
	global_store_dwordx2 v1, v[96:97], s[14:15] offset:1024
	v_lshlrev_b32_e32 v100, 16, v50
	v_mul_f32_e32 v101, 0xbfb8aa3b, v100
	v_exp_f32_e32 v101, v101
	v_mul_f32_e32 v80, v80, v91
	v_add_f32_e32 v101, 1.0, v101
	v_mul_f32_e32 v80, v80, v16
	v_and_b32_e32 v108, 0xffff0000, v50
	v_mul_f32_e32 v109, 0xbfb8aa3b, v108
	v_exp_f32_e32 v109, v109
	v_mul_f32_e32 v81, v81, v91
	v_add_f32_e32 v109, 1.0, v109
	v_mul_f32_e32 v81, v81, v17
	v_div_scale_f32 v103, s[16:17], v101, v101, v100
	v_rcp_f32_e32 v104, v103
	s_nop 0
	v_fma_f32 v105, -v103, v104, 1.0
	v_fmac_f32_e32 v104, v105, v104
	v_div_scale_f32 v111, s[16:17], v109, v109, v108
	v_rcp_f32_e32 v112, v111
	s_nop 0
	v_fma_f32 v113, -v111, v112, 1.0
	v_fmac_f32_e32 v112, v113, v112
	v_div_scale_f32 v106, vcc, v100, v101, v100
	v_mul_f32_e32 v102, v106, v104
	v_fma_f32 v105, -v103, v102, v106
	v_fmac_f32_e32 v102, v105, v104
	v_fma_f32 v105, -v103, v102, v106
	v_div_fmas_f32 v102, v105, v104, v102
	v_div_fixup_f32 v102, v102, v101, v100
	v_mul_f32_e32 v80, v80, v102
	v_div_scale_f32 v114, vcc, v108, v109, v108
	v_mul_f32_e32 v110, v114, v112
	v_fma_f32 v113, -v111, v110, v114
	v_fmac_f32_e32 v110, v113, v112
	v_fma_f32 v113, -v111, v110, v114
	v_div_fmas_f32 v110, v113, v112, v110
	v_div_fixup_f32 v110, v110, v109, v108
	v_mul_f32_e32 v81, v81, v110
	v_lshlrev_b32_e32 v100, 16, v51
	v_mul_f32_e32 v101, 0xbfb8aa3b, v100
	v_exp_f32_e32 v101, v101
	v_mul_f32_e32 v82, v82, v91
	v_add_f32_e32 v101, 1.0, v101
	v_mul_f32_e32 v82, v82, v18
	v_and_b32_e32 v108, 0xffff0000, v51
	v_mul_f32_e32 v109, 0xbfb8aa3b, v108
	v_exp_f32_e32 v109, v109
	v_mul_f32_e32 v83, v83, v91
	v_add_f32_e32 v109, 1.0, v109
	v_mul_f32_e32 v83, v83, v19
	v_div_scale_f32 v103, s[16:17], v101, v101, v100
	v_rcp_f32_e32 v104, v103
	s_nop 0
	v_fma_f32 v105, -v103, v104, 1.0
	v_fmac_f32_e32 v104, v105, v104
	v_div_scale_f32 v111, s[16:17], v109, v109, v108
	v_rcp_f32_e32 v112, v111
	s_nop 0
	v_fma_f32 v113, -v111, v112, 1.0
	v_fmac_f32_e32 v112, v113, v112
	v_div_scale_f32 v106, vcc, v100, v101, v100
	v_mul_f32_e32 v102, v106, v104
	v_fma_f32 v105, -v103, v102, v106
	v_fmac_f32_e32 v102, v105, v104
	v_fma_f32 v105, -v103, v102, v106
	v_div_fmas_f32 v102, v105, v104, v102
	v_div_fixup_f32 v102, v102, v101, v100
	v_mul_f32_e32 v82, v82, v102
	v_div_scale_f32 v114, vcc, v108, v109, v108
	v_mul_f32_e32 v110, v114, v112
	v_fma_f32 v113, -v111, v110, v114
	v_fmac_f32_e32 v110, v113, v112
	v_fma_f32 v113, -v111, v110, v114
	v_div_fmas_f32 v110, v113, v112, v110
	v_div_fixup_f32 v110, v110, v109, v108
	v_mul_f32_e32 v83, v83, v110
	v_cvt_pk_bf16_f32 v98, v80, v81
	v_cvt_pk_bf16_f32 v99, v82, v83
	global_store_dwordx2 v1, v[98:99], s[14:15] offset:1536
	s_add_u32 s14, s14, 0x400000
	s_addc_u32 s15, s15, 0
	s_cmp_eq_u32 s22, 0
	s_cbranch_scc1 .Lgate_done
	s_waitcnt vmcnt(8)
	v_lshlrev_b32_e32 v68, 16, v52
	v_and_b32_e32 v69, 0xffff0000, v52
	v_lshlrev_b32_e32 v70, 16, v53
	v_and_b32_e32 v71, 0xffff0000, v53
	v_lshlrev_b32_e32 v72, 16, v54
	v_and_b32_e32 v73, 0xffff0000, v54
	v_lshlrev_b32_e32 v74, 16, v55
	v_and_b32_e32 v75, 0xffff0000, v55
	v_lshlrev_b32_e32 v76, 16, v56
	v_and_b32_e32 v77, 0xffff0000, v56
	v_lshlrev_b32_e32 v78, 16, v57
	v_and_b32_e32 v79, 0xffff0000, v57
	v_lshlrev_b32_e32 v80, 16, v58
	v_and_b32_e32 v81, 0xffff0000, v58
	v_lshlrev_b32_e32 v82, 16, v59
	v_and_b32_e32 v83, 0xffff0000, v59
	v_mul_f32_e32 v84, v68, v68
	v_mul_f32_e32 v85, v72, v72
	v_mul_f32_e32 v86, v76, v76
	v_mul_f32_e32 v87, v80, v80
	v_fmac_f32_e32 v84, v69, v69
	v_fmac_f32_e32 v85, v73, v73
	v_fmac_f32_e32 v86, v77, v77
	v_fmac_f32_e32 v87, v81, v81
	v_fmac_f32_e32 v84, v70, v70
	v_fmac_f32_e32 v85, v74, v74
	v_fmac_f32_e32 v86, v78, v78
	v_fmac_f32_e32 v87, v82, v82
	v_fmac_f32_e32 v84, v71, v71
	v_fmac_f32_e32 v85, v75, v75
	v_fmac_f32_e32 v86, v79, v79
	v_fmac_f32_e32 v87, v83, v83
	v_add_f32_dpp v84, v84, v84 quad_perm:[1,0,3,2] row_mask:0xf bank_mask:0xf
	v_add_f32_dpp v85, v85, v85 quad_perm:[1,0,3,2] row_mask:0xf bank_mask:0xf
	v_add_f32_dpp v86, v86, v86 quad_perm:[1,0,3,2] row_mask:0xf bank_mask:0xf
	v_add_f32_dpp v87, v87, v87 quad_perm:[1,0,3,2] row_mask:0xf bank_mask:0xf
	v_add_f32_dpp v84, v84, v84 quad_perm:[2,3,0,1] row_mask:0xf bank_mask:0xf
	v_add_f32_dpp v85, v85, v85 quad_perm:[2,3,0,1] row_mask:0xf bank_mask:0xf
	v_add_f32_dpp v86, v86, v86 quad_perm:[2,3,0,1] row_mask:0xf bank_mask:0xf
	v_add_f32_dpp v87, v87, v87 quad_perm:[2,3,0,1] row_mask:0xf bank_mask:0xf
	v_add_f32_dpp v84, v84, v84 row_half_mirror row_mask:0xf bank_mask:0xf
	v_add_f32_dpp v85, v85, v85 row_half_mirror row_mask:0xf bank_mask:0xf
	v_add_f32_dpp v86, v86, v86 row_half_mirror row_mask:0xf bank_mask:0xf
	v_add_f32_dpp v87, v87, v87 row_half_mirror row_mask:0xf bank_mask:0xf
	v_add_f32_dpp v84, v84, v84 row_mirror row_mask:0xf bank_mask:0xf
	v_add_f32_dpp v85, v85, v85 row_mirror row_mask:0xf bank_mask:0xf
	v_add_f32_dpp v86, v86, v86 row_mirror row_mask:0xf bank_mask:0xf
	v_add_f32_dpp v87, v87, v87 row_mirror row_mask:0xf bank_mask:0xf
	v_add_f32_dpp v84, v84, v84 row_bcast:15 row_mask:0xa bank_mask:0xf
	v_add_f32_dpp v85, v85, v85 row_bcast:15 row_mask:0xa bank_mask:0xf
	v_add_f32_dpp v86, v86, v86 row_bcast:15 row_mask:0xa bank_mask:0xf
	v_add_f32_dpp v87, v87, v87 row_bcast:15 row_mask:0xa bank_mask:0xf
	v_add_f32_dpp v84, v84, v84 row_bcast:31 row_mask:0xc bank_mask:0xf
	v_add_f32_dpp v85, v85, v85 row_bcast:31 row_mask:0xc bank_mask:0xf
	v_add_f32_dpp v86, v86, v86 row_bcast:31 row_mask:0xc bank_mask:0xf
	v_add_f32_dpp v87, v87, v87 row_bcast:31 row_mask:0xc bank_mask:0xf
	s_nop 0
	v_readlane_b32 s28, v84, 63
	v_readlane_b32 s29, v85, 63
	v_readlane_b32 s30, v86, 63
	v_readlane_b32 s31, v87, 63
	s_nop 1
	v_fma_f32 v88, s28, v2, v3
	v_fma_f32 v89, s29, v2, v3
	v_fma_f32 v90, s30, v2, v3
	v_fma_f32 v91, s31, v2, v3
	v_rsq_f32_e32 v88, v88
	v_rsq_f32_e32 v89, v89
	v_rsq_f32_e32 v90, v90
	v_rsq_f32_e32 v91, v91
	s_nop 0
	v_lshlrev_b32_e32 v100, 16, v60
	v_mul_f32_e32 v101, 0xbfb8aa3b, v100
	v_exp_f32_e32 v101, v101
	v_mul_f32_e32 v68, v68, v88
	v_add_f32_e32 v101, 1.0, v101
	v_mul_f32_e32 v68, v68, v4
	v_and_b32_e32 v108, 0xffff0000, v60
	v_mul_f32_e32 v109, 0xbfb8aa3b, v108
	v_exp_f32_e32 v109, v109
	v_mul_f32_e32 v69, v69, v88
	v_add_f32_e32 v109, 1.0, v109
	v_mul_f32_e32 v69, v69, v5
	v_div_scale_f32 v103, s[16:17], v101, v101, v100
	v_rcp_f32_e32 v104, v103
	s_nop 0
	v_fma_f32 v105, -v103, v104, 1.0
	v_fmac_f32_e32 v104, v105, v104
	v_div_scale_f32 v111, s[16:17], v109, v109, v108
	v_rcp_f32_e32 v112, v111
	s_nop 0
	v_fma_f32 v113, -v111, v112, 1.0
	v_fmac_f32_e32 v112, v113, v112
	v_div_scale_f32 v106, vcc, v100, v101, v100
	v_mul_f32_e32 v102, v106, v104
	v_fma_f32 v105, -v103, v102, v106
	v_fmac_f32_e32 v102, v105, v104
	v_fma_f32 v105, -v103, v102, v106
	v_div_fmas_f32 v102, v105, v104, v102
	v_div_fixup_f32 v102, v102, v101, v100
	v_mul_f32_e32 v68, v68, v102
	v_div_scale_f32 v114, vcc, v108, v109, v108
	v_mul_f32_e32 v110, v114, v112
	v_fma_f32 v113, -v111, v110, v114
	v_fmac_f32_e32 v110, v113, v112
	v_fma_f32 v113, -v111, v110, v114
	v_div_fmas_f32 v110, v113, v112, v110
	v_div_fixup_f32 v110, v110, v109, v108
	v_mul_f32_e32 v69, v69, v110
	v_lshlrev_b32_e32 v100, 16, v61
	v_mul_f32_e32 v101, 0xbfb8aa3b, v100
	v_exp_f32_e32 v101, v101
	v_mul_f32_e32 v70, v70, v88
	v_add_f32_e32 v101, 1.0, v101
	v_mul_f32_e32 v70, v70, v6
	v_and_b32_e32 v108, 0xffff0000, v61
	v_mul_f32_e32 v109, 0xbfb8aa3b, v108
	v_exp_f32_e32 v109, v109
	v_mul_f32_e32 v71, v71, v88
	v_add_f32_e32 v109, 1.0, v109
	v_mul_f32_e32 v71, v71, v7
	v_div_scale_f32 v103, s[16:17], v101, v101, v100
	v_rcp_f32_e32 v104, v103
	s_nop 0
	v_fma_f32 v105, -v103, v104, 1.0
	v_fmac_f32_e32 v104, v105, v104
	v_div_scale_f32 v111, s[16:17], v109, v109, v108
	v_rcp_f32_e32 v112, v111
	s_nop 0
	v_fma_f32 v113, -v111, v112, 1.0
	v_fmac_f32_e32 v112, v113, v112
	v_div_scale_f32 v106, vcc, v100, v101, v100
	v_mul_f32_e32 v102, v106, v104
	v_fma_f32 v105, -v103, v102, v106
	v_fmac_f32_e32 v102, v105, v104
	v_fma_f32 v105, -v103, v102, v106
	v_div_fmas_f32 v102, v105, v104, v102
	v_div_fixup_f32 v102, v102, v101, v100
	v_mul_f32_e32 v70, v70, v102
	v_div_scale_f32 v114, vcc, v108, v109, v108
	v_mul_f32_e32 v110, v114, v112
	v_fma_f32 v113, -v111, v110, v114
	v_fmac_f32_e32 v110, v113, v112
	v_fma_f32 v113, -v111, v110, v114
	v_div_fmas_f32 v110, v113, v112, v110
	v_div_fixup_f32 v110, v110, v109, v108
	v_mul_f32_e32 v71, v71, v110
	v_cvt_pk_bf16_f32 v92, v68, v69
	v_cvt_pk_bf16_f32 v93, v70, v71
	global_store_dwordx2 v1, v[92:93], s[14:15] offset:0
	v_lshlrev_b32_e32 v100, 16, v62
	v_mul_f32_e32 v101, 0xbfb8aa3b, v100
	v_exp_f32_e32 v101, v101
	v_mul_f32_e32 v72, v72, v89
	v_add_f32_e32 v101, 1.0, v101
	v_mul_f32_e32 v72, v72, v8
	v_and_b32_e32 v108, 0xffff0000, v62
	v_mul_f32_e32 v109, 0xbfb8aa3b, v108
	v_exp_f32_e32 v109, v109
	v_mul_f32_e32 v73, v73, v89
	v_add_f32_e32 v109, 1.0, v109
	v_mul_f32_e32 v73, v73, v9
	v_div_scale_f32 v103, s[16:17], v101, v101, v100
	v_rcp_f32_e32 v104, v103
	s_nop 0
	v_fma_f32 v105, -v103, v104, 1.0
	v_fmac_f32_e32 v104, v105, v104
	v_div_scale_f32 v111, s[16:17], v109, v109, v108
	v_rcp_f32_e32 v112, v111
	s_nop 0
	v_fma_f32 v113, -v111, v112, 1.0
	v_fmac_f32_e32 v112, v113, v112
	v_div_scale_f32 v106, vcc, v100, v101, v100
	v_mul_f32_e32 v102, v106, v104
	v_fma_f32 v105, -v103, v102, v106
	v_fmac_f32_e32 v102, v105, v104
	v_fma_f32 v105, -v103, v102, v106
	v_div_fmas_f32 v102, v105, v104, v102
	v_div_fixup_f32 v102, v102, v101, v100
	v_mul_f32_e32 v72, v72, v102
	v_div_scale_f32 v114, vcc, v108, v109, v108
	v_mul_f32_e32 v110, v114, v112
	v_fma_f32 v113, -v111, v110, v114
	v_fmac_f32_e32 v110, v113, v112
	v_fma_f32 v113, -v111, v110, v114
	v_div_fmas_f32 v110, v113, v112, v110
	v_div_fixup_f32 v110, v110, v109, v108
	v_mul_f32_e32 v73, v73, v110
	v_lshlrev_b32_e32 v100, 16, v63
	v_mul_f32_e32 v101, 0xbfb8aa3b, v100
	v_exp_f32_e32 v101, v101
	v_mul_f32_e32 v74, v74, v89
	v_add_f32_e32 v101, 1.0, v101
	v_mul_f32_e32 v74, v74, v10
	v_and_b32_e32 v108, 0xffff0000, v63
	v_mul_f32_e32 v109, 0xbfb8aa3b, v108
	v_exp_f32_e32 v109, v109
	v_mul_f32_e32 v75, v75, v89
	v_add_f32_e32 v109, 1.0, v109
	v_mul_f32_e32 v75, v75, v11
	v_div_scale_f32 v103, s[16:17], v101, v101, v100
	v_rcp_f32_e32 v104, v103
	s_nop 0
	v_fma_f32 v105, -v103, v104, 1.0
	v_fmac_f32_e32 v104, v105, v104
	v_div_scale_f32 v111, s[16:17], v109, v109, v108
	v_rcp_f32_e32 v112, v111
	s_nop 0
	v_fma_f32 v113, -v111, v112, 1.0
	v_fmac_f32_e32 v112, v113, v112
	v_div_scale_f32 v106, vcc, v100, v101, v100
	v_mul_f32_e32 v102, v106, v104
	v_fma_f32 v105, -v103, v102, v106
	v_fmac_f32_e32 v102, v105, v104
	v_fma_f32 v105, -v103, v102, v106
	v_div_fmas_f32 v102, v105, v104, v102
	v_div_fixup_f32 v102, v102, v101, v100
	v_mul_f32_e32 v74, v74, v102
	v_div_scale_f32 v114, vcc, v108, v109, v108
	v_mul_f32_e32 v110, v114, v112
	v_fma_f32 v113, -v111, v110, v114
	v_fmac_f32_e32 v110, v113, v112
	v_fma_f32 v113, -v111, v110, v114
	v_div_fmas_f32 v110, v113, v112, v110
	v_div_fixup_f32 v110, v110, v109, v108
	v_mul_f32_e32 v75, v75, v110
	v_cvt_pk_bf16_f32 v94, v72, v73
	v_cvt_pk_bf16_f32 v95, v74, v75
	global_store_dwordx2 v1, v[94:95], s[14:15] offset:512
	v_lshlrev_b32_e32 v100, 16, v64
	v_mul_f32_e32 v101, 0xbfb8aa3b, v100
	v_exp_f32_e32 v101, v101
	v_mul_f32_e32 v76, v76, v90
	v_add_f32_e32 v101, 1.0, v101
	v_mul_f32_e32 v76, v76, v12
	v_and_b32_e32 v108, 0xffff0000, v64
	v_mul_f32_e32 v109, 0xbfb8aa3b, v108
	v_exp_f32_e32 v109, v109
	v_mul_f32_e32 v77, v77, v90
	v_add_f32_e32 v109, 1.0, v109
	v_mul_f32_e32 v77, v77, v13
	v_div_scale_f32 v103, s[16:17], v101, v101, v100
	v_rcp_f32_e32 v104, v103
	s_nop 0
	v_fma_f32 v105, -v103, v104, 1.0
	v_fmac_f32_e32 v104, v105, v104
	v_div_scale_f32 v111, s[16:17], v109, v109, v108
	v_rcp_f32_e32 v112, v111
	s_nop 0
	v_fma_f32 v113, -v111, v112, 1.0
	v_fmac_f32_e32 v112, v113, v112
	v_div_scale_f32 v106, vcc, v100, v101, v100
	v_mul_f32_e32 v102, v106, v104
	v_fma_f32 v105, -v103, v102, v106
	v_fmac_f32_e32 v102, v105, v104
	v_fma_f32 v105, -v103, v102, v106
	v_div_fmas_f32 v102, v105, v104, v102
	v_div_fixup_f32 v102, v102, v101, v100
	v_mul_f32_e32 v76, v76, v102
	v_div_scale_f32 v114, vcc, v108, v109, v108
	v_mul_f32_e32 v110, v114, v112
	v_fma_f32 v113, -v111, v110, v114
	v_fmac_f32_e32 v110, v113, v112
	v_fma_f32 v113, -v111, v110, v114
	v_div_fmas_f32 v110, v113, v112, v110
	v_div_fixup_f32 v110, v110, v109, v108
	v_mul_f32_e32 v77, v77, v110
	v_lshlrev_b32_e32 v100, 16, v65
	v_mul_f32_e32 v101, 0xbfb8aa3b, v100
	v_exp_f32_e32 v101, v101
	v_mul_f32_e32 v78, v78, v90
	v_add_f32_e32 v101, 1.0, v101
	v_mul_f32_e32 v78, v78, v14
	v_and_b32_e32 v108, 0xffff0000, v65
	v_mul_f32_e32 v109, 0xbfb8aa3b, v108
	v_exp_f32_e32 v109, v109
	v_mul_f32_e32 v79, v79, v90
	v_add_f32_e32 v109, 1.0, v109
	v_mul_f32_e32 v79, v79, v15
	v_div_scale_f32 v103, s[16:17], v101, v101, v100
	v_rcp_f32_e32 v104, v103
	s_nop 0
	v_fma_f32 v105, -v103, v104, 1.0
	v_fmac_f32_e32 v104, v105, v104
	v_div_scale_f32 v111, s[16:17], v109, v109, v108
	v_rcp_f32_e32 v112, v111
	s_nop 0
	v_fma_f32 v113, -v111, v112, 1.0
	v_fmac_f32_e32 v112, v113, v112
	v_div_scale_f32 v106, vcc, v100, v101, v100
	v_mul_f32_e32 v102, v106, v104
	v_fma_f32 v105, -v103, v102, v106
	v_fmac_f32_e32 v102, v105, v104
	v_fma_f32 v105, -v103, v102, v106
	v_div_fmas_f32 v102, v105, v104, v102
	v_div_fixup_f32 v102, v102, v101, v100
	v_mul_f32_e32 v78, v78, v102
	v_div_scale_f32 v114, vcc, v108, v109, v108
	v_mul_f32_e32 v110, v114, v112
	v_fma_f32 v113, -v111, v110, v114
	v_fmac_f32_e32 v110, v113, v112
	v_fma_f32 v113, -v111, v110, v114
	v_div_fmas_f32 v110, v113, v112, v110
	v_div_fixup_f32 v110, v110, v109, v108
	v_mul_f32_e32 v79, v79, v110
	v_cvt_pk_bf16_f32 v96, v76, v77
	v_cvt_pk_bf16_f32 v97, v78, v79
	global_store_dwordx2 v1, v[96:97], s[14:15] offset:1024
	v_lshlrev_b32_e32 v100, 16, v66
	v_mul_f32_e32 v101, 0xbfb8aa3b, v100
	v_exp_f32_e32 v101, v101
	v_mul_f32_e32 v80, v80, v91
	v_add_f32_e32 v101, 1.0, v101
	v_mul_f32_e32 v80, v80, v16
	v_and_b32_e32 v108, 0xffff0000, v66
	v_mul_f32_e32 v109, 0xbfb8aa3b, v108
	v_exp_f32_e32 v109, v109
	v_mul_f32_e32 v81, v81, v91
	v_add_f32_e32 v109, 1.0, v109
	v_mul_f32_e32 v81, v81, v17
	v_div_scale_f32 v103, s[16:17], v101, v101, v100
	v_rcp_f32_e32 v104, v103
	s_nop 0
	v_fma_f32 v105, -v103, v104, 1.0
	v_fmac_f32_e32 v104, v105, v104
	v_div_scale_f32 v111, s[16:17], v109, v109, v108
	v_rcp_f32_e32 v112, v111
	s_nop 0
	v_fma_f32 v113, -v111, v112, 1.0
	v_fmac_f32_e32 v112, v113, v112
	v_div_scale_f32 v106, vcc, v100, v101, v100
	v_mul_f32_e32 v102, v106, v104
	v_fma_f32 v105, -v103, v102, v106
	v_fmac_f32_e32 v102, v105, v104
	v_fma_f32 v105, -v103, v102, v106
	v_div_fmas_f32 v102, v105, v104, v102
	v_div_fixup_f32 v102, v102, v101, v100
	v_mul_f32_e32 v80, v80, v102
	v_div_scale_f32 v114, vcc, v108, v109, v108
	v_mul_f32_e32 v110, v114, v112
	v_fma_f32 v113, -v111, v110, v114
	v_fmac_f32_e32 v110, v113, v112
	v_fma_f32 v113, -v111, v110, v114
	v_div_fmas_f32 v110, v113, v112, v110
	v_div_fixup_f32 v110, v110, v109, v108
	v_mul_f32_e32 v81, v81, v110
	v_lshlrev_b32_e32 v100, 16, v67
	v_mul_f32_e32 v101, 0xbfb8aa3b, v100
	v_exp_f32_e32 v101, v101
	v_mul_f32_e32 v82, v82, v91
	v_add_f32_e32 v101, 1.0, v101
	v_mul_f32_e32 v82, v82, v18
	v_and_b32_e32 v108, 0xffff0000, v67
	v_mul_f32_e32 v109, 0xbfb8aa3b, v108
	v_exp_f32_e32 v109, v109
	v_mul_f32_e32 v83, v83, v91
	v_add_f32_e32 v109, 1.0, v109
	v_mul_f32_e32 v83, v83, v19
	v_div_scale_f32 v103, s[16:17], v101, v101, v100
	v_rcp_f32_e32 v104, v103
	s_nop 0
	v_fma_f32 v105, -v103, v104, 1.0
	v_fmac_f32_e32 v104, v105, v104
	v_div_scale_f32 v111, s[16:17], v109, v109, v108
	v_rcp_f32_e32 v112, v111
	s_nop 0
	v_fma_f32 v113, -v111, v112, 1.0
	v_fmac_f32_e32 v112, v113, v112
	v_div_scale_f32 v106, vcc, v100, v101, v100
	v_mul_f32_e32 v102, v106, v104
	v_fma_f32 v105, -v103, v102, v106
	v_fmac_f32_e32 v102, v105, v104
	v_fma_f32 v105, -v103, v102, v106
	v_div_fmas_f32 v102, v105, v104, v102
	v_div_fixup_f32 v102, v102, v101, v100
	v_mul_f32_e32 v82, v82, v102
	v_div_scale_f32 v114, vcc, v108, v109, v108
	v_mul_f32_e32 v110, v114, v112
	v_fma_f32 v113, -v111, v110, v114
	v_fmac_f32_e32 v110, v113, v112
	v_fma_f32 v113, -v111, v110, v114
	v_div_fmas_f32 v110, v113, v112, v110
	v_div_fixup_f32 v110, v110, v109, v108
	v_mul_f32_e32 v83, v83, v110
	v_cvt_pk_bf16_f32 v98, v80, v81
	v_cvt_pk_bf16_f32 v99, v82, v83
	global_store_dwordx2 v1, v[98:99], s[14:15] offset:1536
	s_add_u32 s14, s14, 0x400000
	s_addc_u32 s15, s15, 0
.Lgate_done:
.LBB0_424:
	s_or_b64 exec, exec, s[10:11]
	s_cmp_lt_i32 s25, 6
	s_cbranch_scc1 .LBB0_478
	s_waitcnt vmcnt(0)
	s_waitcnt lgkmcnt(0)
	s_barrier
	s_and_saveexec_b64 s[4:5], s[92:93]
	s_cbranch_execz .LBB0_477
	s_add_i32 s6, 0, 0x20000
	v_mov_b32_e32 v0, s6
	s_waitcnt vmcnt(0) expcnt(0) lgkmcnt(0)
	ds_read_b32 v2, v0
	s_add_i32 s6, 0, 0x20004
	v_mov_b32_e32 v0, s6
	ds_read_b32 v0, v0
	s_waitcnt lgkmcnt(1)
	v_cmp_ne_u32_e32 vcc, 0, v2
	s_cbranch_vccnz .LBB0_441
	s_load_dwordx2 s[10:11], s[8:9], 0x4
	s_add_u32 s6, s48, 0x1000
	s_addc_u32 s7, s49, 0
	s_add_u32 s8, s48, 0x1100
	s_addc_u32 s9, s49, 0
	s_waitcnt lgkmcnt(0)
	s_mul_i32 s3, s10, s3
	s_add_u32 s10, s48, 0x1200
	s_mul_i32 s3, s3, s11
	s_addc_u32 s11, s49, 0
	s_add_u32 s12, s48, 0x1300
	s_addc_u32 s13, s49, 0
	s_mov_b32 s20, 1
	v_mov_b32_e32 v16, 0
	s_branch .LBB0_429
